# v21 + GEMM phases keep s_setprio 1 across both MFMA clusters (32 setprio 0/1 pairs removed)
# speedup vs baseline: 1.0022x; 1.0022x over previous
; #define PG8_STAGE(bufoff, gbase, voff) do { _Pragma("unroll") for (int _i = 0; _i < 2; ++_i) \
;         __builtin_amdgcn_global_load_lds((const unsigned*)((const char*)(gbase) + (voff)[_i]), (LAS unsigned*)(lds + (bufoff) + ldsw + _i * 8192), 16, 0, 0); } while (0)
; #define PG8_LDA(dst, b, h) do { _Pragma("unroll") for (int m = 0; m < 4; ++m) _Pragma("unroll") for (int k = 0; k < 2; ++k) dst[m][k] = *(const LAS bf16x8*)(lds + PG8_SA(b, h) + aoff + m * 2048 + k * 1024); } while (0)
; #define PG8_LDB(dst, b, h) do { _Pragma("unroll") for (int n = 0; n < 2; ++n) _Pragma("unroll") for (int k = 0; k < 2; ++k) dst[n][k] = *(const LAS bf16x8*)(lds + PG8_SB(b, h) + boff + n * 2048 + k * 1024); } while (0)
; #define PG8_MMA(ai, bj, At, Bt) do { __builtin_amdgcn_s_setprio(1); _Pragma("unroll") for (int m = 0; m < 4; ++m) _Pragma("unroll") for (int n = 0; n < 2; ++n) _Pragma("unroll") for (int k = 0; k < 2; ++k) \
;         acc[ai][bj][m][n] = __builtin_amdgcn_mfma_f32_16x16x32_bf16(Bt[n][k], At[m][k], acc[ai][bj][m][n], 0, 0, 0); __builtin_amdgcn_s_setprio(0); } while (0)
; #define PG8_WAIT_V(n) asm volatile("s_waitcnt vmcnt(" #n ")" ::: "memory")
; #define PG8_WAIT_L(n) asm volatile("s_waitcnt lgkmcnt(" #n ")" ::: "memory")
; #define PG8_BAR __builtin_amdgcn_s_barrier()
; #define PG8_SCHED __builtin_amdgcn_sched_barrier(0)
; template <class Epi, class Sched>
; __device__ __forceinline__ void gemm_phase(LAS unsigned char* lds, const Gemm g, const Sched& S, const Epi& E, int wid) {
;     ...
;             PG8_LDB(B0, 0, 0); PG8_LDB(B1, 0, 1); PG8_SCHED; PG8_LDA(At, 0, 0); PG8_STAGE(PG8_SA(1, 1), a1 + hstep, voffA);
;             PG8_WAIT_V(8); PG8_WAIT_L(0); PG8_BAR; PG8_MMA(0, 0, At, B0); PG8_MMA(0, 1, At, B1); PG8_BAR; PG8_SCHED;
;             PG8_LDA(At, 0, 1); PG8_STAGE(PG8_SB(0, 0), b2, voffB); PG8_STAGE(PG8_SB(0, 1), b2 + hstep, voffB); PG8_STAGE(PG8_SA(0, 0), a2, voffA);
;             PG8_WAIT_V(8); PG8_WAIT_L(0); PG8_BAR; PG8_MMA(1, 0, At, B0); PG8_MMA(1, 1, At, B1); PG8_BAR; PG8_SCHED;
.LBB0_197:
	ds_read_b128 v[148:151], v145
	ds_read_b128 v[152:155], v145 offset:1024
	ds_read_b128 v[156:159], v145 offset:2048
	ds_read_b128 v[160:163], v145 offset:3072
	ds_read_b128 v[168:171], v146
	ds_read_b128 v[172:175], v146 offset:1024
	ds_read_b128 v[176:179], v146 offset:2048
	ds_read_b128 v[180:183], v146 offset:3072
	s_add_u32 s34, s30, 0xfffc0080
	s_addc_u32 s35, s31, -1
	s_cmp_eq_u32 s57, 12
	s_cselect_b32 s37, s21, s35
	s_cselect_b32 s36, s27, s34
	s_cselect_b32 s35, s19, s56
	s_cselect_b32 s34, s54, s55
	v_lshl_add_u64 v[140:141], s[30:31], 0, v[136:137]
	s_add_i32 m0, s29, 0xc000
	ds_read_b128 v[184:187], v147
	ds_read_b128 v[188:191], v147 offset:1024
	ds_read_b128 v[192:195], v147 offset:2048
	ds_read_b128 v[196:199], v147 offset:3072
	ds_read_b128 v[200:203], v147 offset:4096
	ds_read_b128 v[204:207], v147 offset:5120
	ds_read_b128 v[208:211], v147 offset:6144
	ds_read_b128 v[212:215], v147 offset:7168
	global_load_lds_dwordx4 v[140:141], off
	v_lshl_add_u64 v[140:141], s[30:31], 0, v[138:139]
	s_add_i32 m0, s29, 0xe000
	s_nop 0
	global_load_lds_dwordx4 v[140:141], off
	s_waitcnt vmcnt(8)
	s_waitcnt lgkmcnt(0)
	s_barrier
	s_setprio 1
	s_waitcnt lgkmcnt(0)
	v_mfma_f32_16x16x32_bf16 v[124:127], v[148:151], v[184:187], v[124:127]
	v_mfma_f32_16x16x32_bf16 v[120:123], v[156:159], v[184:187], v[120:123]
	v_mfma_f32_16x16x32_bf16 v[108:111], v[148:151], v[192:195], v[108:111]
	v_mfma_f32_16x16x32_bf16 v[104:107], v[156:159], v[192:195], v[104:107]
	v_mfma_f32_16x16x32_bf16 v[92:95], v[148:151], v[200:203], v[92:95]
	v_mfma_f32_16x16x32_bf16 v[88:91], v[156:159], v[200:203], v[88:91]
	v_mfma_f32_16x16x32_bf16 v[76:79], v[148:151], v[208:211], v[76:79]
	v_mfma_f32_16x16x32_bf16 v[72:75], v[156:159], v[208:211], v[72:75]
	v_mfma_f32_16x16x32_bf16 v[124:127], v[152:155], v[188:191], v[124:127]
	v_mfma_f32_16x16x32_bf16 v[120:123], v[160:163], v[188:191], v[120:123]
	v_mfma_f32_16x16x32_bf16 v[108:111], v[152:155], v[196:199], v[108:111]
	v_mfma_f32_16x16x32_bf16 v[104:107], v[160:163], v[196:199], v[104:107]
	v_mfma_f32_16x16x32_bf16 v[92:95], v[152:155], v[204:207], v[92:95]
	v_mfma_f32_16x16x32_bf16 v[88:91], v[160:163], v[204:207], v[88:91]
	v_mfma_f32_16x16x32_bf16 v[76:79], v[152:155], v[212:215], v[76:79]
	v_mfma_f32_16x16x32_bf16 v[72:75], v[160:163], v[212:215], v[72:75]
	v_mfma_f32_16x16x32_bf16 v[116:119], v[168:171], v[184:187], v[116:119]
	v_mfma_f32_16x16x32_bf16 v[112:115], v[176:179], v[184:187], v[112:115]
	v_mfma_f32_16x16x32_bf16 v[100:103], v[168:171], v[192:195], v[100:103]
	v_mfma_f32_16x16x32_bf16 v[96:99], v[176:179], v[192:195], v[96:99]
	v_mfma_f32_16x16x32_bf16 v[84:87], v[168:171], v[200:203], v[84:87]
	v_mfma_f32_16x16x32_bf16 v[80:83], v[176:179], v[200:203], v[80:83]
	v_mfma_f32_16x16x32_bf16 v[68:71], v[168:171], v[208:211], v[68:71]
	v_mfma_f32_16x16x32_bf16 v[64:67], v[176:179], v[208:211], v[64:67]
	v_mfma_f32_16x16x32_bf16 v[116:119], v[172:175], v[188:191], v[116:119]
	v_mfma_f32_16x16x32_bf16 v[112:115], v[180:183], v[188:191], v[112:115]
	v_mfma_f32_16x16x32_bf16 v[100:103], v[172:175], v[196:199], v[100:103]
	v_mfma_f32_16x16x32_bf16 v[96:99], v[180:183], v[196:199], v[96:99]
	v_mfma_f32_16x16x32_bf16 v[84:87], v[172:175], v[204:207], v[84:87]
	v_mfma_f32_16x16x32_bf16 v[80:83], v[180:183], v[204:207], v[80:83]
	v_mfma_f32_16x16x32_bf16 v[68:71], v[172:175], v[212:215], v[68:71]
	v_mfma_f32_16x16x32_bf16 v[64:67], v[180:183], v[212:215], v[64:67]
	s_setprio 0
	s_barrier
	s_add_i32 s58, s50, s75
	v_lshl_add_u64 v[140:141], s[34:35], 0, v[130:131]
	s_mov_b32 m0, s58
	ds_read_b128 v[184:187], v147 offset:16384
	ds_read_b128 v[188:191], v147 offset:17408
	global_load_lds_dwordx4 v[140:141], off
	s_add_i32 m0, s58, 0x2000
	s_add_u32 s58, s34, 0x40000
	v_lshl_add_u64 v[164:165], s[34:35], 0, v[134:135]
	s_addc_u32 s59, s35, 0
	s_add_i32 s60, s51, s75
	global_load_lds_dwordx4 v[164:165], off
	v_lshl_add_u64 v[216:217], s[58:59], 0, v[130:131]
	s_mov_b32 m0, s60
	v_lshl_add_u64 v[218:219], s[36:37], 0, v[132:133]
	global_load_lds_dwordx4 v[216:217], off
	v_lshl_add_u64 v[216:217], s[58:59], 0, v[134:135]
	s_add_i32 m0, s60, 0x2000
	s_nop 0
	global_load_lds_dwordx4 v[216:217], off
	v_lshl_add_u64 v[216:217], s[36:37], 0, v[128:129]
	s_mov_b32 m0, s29
	s_nop 0
	global_load_lds_dwordx4 v[216:217], off
	s_mov_b32 m0, s41
	s_nop 0
	global_load_lds_dwordx4 v[218:219], off
	s_waitcnt vmcnt(8)
	s_waitcnt lgkmcnt(0)
	s_barrier
	s_setprio 1
	s_waitcnt lgkmcnt(0)
	v_mfma_f32_16x16x32_bf16 v[60:63], v[148:151], v[184:187], v[60:63]
	v_mfma_f32_16x16x32_bf16 v[56:59], v[156:159], v[184:187], v[56:59]
	v_mfma_f32_16x16x32_bf16 v[60:63], v[152:155], v[188:191], v[60:63]
	v_mfma_f32_16x16x32_bf16 v[56:59], v[160:163], v[188:191], v[56:59]
	v_mfma_f32_16x16x32_bf16 v[52:55], v[168:171], v[184:187], v[52:55]
	v_mfma_f32_16x16x32_bf16 v[48:51], v[176:179], v[184:187], v[48:51]
	v_mfma_f32_16x16x32_bf16 v[52:55], v[172:175], v[188:191], v[52:55]
	v_mfma_f32_16x16x32_bf16 v[48:51], v[180:183], v[188:191], v[48:51]
	s_setprio 0
	s_barrier
; #define PG8_STAGE(bufoff, gbase, voff) do { _Pragma("unroll") for (int _i = 0; _i < 2; ++_i) \
;         __builtin_amdgcn_global_load_lds((const unsigned*)((const char*)(gbase) + (voff)[_i]), (LAS unsigned*)(lds + (bufoff) + ldsw + _i * 8192), 16, 0, 0); } while (0)
; #define PG8_LDA(dst, b, h) do { _Pragma("unroll") for (int m = 0; m < 4; ++m) _Pragma("unroll") for (int k = 0; k < 2; ++k) dst[m][k] = *(const LAS bf16x8*)(lds + PG8_SA(b, h) + aoff + m * 2048 + k * 1024); } while (0)
; #define PG8_LDB(dst, b, h) do { _Pragma("unroll") for (int n = 0; n < 2; ++n) _Pragma("unroll") for (int k = 0; k < 2; ++k) dst[n][k] = *(const LAS bf16x8*)(lds + PG8_SB(b, h) + boff + n * 2048 + k * 1024); } while (0)
; #define PG8_MMA(ai, bj, At, Bt) do { __builtin_amdgcn_s_setprio(1); _Pragma("unroll") for (int m = 0; m < 4; ++m) _Pragma("unroll") for (int n = 0; n < 2; ++n) _Pragma("unroll") for (int k = 0; k < 2; ++k) \
;         acc[ai][bj][m][n] = __builtin_amdgcn_mfma_f32_16x16x32_bf16(Bt[n][k], At[m][k], acc[ai][bj][m][n], 0, 0, 0); __builtin_amdgcn_s_setprio(0); } while (0)
; #define PG8_WAIT_V(n) asm volatile("s_waitcnt vmcnt(" #n ")" ::: "memory")
; #define PG8_WAIT_L(n) asm volatile("s_waitcnt lgkmcnt(" #n ")" ::: "memory")
; #define PG8_BAR __builtin_amdgcn_s_barrier()
; #define PG8_SCHED __builtin_amdgcn_sched_barrier(0)
; template <class Epi, class Sched>
; __device__ __forceinline__ void gemm_phase(LAS unsigned char* lds, const Gemm g, const Sched& S, const Epi& E, int wid) {
;     ...
;             PG8_LDB(B0, 1, 0); PG8_LDB(B1, 1, 1); PG8_SCHED; PG8_LDA(At, 1, 0); PG8_STAGE(PG8_SA(0, 1), a2 + hstep, voffA);
;             PG8_WAIT_V(8); PG8_WAIT_L(0); PG8_BAR; PG8_MMA(0, 0, At, B0); PG8_MMA(0, 1, At, B1); PG8_BAR; PG8_SCHED;
;             PG8_LDA(At, 1, 1); PG8_STAGE(PG8_SB(1, 0), b3, voffB); PG8_STAGE(PG8_SB(1, 1), b3 + hstep, voffB); PG8_STAGE(PG8_SA(1, 0), a3, voffA);
;             PG8_WAIT_V(8); PG8_WAIT_L(0); PG8_BAR; PG8_MMA(1, 0, At, B0); PG8_MMA(1, 1, At, B1); PG8_BAR; PG8_SCHED;
;         }
	s_add_i32 s58, 0, 0x18000
	s_add_i32 s59, 0, 0x1c000
	v_add_u32_e32 v160, s58, v143
	v_add_u32_e32 v180, s59, v143
	ds_read_b128 v[148:151], v160
	ds_read_b128 v[152:155], v160 offset:1024
	ds_read_b128 v[156:159], v160 offset:2048
	ds_read_b128 v[160:163], v160 offset:3072
	ds_read_b128 v[168:171], v180
	ds_read_b128 v[172:175], v180 offset:1024
	ds_read_b128 v[176:179], v180 offset:2048
	ds_read_b128 v[180:183], v180 offset:3072
	s_add_u32 s36, s36, 0x40000
	s_addc_u32 s37, s37, 0
	s_mov_b32 m0, s42
	v_lshl_add_u64 v[220:221], s[36:37], 0, v[128:129]
	ds_read_b128 v[184:187], v147 offset:32768
	ds_read_b128 v[188:191], v147 offset:33792
	ds_read_b128 v[192:195], v147 offset:34816
	ds_read_b128 v[196:199], v147 offset:35840
	ds_read_b128 v[200:203], v147 offset:36864
	ds_read_b128 v[204:207], v147 offset:37888
	ds_read_b128 v[208:211], v147 offset:38912
	ds_read_b128 v[212:215], v147 offset:39936
	global_load_lds_dwordx4 v[220:221], off
	v_lshl_add_u64 v[220:221], s[36:37], 0, v[132:133]
	s_mov_b32 m0, s43
	s_nop 0
	global_load_lds_dwordx4 v[220:221], off
	s_waitcnt vmcnt(8)
	s_waitcnt lgkmcnt(0)
	s_barrier
	s_setprio 1
	s_waitcnt lgkmcnt(0)
	v_mfma_f32_16x16x32_bf16 v[124:127], v[148:151], v[184:187], v[124:127]
	v_mfma_f32_16x16x32_bf16 v[120:123], v[156:159], v[184:187], v[120:123]
	v_mfma_f32_16x16x32_bf16 v[108:111], v[148:151], v[192:195], v[108:111]
	v_mfma_f32_16x16x32_bf16 v[104:107], v[156:159], v[192:195], v[104:107]
	v_mfma_f32_16x16x32_bf16 v[92:95], v[148:151], v[200:203], v[92:95]
	v_mfma_f32_16x16x32_bf16 v[88:91], v[156:159], v[200:203], v[88:91]
	v_mfma_f32_16x16x32_bf16 v[76:79], v[148:151], v[208:211], v[76:79]
	v_mfma_f32_16x16x32_bf16 v[72:75], v[156:159], v[208:211], v[72:75]
	v_mfma_f32_16x16x32_bf16 v[124:127], v[152:155], v[188:191], v[124:127]
	v_mfma_f32_16x16x32_bf16 v[120:123], v[160:163], v[188:191], v[120:123]
	v_mfma_f32_16x16x32_bf16 v[108:111], v[152:155], v[196:199], v[108:111]
	v_mfma_f32_16x16x32_bf16 v[104:107], v[160:163], v[196:199], v[104:107]
	v_mfma_f32_16x16x32_bf16 v[92:95], v[152:155], v[204:207], v[92:95]
	v_mfma_f32_16x16x32_bf16 v[88:91], v[160:163], v[204:207], v[88:91]
	v_mfma_f32_16x16x32_bf16 v[76:79], v[152:155], v[212:215], v[76:79]
	v_mfma_f32_16x16x32_bf16 v[72:75], v[160:163], v[212:215], v[72:75]
	v_mfma_f32_16x16x32_bf16 v[116:119], v[168:171], v[184:187], v[116:119]
	v_mfma_f32_16x16x32_bf16 v[112:115], v[176:179], v[184:187], v[112:115]
	v_mfma_f32_16x16x32_bf16 v[100:103], v[168:171], v[192:195], v[100:103]
	v_mfma_f32_16x16x32_bf16 v[96:99], v[176:179], v[192:195], v[96:99]
	v_mfma_f32_16x16x32_bf16 v[84:87], v[168:171], v[200:203], v[84:87]
	v_mfma_f32_16x16x32_bf16 v[80:83], v[176:179], v[200:203], v[80:83]
	v_mfma_f32_16x16x32_bf16 v[68:71], v[168:171], v[208:211], v[68:71]
	v_mfma_f32_16x16x32_bf16 v[64:67], v[176:179], v[208:211], v[64:67]
	v_mfma_f32_16x16x32_bf16 v[116:119], v[172:175], v[188:191], v[116:119]
	v_mfma_f32_16x16x32_bf16 v[112:115], v[180:183], v[188:191], v[112:115]
	v_mfma_f32_16x16x32_bf16 v[100:103], v[172:175], v[196:199], v[100:103]
	v_mfma_f32_16x16x32_bf16 v[96:99], v[180:183], v[196:199], v[96:99]
	v_mfma_f32_16x16x32_bf16 v[84:87], v[172:175], v[204:207], v[84:87]
	v_mfma_f32_16x16x32_bf16 v[80:83], v[180:183], v[204:207], v[80:83]
	v_mfma_f32_16x16x32_bf16 v[68:71], v[172:175], v[212:215], v[68:71]
	v_mfma_f32_16x16x32_bf16 v[64:67], v[180:183], v[212:215], v[64:67]
	s_setprio 0
	s_barrier
	s_add_i32 s36, s58, s75
	v_lshl_add_u64 v[140:141], v[140:141], 0, s[10:11]
	s_mov_b32 m0, s36
	ds_read_b128 v[184:187], v147 offset:49152
	ds_read_b128 v[188:191], v147 offset:50176
	global_load_lds_dwordx4 v[140:141], off
	s_add_i32 m0, s36, 0x2000
	s_add_u32 s34, s34, 0x40080
	v_lshl_add_u64 v[140:141], v[164:165], 0, s[10:11]
	s_addc_u32 s35, s35, 0
	s_add_i32 s36, s59, s75
	global_load_lds_dwordx4 v[140:141], off
	v_lshl_add_u64 v[140:141], s[34:35], 0, v[130:131]
	s_mov_b32 m0, s36
	s_nop 0
	global_load_lds_dwordx4 v[140:141], off
	v_lshl_add_u64 v[140:141], s[34:35], 0, v[134:135]
	s_add_i32 m0, s36, 0x2000
	s_nop 0
	global_load_lds_dwordx4 v[140:141], off
	v_lshl_add_u64 v[140:141], v[216:217], 0, s[10:11]
	s_mov_b32 m0, s45
	s_nop 0
	global_load_lds_dwordx4 v[140:141], off
	v_lshl_add_u64 v[140:141], v[218:219], 0, s[10:11]
	s_mov_b32 m0, s46
	s_nop 0
	global_load_lds_dwordx4 v[140:141], off
	s_waitcnt vmcnt(8)
	s_waitcnt lgkmcnt(0)
	s_barrier
	s_setprio 1
	s_waitcnt lgkmcnt(0)
	v_mfma_f32_16x16x32_bf16 v[60:63], v[148:151], v[184:187], v[60:63]
	v_mfma_f32_16x16x32_bf16 v[56:59], v[156:159], v[184:187], v[56:59]
	v_mfma_f32_16x16x32_bf16 v[60:63], v[152:155], v[188:191], v[60:63]
	v_mfma_f32_16x16x32_bf16 v[56:59], v[160:163], v[188:191], v[56:59]
	v_mfma_f32_16x16x32_bf16 v[52:55], v[168:171], v[184:187], v[52:55]
	v_mfma_f32_16x16x32_bf16 v[48:51], v[176:179], v[184:187], v[48:51]
	v_mfma_f32_16x16x32_bf16 v[52:55], v[172:175], v[188:191], v[52:55]
	v_mfma_f32_16x16x32_bf16 v[48:51], v[180:183], v[188:191], v[48:51]
	s_setprio 0
	s_barrier
	s_add_i32 s57, s57, 2
	s_add_u32 s30, s30, 0x100
	s_addc_u32 s31, s31, 0
	s_add_u32 s55, s55, 0x100
	s_addc_u32 s56, s56, 0
	s_cmp_gt_u32 s57, 13
	s_cbranch_scc0 .LBB0_197
	s_and_b64 vcc, exec, s[14:15]
	s_cbranch_vccz .LBB0_200
	s_barrier

; #define PG8_STAGE(bufoff, gbase, voff) do { _Pragma("unroll") for (int _i = 0; _i < 2; ++_i) \
;         __builtin_amdgcn_global_load_lds((const unsigned*)((const char*)(gbase) + (voff)[_i]), (LAS unsigned*)(lds + (bufoff) + ldsw + _i * 8192), 16, 0, 0); } while (0)
; #define PG8_LDA(dst, b, h) do { _Pragma("unroll") for (int m = 0; m < 4; ++m) _Pragma("unroll") for (int k = 0; k < 2; ++k) dst[m][k] = *(const LAS bf16x8*)(lds + PG8_SA(b, h) + aoff + m * 2048 + k * 1024); } while (0)
; #define PG8_LDB(dst, b, h) do { _Pragma("unroll") for (int n = 0; n < 2; ++n) _Pragma("unroll") for (int k = 0; k < 2; ++k) dst[n][k] = *(const LAS bf16x8*)(lds + PG8_SB(b, h) + boff + n * 2048 + k * 1024); } while (0)
; #define PG8_MMA(ai, bj, At, Bt) do { __builtin_amdgcn_s_setprio(1); _Pragma("unroll") for (int m = 0; m < 4; ++m) _Pragma("unroll") for (int n = 0; n < 2; ++n) _Pragma("unroll") for (int k = 0; k < 2; ++k) \
;         acc[ai][bj][m][n] = __builtin_amdgcn_mfma_f32_16x16x32_bf16(Bt[n][k], At[m][k], acc[ai][bj][m][n], 0, 0, 0); __builtin_amdgcn_s_setprio(0); } while (0)
; #define PG8_WAIT_V(n) asm volatile("s_waitcnt vmcnt(" #n ")" ::: "memory")
; #define PG8_WAIT_L(n) asm volatile("s_waitcnt lgkmcnt(" #n ")" ::: "memory")
; #define PG8_BAR __builtin_amdgcn_s_barrier()
; #define PG8_SCHED __builtin_amdgcn_sched_barrier(0)
; template <class Epi, class Sched>
; __device__ __forceinline__ void gemm_phase(LAS unsigned char* lds, const Gemm g, const Sched& S, const Epi& E, int wid) {
;     ...
;             PG8_LDB(B0, 0, 0); PG8_LDB(B1, 0, 1); PG8_SCHED; PG8_LDA(At, 0, 0); PG8_STAGE(PG8_SA(1, 1), a1 + hstep, voffA);
;             PG8_WAIT_V(8); PG8_WAIT_L(0); PG8_BAR; PG8_MMA(0, 0, At, B0); PG8_MMA(0, 1, At, B1); PG8_BAR; PG8_SCHED;
;             PG8_LDA(At, 0, 1); PG8_STAGE(PG8_SB(0, 0), b2, voffB); PG8_STAGE(PG8_SB(0, 1), b2 + hstep, voffB); PG8_STAGE(PG8_SA(0, 0), a2, voffA);
;             PG8_WAIT_V(8); PG8_WAIT_L(0); PG8_BAR; PG8_MMA(1, 0, At, B0); PG8_MMA(1, 1, At, B1); PG8_BAR; PG8_SCHED;
;             PG8_LDB(B0, 1, 0); PG8_LDB(B1, 1, 1); PG8_SCHED; PG8_LDA(At, 1, 0); PG8_STAGE(PG8_SA(0, 1), a2 + hstep, voffA);
;             PG8_WAIT_V(8); PG8_WAIT_L(0); PG8_BAR; PG8_MMA(0, 0, At, B0); PG8_MMA(0, 1, At, B1); PG8_BAR; PG8_SCHED;
.LBB0_475:
	ds_read_b128 v[152:155], v148
	ds_read_b128 v[156:159], v148 offset:1024
	ds_read_b128 v[160:163], v148 offset:2048
	ds_read_b128 v[168:171], v148 offset:3072
	ds_read_b128 v[172:175], v149
	ds_read_b128 v[176:179], v149 offset:1024
	ds_read_b128 v[180:183], v149 offset:2048
	ds_read_b128 v[184:187], v149 offset:3072
	s_add_u32 s26, s24, 0xfffc0080
	s_addc_u32 s27, s25, -1
	s_cmp_eq_u32 s51, 12
	s_cselect_b32 s29, s17, s27
	s_cselect_b32 s28, s23, s26
	s_cselect_b32 s27, s15, s50
	s_cselect_b32 s26, s48, s49
	v_lshl_add_u64 v[164:165], s[24:25], 0, v[138:139]
	s_add_i32 m0, s34, 0xc000
	ds_read_b128 v[188:191], v150
	ds_read_b128 v[192:195], v150 offset:1024
	ds_read_b128 v[196:199], v150 offset:2048
	ds_read_b128 v[200:203], v150 offset:3072
	ds_read_b128 v[204:207], v150 offset:4096
	ds_read_b128 v[208:211], v150 offset:5120
	ds_read_b128 v[212:215], v150 offset:6144
	ds_read_b128 v[216:219], v150 offset:7168
	global_load_lds_dwordx4 v[164:165], off
	v_lshl_add_u64 v[164:165], s[24:25], 0, v[140:141]
	s_add_i32 m0, s34, 0xe000
	s_nop 0
	global_load_lds_dwordx4 v[164:165], off
	s_waitcnt vmcnt(8)
	s_waitcnt lgkmcnt(0)
	s_barrier
	s_setprio 1
	s_waitcnt lgkmcnt(0)
	v_mfma_f32_16x16x32_bf16 v[124:127], v[152:155], v[188:191], v[124:127]
	v_mfma_f32_16x16x32_bf16 v[116:119], v[160:163], v[188:191], v[116:119]
	v_mfma_f32_16x16x32_bf16 v[108:111], v[152:155], v[196:199], v[108:111]
	v_mfma_f32_16x16x32_bf16 v[100:103], v[160:163], v[196:199], v[100:103]
	v_mfma_f32_16x16x32_bf16 v[92:95], v[152:155], v[204:207], v[92:95]
	v_mfma_f32_16x16x32_bf16 v[84:87], v[160:163], v[204:207], v[84:87]
	v_mfma_f32_16x16x32_bf16 v[76:79], v[152:155], v[212:215], v[76:79]
	v_mfma_f32_16x16x32_bf16 v[68:71], v[160:163], v[212:215], v[68:71]
	v_mfma_f32_16x16x32_bf16 v[124:127], v[156:159], v[192:195], v[124:127]
	v_mfma_f32_16x16x32_bf16 v[116:119], v[168:171], v[192:195], v[116:119]
	v_mfma_f32_16x16x32_bf16 v[108:111], v[156:159], v[200:203], v[108:111]
	v_mfma_f32_16x16x32_bf16 v[100:103], v[168:171], v[200:203], v[100:103]
	v_mfma_f32_16x16x32_bf16 v[92:95], v[156:159], v[208:211], v[92:95]
	v_mfma_f32_16x16x32_bf16 v[84:87], v[168:171], v[208:211], v[84:87]
	v_mfma_f32_16x16x32_bf16 v[76:79], v[156:159], v[216:219], v[76:79]
	v_mfma_f32_16x16x32_bf16 v[68:71], v[168:171], v[216:219], v[68:71]
	v_mfma_f32_16x16x32_bf16 v[120:123], v[172:175], v[188:191], v[120:123]
	v_mfma_f32_16x16x32_bf16 v[112:115], v[180:183], v[188:191], v[112:115]
	v_mfma_f32_16x16x32_bf16 v[104:107], v[172:175], v[196:199], v[104:107]
	v_mfma_f32_16x16x32_bf16 v[96:99], v[180:183], v[196:199], v[96:99]
	v_mfma_f32_16x16x32_bf16 v[88:91], v[172:175], v[204:207], v[88:91]
	v_mfma_f32_16x16x32_bf16 v[80:83], v[180:183], v[204:207], v[80:83]
	v_mfma_f32_16x16x32_bf16 v[72:75], v[172:175], v[212:215], v[72:75]
	v_mfma_f32_16x16x32_bf16 v[64:67], v[180:183], v[212:215], v[64:67]
	v_mfma_f32_16x16x32_bf16 v[120:123], v[176:179], v[192:195], v[120:123]
	v_mfma_f32_16x16x32_bf16 v[112:115], v[184:187], v[192:195], v[112:115]
	v_mfma_f32_16x16x32_bf16 v[104:107], v[176:179], v[200:203], v[104:107]
	v_mfma_f32_16x16x32_bf16 v[96:99], v[184:187], v[200:203], v[96:99]
	v_mfma_f32_16x16x32_bf16 v[88:91], v[176:179], v[208:211], v[88:91]
	v_mfma_f32_16x16x32_bf16 v[80:83], v[184:187], v[208:211], v[80:83]
	v_mfma_f32_16x16x32_bf16 v[72:75], v[176:179], v[216:219], v[72:75]
	v_mfma_f32_16x16x32_bf16 v[64:67], v[184:187], v[216:219], v[64:67]
	s_setprio 0
	s_barrier
	s_add_i32 s52, s43, s75
	v_lshl_add_u64 v[164:165], s[26:27], 0, v[130:131]
	s_mov_b32 m0, s52
	ds_read_b128 v[188:191], v150 offset:16384
	ds_read_b128 v[192:195], v150 offset:17408
	ds_read_b128 v[196:199], v150 offset:18432
	ds_read_b128 v[200:203], v150 offset:19456
	ds_read_b128 v[204:207], v150 offset:20480
	ds_read_b128 v[208:211], v150 offset:21504
	ds_read_b128 v[212:215], v150 offset:22528
	ds_read_b128 v[216:219], v150 offset:23552
	global_load_lds_dwordx4 v[164:165], off
	s_add_i32 m0, s52, 0x2000
	s_add_u32 s52, s26, 0x40000
	v_lshl_add_u64 v[220:221], s[26:27], 0, v[134:135]
	s_addc_u32 s53, s27, 0
	s_add_i32 s54, s44, s75
	global_load_lds_dwordx4 v[220:221], off
	v_lshl_add_u64 v[222:223], s[52:53], 0, v[130:131]
	s_mov_b32 m0, s54
	v_lshl_add_u64 v[224:225], s[28:29], 0, v[132:133]
	global_load_lds_dwordx4 v[222:223], off
	v_lshl_add_u64 v[222:223], s[52:53], 0, v[134:135]
	s_add_i32 m0, s54, 0x2000
	s_nop 0
	global_load_lds_dwordx4 v[222:223], off
	v_lshl_add_u64 v[222:223], s[28:29], 0, v[128:129]
	s_mov_b32 m0, s34
	s_nop 0
	global_load_lds_dwordx4 v[222:223], off
	s_mov_b32 m0, s35
	s_nop 0
	global_load_lds_dwordx4 v[224:225], off
	s_waitcnt vmcnt(8)
	s_waitcnt lgkmcnt(0)
	s_barrier
; #define PG8_STAGE(bufoff, gbase, voff) do { _Pragma("unroll") for (int _i = 0; _i < 2; ++_i) \
;         __builtin_amdgcn_global_load_lds((const unsigned*)((const char*)(gbase) + (voff)[_i]), (LAS unsigned*)(lds + (bufoff) + ldsw + _i * 8192), 16, 0, 0); } while (0)
; #define PG8_LDA(dst, b, h) do { _Pragma("unroll") for (int m = 0; m < 4; ++m) _Pragma("unroll") for (int k = 0; k < 2; ++k) dst[m][k] = *(const LAS bf16x8*)(lds + PG8_SA(b, h) + aoff + m * 2048 + k * 1024); } while (0)
; #define PG8_LDB(dst, b, h) do { _Pragma("unroll") for (int n = 0; n < 2; ++n) _Pragma("unroll") for (int k = 0; k < 2; ++k) dst[n][k] = *(const LAS bf16x8*)(lds + PG8_SB(b, h) + boff + n * 2048 + k * 1024); } while (0)
; #define PG8_MMA(ai, bj, At, Bt) do { __builtin_amdgcn_s_setprio(1); _Pragma("unroll") for (int m = 0; m < 4; ++m) _Pragma("unroll") for (int n = 0; n < 2; ++n) _Pragma("unroll") for (int k = 0; k < 2; ++k) \
;         acc[ai][bj][m][n] = __builtin_amdgcn_mfma_f32_16x16x32_bf16(Bt[n][k], At[m][k], acc[ai][bj][m][n], 0, 0, 0); __builtin_amdgcn_s_setprio(0); } while (0)
; #define PG8_WAIT_V(n) asm volatile("s_waitcnt vmcnt(" #n ")" ::: "memory")
; #define PG8_WAIT_L(n) asm volatile("s_waitcnt lgkmcnt(" #n ")" ::: "memory")
; #define PG8_BAR __builtin_amdgcn_s_barrier()
; #define PG8_SCHED __builtin_amdgcn_sched_barrier(0)
; template <class Epi, class Sched>
; __device__ __forceinline__ void gemm_phase(LAS unsigned char* lds, const Gemm g, const Sched& S, const Epi& E, int wid) {
;     ...
;             PG8_WAIT_V(8); PG8_WAIT_L(0); PG8_BAR; PG8_MMA(1, 0, At, B0); PG8_MMA(1, 1, At, B1); PG8_BAR; PG8_SCHED;
;             PG8_LDB(B0, 1, 0); PG8_LDB(B1, 1, 1); PG8_SCHED; PG8_LDA(At, 1, 0); PG8_STAGE(PG8_SA(0, 1), a2 + hstep, voffA);
;             PG8_WAIT_V(8); PG8_WAIT_L(0); PG8_BAR; PG8_MMA(0, 0, At, B0); PG8_MMA(0, 1, At, B1); PG8_BAR; PG8_SCHED;
	s_setprio 1
	s_waitcnt lgkmcnt(0)
	v_mfma_f32_16x16x32_bf16 v[60:63], v[152:155], v[188:191], v[60:63]
	v_mfma_f32_16x16x32_bf16 v[52:55], v[160:163], v[188:191], v[52:55]
	v_mfma_f32_16x16x32_bf16 v[44:47], v[152:155], v[196:199], v[44:47]
	v_mfma_f32_16x16x32_bf16 v[36:39], v[160:163], v[196:199], v[36:39]
	v_mfma_f32_16x16x32_bf16 v[28:31], v[152:155], v[204:207], v[28:31]
	v_mfma_f32_16x16x32_bf16 v[20:23], v[160:163], v[204:207], v[20:23]
	v_mfma_f32_16x16x32_bf16 v[12:15], v[152:155], v[212:215], v[12:15]
	v_mfma_f32_16x16x32_bf16 v[4:7], v[160:163], v[212:215], v[4:7]
	v_mfma_f32_16x16x32_bf16 v[60:63], v[156:159], v[192:195], v[60:63]
	v_mfma_f32_16x16x32_bf16 v[52:55], v[168:171], v[192:195], v[52:55]
	v_mfma_f32_16x16x32_bf16 v[44:47], v[156:159], v[200:203], v[44:47]
	v_mfma_f32_16x16x32_bf16 v[36:39], v[168:171], v[200:203], v[36:39]
	v_mfma_f32_16x16x32_bf16 v[28:31], v[156:159], v[208:211], v[28:31]
	v_mfma_f32_16x16x32_bf16 v[20:23], v[168:171], v[208:211], v[20:23]
	v_mfma_f32_16x16x32_bf16 v[12:15], v[156:159], v[216:219], v[12:15]
	v_mfma_f32_16x16x32_bf16 v[4:7], v[168:171], v[216:219], v[4:7]
	v_mfma_f32_16x16x32_bf16 v[56:59], v[172:175], v[188:191], v[56:59]
	v_mfma_f32_16x16x32_bf16 v[48:51], v[180:183], v[188:191], v[48:51]
	v_mfma_f32_16x16x32_bf16 v[40:43], v[172:175], v[196:199], v[40:43]
	v_mfma_f32_16x16x32_bf16 v[32:35], v[180:183], v[196:199], v[32:35]
	v_mfma_f32_16x16x32_bf16 v[24:27], v[172:175], v[204:207], v[24:27]
	v_mfma_f32_16x16x32_bf16 v[16:19], v[180:183], v[204:207], v[16:19]
	v_mfma_f32_16x16x32_bf16 v[8:11], v[172:175], v[212:215], v[8:11]
	v_mfma_f32_16x16x32_bf16 v[0:3], v[180:183], v[212:215], v[0:3]
	v_mfma_f32_16x16x32_bf16 v[56:59], v[176:179], v[192:195], v[56:59]
	v_mfma_f32_16x16x32_bf16 v[48:51], v[184:187], v[192:195], v[48:51]
	v_mfma_f32_16x16x32_bf16 v[40:43], v[176:179], v[200:203], v[40:43]
	v_mfma_f32_16x16x32_bf16 v[32:35], v[184:187], v[200:203], v[32:35]
	v_mfma_f32_16x16x32_bf16 v[24:27], v[176:179], v[208:211], v[24:27]
	v_mfma_f32_16x16x32_bf16 v[16:19], v[184:187], v[208:211], v[16:19]
	v_mfma_f32_16x16x32_bf16 v[8:11], v[176:179], v[216:219], v[8:11]
	v_mfma_f32_16x16x32_bf16 v[0:3], v[184:187], v[216:219], v[0:3]
	s_setprio 0
	s_barrier
	s_add_i32 s52, 0, 0x18000
	v_add_u32_e32 v151, s52, v147
	s_add_i32 s53, 0, 0x1c000
	ds_read_b128 v[152:155], v151
	ds_read_b128 v[156:159], v151 offset:1024
	ds_read_b128 v[160:163], v151 offset:2048
	ds_read_b128 v[168:171], v151 offset:3072
	v_add_u32_e32 v151, s53, v147
	ds_read_b128 v[172:175], v151
	ds_read_b128 v[176:179], v151 offset:1024
	ds_read_b128 v[180:183], v151 offset:2048
	ds_read_b128 v[184:187], v151 offset:3072
	s_add_u32 s28, s28, 0x40000
	s_addc_u32 s29, s29, 0
	s_mov_b32 m0, s36
	v_lshl_add_u64 v[226:227], s[28:29], 0, v[128:129]
	ds_read_b128 v[188:191], v150 offset:32768
	ds_read_b128 v[192:195], v150 offset:33792
	ds_read_b128 v[196:199], v150 offset:34816
	ds_read_b128 v[200:203], v150 offset:35840
	ds_read_b128 v[204:207], v150 offset:36864
	ds_read_b128 v[208:211], v150 offset:37888
	ds_read_b128 v[212:215], v150 offset:38912
	ds_read_b128 v[216:219], v150 offset:39936
	global_load_lds_dwordx4 v[226:227], off
	v_lshl_add_u64 v[226:227], s[28:29], 0, v[132:133]
	s_mov_b32 m0, s37
	s_nop 0
	global_load_lds_dwordx4 v[226:227], off
	s_waitcnt vmcnt(8)
	s_waitcnt lgkmcnt(0)
	s_barrier
	s_setprio 1
	s_waitcnt lgkmcnt(0)
	v_mfma_f32_16x16x32_bf16 v[124:127], v[152:155], v[188:191], v[124:127]
	v_mfma_f32_16x16x32_bf16 v[116:119], v[160:163], v[188:191], v[116:119]
	v_mfma_f32_16x16x32_bf16 v[108:111], v[152:155], v[196:199], v[108:111]
	v_mfma_f32_16x16x32_bf16 v[100:103], v[160:163], v[196:199], v[100:103]
	v_mfma_f32_16x16x32_bf16 v[92:95], v[152:155], v[204:207], v[92:95]
	v_mfma_f32_16x16x32_bf16 v[84:87], v[160:163], v[204:207], v[84:87]
	v_mfma_f32_16x16x32_bf16 v[76:79], v[152:155], v[212:215], v[76:79]
	v_mfma_f32_16x16x32_bf16 v[68:71], v[160:163], v[212:215], v[68:71]
	v_mfma_f32_16x16x32_bf16 v[124:127], v[156:159], v[192:195], v[124:127]
	v_mfma_f32_16x16x32_bf16 v[116:119], v[168:171], v[192:195], v[116:119]
	v_mfma_f32_16x16x32_bf16 v[108:111], v[156:159], v[200:203], v[108:111]
	v_mfma_f32_16x16x32_bf16 v[100:103], v[168:171], v[200:203], v[100:103]
	v_mfma_f32_16x16x32_bf16 v[92:95], v[156:159], v[208:211], v[92:95]
	v_mfma_f32_16x16x32_bf16 v[84:87], v[168:171], v[208:211], v[84:87]
	v_mfma_f32_16x16x32_bf16 v[76:79], v[156:159], v[216:219], v[76:79]
	v_mfma_f32_16x16x32_bf16 v[68:71], v[168:171], v[216:219], v[68:71]
	v_mfma_f32_16x16x32_bf16 v[120:123], v[172:175], v[188:191], v[120:123]
	v_mfma_f32_16x16x32_bf16 v[112:115], v[180:183], v[188:191], v[112:115]
	v_mfma_f32_16x16x32_bf16 v[104:107], v[172:175], v[196:199], v[104:107]
	v_mfma_f32_16x16x32_bf16 v[96:99], v[180:183], v[196:199], v[96:99]
	v_mfma_f32_16x16x32_bf16 v[88:91], v[172:175], v[204:207], v[88:91]
	v_mfma_f32_16x16x32_bf16 v[80:83], v[180:183], v[204:207], v[80:83]
	v_mfma_f32_16x16x32_bf16 v[72:75], v[172:175], v[212:215], v[72:75]
	v_mfma_f32_16x16x32_bf16 v[64:67], v[180:183], v[212:215], v[64:67]
	v_mfma_f32_16x16x32_bf16 v[120:123], v[176:179], v[192:195], v[120:123]
	v_mfma_f32_16x16x32_bf16 v[112:115], v[184:187], v[192:195], v[112:115]
	v_mfma_f32_16x16x32_bf16 v[104:107], v[176:179], v[200:203], v[104:107]
	v_mfma_f32_16x16x32_bf16 v[96:99], v[184:187], v[200:203], v[96:99]
	v_mfma_f32_16x16x32_bf16 v[88:91], v[176:179], v[208:211], v[88:91]
	v_mfma_f32_16x16x32_bf16 v[80:83], v[184:187], v[208:211], v[80:83]
	v_mfma_f32_16x16x32_bf16 v[72:75], v[176:179], v[216:219], v[72:75]
	v_mfma_f32_16x16x32_bf16 v[64:67], v[184:187], v[216:219], v[64:67]
	s_setprio 0
	s_barrier
; #define PG8_STAGE(bufoff, gbase, voff) do { _Pragma("unroll") for (int _i = 0; _i < 2; ++_i) \
;         __builtin_amdgcn_global_load_lds((const unsigned*)((const char*)(gbase) + (voff)[_i]), (LAS unsigned*)(lds + (bufoff) + ldsw + _i * 8192), 16, 0, 0); } while (0)
; #define PG8_LDA(dst, b, h) do { _Pragma("unroll") for (int m = 0; m < 4; ++m) _Pragma("unroll") for (int k = 0; k < 2; ++k) dst[m][k] = *(const LAS bf16x8*)(lds + PG8_SA(b, h) + aoff + m * 2048 + k * 1024); } while (0)
; #define PG8_MMA(ai, bj, At, Bt) do { __builtin_amdgcn_s_setprio(1); _Pragma("unroll") for (int m = 0; m < 4; ++m) _Pragma("unroll") for (int n = 0; n < 2; ++n) _Pragma("unroll") for (int k = 0; k < 2; ++k) \
;         acc[ai][bj][m][n] = __builtin_amdgcn_mfma_f32_16x16x32_bf16(Bt[n][k], At[m][k], acc[ai][bj][m][n], 0, 0, 0); __builtin_amdgcn_s_setprio(0); } while (0)
; #define PG8_WAIT_V(n) asm volatile("s_waitcnt vmcnt(" #n ")" ::: "memory")
; #define PG8_WAIT_L(n) asm volatile("s_waitcnt lgkmcnt(" #n ")" ::: "memory")
; #define PG8_BAR __builtin_amdgcn_s_barrier()
; #define PG8_SCHED __builtin_amdgcn_sched_barrier(0)
; template <class Epi, class Sched>
; __device__ __forceinline__ void gemm_phase(LAS unsigned char* lds, const Gemm g, const Sched& S, const Epi& E, int wid) {
;     ...
;             PG8_LDA(At, 1, 1); PG8_STAGE(PG8_SB(1, 0), b3, voffB); PG8_STAGE(PG8_SB(1, 1), b3 + hstep, voffB); PG8_STAGE(PG8_SA(1, 0), a3, voffA);
;             PG8_WAIT_V(8); PG8_WAIT_L(0); PG8_BAR; PG8_MMA(1, 0, At, B0); PG8_MMA(1, 1, At, B1); PG8_BAR; PG8_SCHED;
	s_add_i32 s28, s52, s75
	v_lshl_add_u64 v[164:165], v[164:165], 0, s[10:11]
	s_mov_b32 m0, s28
	ds_read_b128 v[188:191], v150 offset:49152
	ds_read_b128 v[192:195], v150 offset:50176
	ds_read_b128 v[196:199], v150 offset:51200
	ds_read_b128 v[200:203], v150 offset:52224
	ds_read_b128 v[204:207], v150 offset:53248
	ds_read_b128 v[208:211], v150 offset:54272
	ds_read_b128 v[212:215], v150 offset:55296
	ds_read_b128 v[216:219], v150 offset:56320
	global_load_lds_dwordx4 v[164:165], off
	s_add_i32 m0, s28, 0x2000
	s_add_u32 s26, s26, 0x40080
	v_lshl_add_u64 v[164:165], v[220:221], 0, s[10:11]
	s_addc_u32 s27, s27, 0
	s_add_i32 s28, s53, s75
	global_load_lds_dwordx4 v[164:165], off
	v_lshl_add_u64 v[164:165], s[26:27], 0, v[130:131]
	s_mov_b32 m0, s28
	s_nop 0
	global_load_lds_dwordx4 v[164:165], off
	v_lshl_add_u64 v[164:165], s[26:27], 0, v[134:135]
	s_add_i32 m0, s28, 0x2000
	s_nop 0
	global_load_lds_dwordx4 v[164:165], off
	v_lshl_add_u64 v[164:165], v[222:223], 0, s[10:11]
	s_mov_b32 m0, s38
	s_nop 0
	global_load_lds_dwordx4 v[164:165], off
	v_lshl_add_u64 v[164:165], v[224:225], 0, s[10:11]
	s_mov_b32 m0, s39
	s_nop 0
	global_load_lds_dwordx4 v[164:165], off
	s_waitcnt vmcnt(8)
	s_waitcnt lgkmcnt(0)
	s_barrier
	s_setprio 1
	s_waitcnt lgkmcnt(0)
	v_mfma_f32_16x16x32_bf16 v[60:63], v[152:155], v[188:191], v[60:63]
	v_mfma_f32_16x16x32_bf16 v[52:55], v[160:163], v[188:191], v[52:55]
	v_mfma_f32_16x16x32_bf16 v[44:47], v[152:155], v[196:199], v[44:47]
	v_mfma_f32_16x16x32_bf16 v[36:39], v[160:163], v[196:199], v[36:39]
	v_mfma_f32_16x16x32_bf16 v[28:31], v[152:155], v[204:207], v[28:31]
	v_mfma_f32_16x16x32_bf16 v[20:23], v[160:163], v[204:207], v[20:23]
	v_mfma_f32_16x16x32_bf16 v[12:15], v[152:155], v[212:215], v[12:15]
	v_mfma_f32_16x16x32_bf16 v[4:7], v[160:163], v[212:215], v[4:7]
	v_mfma_f32_16x16x32_bf16 v[60:63], v[156:159], v[192:195], v[60:63]
	v_mfma_f32_16x16x32_bf16 v[52:55], v[168:171], v[192:195], v[52:55]
	v_mfma_f32_16x16x32_bf16 v[44:47], v[156:159], v[200:203], v[44:47]
	v_mfma_f32_16x16x32_bf16 v[36:39], v[168:171], v[200:203], v[36:39]
	v_mfma_f32_16x16x32_bf16 v[28:31], v[156:159], v[208:211], v[28:31]
	v_mfma_f32_16x16x32_bf16 v[20:23], v[168:171], v[208:211], v[20:23]
	v_mfma_f32_16x16x32_bf16 v[12:15], v[156:159], v[216:219], v[12:15]
	v_mfma_f32_16x16x32_bf16 v[4:7], v[168:171], v[216:219], v[4:7]
	v_mfma_f32_16x16x32_bf16 v[56:59], v[172:175], v[188:191], v[56:59]
	v_mfma_f32_16x16x32_bf16 v[48:51], v[180:183], v[188:191], v[48:51]
	v_mfma_f32_16x16x32_bf16 v[40:43], v[172:175], v[196:199], v[40:43]
	v_mfma_f32_16x16x32_bf16 v[32:35], v[180:183], v[196:199], v[32:35]
	v_mfma_f32_16x16x32_bf16 v[24:27], v[172:175], v[204:207], v[24:27]
	v_mfma_f32_16x16x32_bf16 v[16:19], v[180:183], v[204:207], v[16:19]
	v_mfma_f32_16x16x32_bf16 v[8:11], v[172:175], v[212:215], v[8:11]
	v_mfma_f32_16x16x32_bf16 v[0:3], v[180:183], v[212:215], v[0:3]
	v_mfma_f32_16x16x32_bf16 v[56:59], v[176:179], v[192:195], v[56:59]
	v_mfma_f32_16x16x32_bf16 v[48:51], v[184:187], v[192:195], v[48:51]
	v_mfma_f32_16x16x32_bf16 v[40:43], v[176:179], v[200:203], v[40:43]
	v_mfma_f32_16x16x32_bf16 v[32:35], v[184:187], v[200:203], v[32:35]
	v_mfma_f32_16x16x32_bf16 v[24:27], v[176:179], v[208:211], v[24:27]
	v_mfma_f32_16x16x32_bf16 v[16:19], v[184:187], v[208:211], v[16:19]
	v_mfma_f32_16x16x32_bf16 v[8:11], v[176:179], v[216:219], v[8:11]
	v_mfma_f32_16x16x32_bf16 v[0:3], v[184:187], v[216:219], v[0:3]
	s_setprio 0
	s_barrier
	s_add_i32 s51, s51, 2
	s_add_u32 s24, s24, 0x100
	s_addc_u32 s25, s25, 0
	s_add_u32 s49, s49, 0x100
	s_addc_u32 s50, s50, 0
	s_cmp_gt_u32 s51, 13
	s_cbranch_scc0 .LBB0_475
	s_and_b64 vcc, exec, s[12:13]
	s_cbranch_vccz .LBB0_478
	s_barrier

; #define PG8_STAGE(bufoff, gbase, voff) do { _Pragma("unroll") for (int _i = 0; _i < 2; ++_i) \
;         __builtin_amdgcn_global_load_lds((const unsigned*)((const char*)(gbase) + (voff)[_i]), (LAS unsigned*)(lds + (bufoff) + ldsw + _i * 8192), 16, 0, 0); } while (0)
; #define PG8_LDA(dst, b, h) do { _Pragma("unroll") for (int m = 0; m < 4; ++m) _Pragma("unroll") for (int k = 0; k < 2; ++k) dst[m][k] = *(const LAS bf16x8*)(lds + PG8_SA(b, h) + aoff + m * 2048 + k * 1024); } while (0)
; #define PG8_LDB(dst, b, h) do { _Pragma("unroll") for (int n = 0; n < 2; ++n) _Pragma("unroll") for (int k = 0; k < 2; ++k) dst[n][k] = *(const LAS bf16x8*)(lds + PG8_SB(b, h) + boff + n * 2048 + k * 1024); } while (0)
; #define PG8_MMA(ai, bj, At, Bt) do { __builtin_amdgcn_s_setprio(1); _Pragma("unroll") for (int m = 0; m < 4; ++m) _Pragma("unroll") for (int n = 0; n < 2; ++n) _Pragma("unroll") for (int k = 0; k < 2; ++k) \
;         acc[ai][bj][m][n] = __builtin_amdgcn_mfma_f32_16x16x32_bf16(Bt[n][k], At[m][k], acc[ai][bj][m][n], 0, 0, 0); __builtin_amdgcn_s_setprio(0); } while (0)
; #define PG8_WAIT_V(n) asm volatile("s_waitcnt vmcnt(" #n ")" ::: "memory")
; #define PG8_WAIT_L(n) asm volatile("s_waitcnt lgkmcnt(" #n ")" ::: "memory")
; #define PG8_BAR __builtin_amdgcn_s_barrier()
; #define PG8_SCHED __builtin_amdgcn_sched_barrier(0)
; template <class Epi, class Sched>
; __device__ __forceinline__ void gemm_phase(LAS unsigned char* lds, const Gemm g, const Sched& S, const Epi& E, int wid) {
;     ...
;             PG8_LDB(B0, 0, 0); PG8_LDB(B1, 0, 1); PG8_SCHED; PG8_LDA(At, 0, 0); PG8_STAGE(PG8_SA(1, 1), a1 + hstep, voffA);
;             PG8_WAIT_V(8); PG8_WAIT_L(0); PG8_BAR; PG8_MMA(0, 0, At, B0); PG8_MMA(0, 1, At, B1); PG8_BAR; PG8_SCHED;
;             PG8_LDA(At, 0, 1); PG8_STAGE(PG8_SB(0, 0), b2, voffB); PG8_STAGE(PG8_SB(0, 1), b2 + hstep, voffB); PG8_STAGE(PG8_SA(0, 0), a2, voffA);
.LBB0_573:
	ds_read_b128 v[128:131], v169
	ds_read_b128 v[132:135], v169 offset:1024
	ds_read_b128 v[152:155], v169 offset:2048
	ds_read_b128 v[156:159], v169 offset:3072
	ds_read_b128 v[160:163], v170
	ds_read_b128 v[174:177], v170 offset:1024
	ds_read_b128 v[178:181], v170 offset:2048
	ds_read_b128 v[182:185], v170 offset:3072
	s_add_u32 s4, s6, 0x100
	s_addc_u32 s5, s7, 0
	s_cmp_eq_u32 s40, 40
	s_cselect_b32 s39, s29, s5
	s_cselect_b32 s38, s28, s4
	s_cselect_b32 s11, s31, s37
	s_cselect_b32 s10, s30, s35
	v_lshl_add_u64 v[218:219], s[6:7], 0, v[144:145]
	s_add_i32 m0, s44, 0xc000
	ds_read_b128 v[186:189], v171
	ds_read_b128 v[190:193], v171 offset:1024
	ds_read_b128 v[194:197], v171 offset:2048
	ds_read_b128 v[198:201], v171 offset:3072
	ds_read_b128 v[202:205], v171 offset:4096
	ds_read_b128 v[206:209], v171 offset:5120
	ds_read_b128 v[210:213], v171 offset:6144
	ds_read_b128 v[214:217], v171 offset:7168
	global_load_lds_dwordx4 v[218:219], off
	v_lshl_add_u64 v[218:219], s[6:7], 0, v[146:147]
	s_add_i32 m0, s44, 0xe000
	s_nop 0
	global_load_lds_dwordx4 v[218:219], off
	s_waitcnt vmcnt(8)
	s_waitcnt lgkmcnt(0)
	s_barrier
	s_setprio 1
	s_waitcnt lgkmcnt(0)
	v_mfma_f32_16x16x32_bf16 v[56:59], v[128:131], v[186:189], v[56:59]
	v_mfma_f32_16x16x32_bf16 v[60:63], v[152:155], v[186:189], v[60:63]
	v_mfma_f32_16x16x32_bf16 v[84:87], v[128:131], v[194:197], v[84:87]
	v_mfma_f32_16x16x32_bf16 v[88:91], v[152:155], v[194:197], v[88:91]
	v_mfma_f32_16x16x32_bf16 v[112:115], v[128:131], v[202:205], v[112:115]
	v_mfma_f32_16x16x32_bf16 v[116:119], v[152:155], v[202:205], v[116:119]
	v_mfma_f32_16x16x32_bf16 v[120:123], v[128:131], v[210:213], v[120:123]
	v_mfma_f32_16x16x32_bf16 v[124:127], v[152:155], v[210:213], v[124:127]
	v_mfma_f32_16x16x32_bf16 v[56:59], v[132:135], v[190:193], v[56:59]
	v_mfma_f32_16x16x32_bf16 v[60:63], v[156:159], v[190:193], v[60:63]
	v_mfma_f32_16x16x32_bf16 v[84:87], v[132:135], v[198:201], v[84:87]
	v_mfma_f32_16x16x32_bf16 v[88:91], v[156:159], v[198:201], v[88:91]
	v_mfma_f32_16x16x32_bf16 v[112:115], v[132:135], v[206:209], v[112:115]
	v_mfma_f32_16x16x32_bf16 v[116:119], v[156:159], v[206:209], v[116:119]
	v_mfma_f32_16x16x32_bf16 v[120:123], v[132:135], v[214:217], v[120:123]
	v_mfma_f32_16x16x32_bf16 v[124:127], v[156:159], v[214:217], v[124:127]
	v_mfma_f32_16x16x32_bf16 v[20:23], v[160:163], v[186:189], v[20:23]
	v_mfma_f32_16x16x32_bf16 v[28:31], v[178:181], v[186:189], v[28:31]
	v_mfma_f32_16x16x32_bf16 v[40:43], v[160:163], v[194:197], v[40:43]
	v_mfma_f32_16x16x32_bf16 v[48:51], v[178:181], v[194:197], v[48:51]
	v_mfma_f32_16x16x32_bf16 v[64:67], v[160:163], v[202:205], v[64:67]
	v_mfma_f32_16x16x32_bf16 v[80:83], v[178:181], v[202:205], v[80:83]
	v_mfma_f32_16x16x32_bf16 v[96:99], v[160:163], v[210:213], v[96:99]
	v_mfma_f32_16x16x32_bf16 v[104:107], v[178:181], v[210:213], v[104:107]
	v_mfma_f32_16x16x32_bf16 v[20:23], v[174:177], v[190:193], v[20:23]
	v_mfma_f32_16x16x32_bf16 v[28:31], v[182:185], v[190:193], v[28:31]
	v_mfma_f32_16x16x32_bf16 v[40:43], v[174:177], v[198:201], v[40:43]
	v_mfma_f32_16x16x32_bf16 v[48:51], v[182:185], v[198:201], v[48:51]
	v_mfma_f32_16x16x32_bf16 v[64:67], v[174:177], v[206:209], v[64:67]
	v_mfma_f32_16x16x32_bf16 v[80:83], v[182:185], v[206:209], v[80:83]
	v_mfma_f32_16x16x32_bf16 v[96:99], v[174:177], v[214:217], v[96:99]
	v_mfma_f32_16x16x32_bf16 v[104:107], v[182:185], v[214:217], v[104:107]
	s_setprio 0
	s_barrier
	s_add_i32 s6, s61, s75
	v_lshl_add_u64 v[218:219], s[10:11], 0, v[138:139]
	s_mov_b32 m0, s6
	ds_read_b128 v[186:189], v171 offset:16384
	ds_read_b128 v[190:193], v171 offset:17408
	ds_read_b128 v[194:197], v171 offset:18432
	ds_read_b128 v[198:201], v171 offset:19456
	ds_read_b128 v[202:205], v171 offset:20480
	ds_read_b128 v[206:209], v171 offset:21504
	ds_read_b128 v[210:213], v171 offset:22528
	ds_read_b128 v[214:217], v171 offset:23552
	global_load_lds_dwordx4 v[218:219], off
	s_add_i32 m0, s6, 0x2000
	s_add_u32 s6, s10, 0xb0000
	v_lshl_add_u64 v[220:221], s[10:11], 0, v[142:143]
	s_addc_u32 s7, s11, 0
	s_add_i32 s41, s62, s75
	global_load_lds_dwordx4 v[220:221], off
	v_lshl_add_u64 v[222:223], s[6:7], 0, v[138:139]
	s_mov_b32 m0, s41
	v_lshl_add_u64 v[224:225], s[38:39], 0, v[140:141]
	global_load_lds_dwordx4 v[222:223], off
	v_lshl_add_u64 v[222:223], s[6:7], 0, v[142:143]
	s_add_i32 m0, s41, 0x2000
	s_nop 0
	global_load_lds_dwordx4 v[222:223], off
	v_lshl_add_u64 v[222:223], s[38:39], 0, v[136:137]
	s_mov_b32 m0, s44
	s_nop 0
	global_load_lds_dwordx4 v[222:223], off
	s_mov_b32 m0, s45
	s_nop 0
	global_load_lds_dwordx4 v[224:225], off
	s_waitcnt vmcnt(8)
	s_waitcnt lgkmcnt(0)
	s_barrier
; #define PG8_STAGE(bufoff, gbase, voff) do { _Pragma("unroll") for (int _i = 0; _i < 2; ++_i) \
;         __builtin_amdgcn_global_load_lds((const unsigned*)((const char*)(gbase) + (voff)[_i]), (LAS unsigned*)(lds + (bufoff) + ldsw + _i * 8192), 16, 0, 0); } while (0)
; #define PG8_LDA(dst, b, h) do { _Pragma("unroll") for (int m = 0; m < 4; ++m) _Pragma("unroll") for (int k = 0; k < 2; ++k) dst[m][k] = *(const LAS bf16x8*)(lds + PG8_SA(b, h) + aoff + m * 2048 + k * 1024); } while (0)
; #define PG8_LDB(dst, b, h) do { _Pragma("unroll") for (int n = 0; n < 2; ++n) _Pragma("unroll") for (int k = 0; k < 2; ++k) dst[n][k] = *(const LAS bf16x8*)(lds + PG8_SB(b, h) + boff + n * 2048 + k * 1024); } while (0)
; #define PG8_MMA(ai, bj, At, Bt) do { __builtin_amdgcn_s_setprio(1); _Pragma("unroll") for (int m = 0; m < 4; ++m) _Pragma("unroll") for (int n = 0; n < 2; ++n) _Pragma("unroll") for (int k = 0; k < 2; ++k) \
;         acc[ai][bj][m][n] = __builtin_amdgcn_mfma_f32_16x16x32_bf16(Bt[n][k], At[m][k], acc[ai][bj][m][n], 0, 0, 0); __builtin_amdgcn_s_setprio(0); } while (0)
; #define PG8_WAIT_V(n) asm volatile("s_waitcnt vmcnt(" #n ")" ::: "memory")
; #define PG8_WAIT_L(n) asm volatile("s_waitcnt lgkmcnt(" #n ")" ::: "memory")
; #define PG8_BAR __builtin_amdgcn_s_barrier()
; #define PG8_SCHED __builtin_amdgcn_sched_barrier(0)
; template <class Epi, class Sched>
; __device__ __forceinline__ void gemm_phase(LAS unsigned char* lds, const Gemm g, const Sched& S, const Epi& E, int wid) {
;     ...
;             PG8_WAIT_V(8); PG8_WAIT_L(0); PG8_BAR; PG8_MMA(1, 0, At, B0); PG8_MMA(1, 1, At, B1); PG8_BAR; PG8_SCHED;
;             PG8_LDB(B0, 1, 0); PG8_LDB(B1, 1, 1); PG8_SCHED; PG8_LDA(At, 1, 0); PG8_STAGE(PG8_SA(0, 1), a2 + hstep, voffA);
;             PG8_WAIT_V(8); PG8_WAIT_L(0); PG8_BAR; PG8_MMA(0, 0, At, B0); PG8_MMA(0, 1, At, B1); PG8_BAR; PG8_SCHED;
	s_setprio 1
	s_waitcnt lgkmcnt(0)
	v_mfma_f32_16x16x32_bf16 v[108:111], v[128:131], v[186:189], v[108:111]
	v_mfma_f32_16x16x32_bf16 v[100:103], v[152:155], v[186:189], v[100:103]
	v_mfma_f32_16x16x32_bf16 v[72:75], v[128:131], v[194:197], v[72:75]
	v_mfma_f32_16x16x32_bf16 v[68:71], v[152:155], v[194:197], v[68:71]
	v_mfma_f32_16x16x32_bf16 v[36:39], v[128:131], v[202:205], v[36:39]
	v_mfma_f32_16x16x32_bf16 v[32:35], v[152:155], v[202:205], v[32:35]
	v_mfma_f32_16x16x32_bf16 v[12:15], v[128:131], v[210:213], v[12:15]
	v_mfma_f32_16x16x32_bf16 v[8:11], v[152:155], v[210:213], v[8:11]
	v_mfma_f32_16x16x32_bf16 v[108:111], v[132:135], v[190:193], v[108:111]
	v_mfma_f32_16x16x32_bf16 v[100:103], v[156:159], v[190:193], v[100:103]
	v_mfma_f32_16x16x32_bf16 v[72:75], v[132:135], v[198:201], v[72:75]
	v_mfma_f32_16x16x32_bf16 v[68:71], v[156:159], v[198:201], v[68:71]
	v_mfma_f32_16x16x32_bf16 v[36:39], v[132:135], v[206:209], v[36:39]
	v_mfma_f32_16x16x32_bf16 v[32:35], v[156:159], v[206:209], v[32:35]
	v_mfma_f32_16x16x32_bf16 v[12:15], v[132:135], v[214:217], v[12:15]
	v_mfma_f32_16x16x32_bf16 v[8:11], v[156:159], v[214:217], v[8:11]
	v_mfma_f32_16x16x32_bf16 v[92:95], v[160:163], v[186:189], v[92:95]
	v_mfma_f32_16x16x32_bf16 v[76:79], v[178:181], v[186:189], v[76:79]
	v_mfma_f32_16x16x32_bf16 v[52:55], v[160:163], v[194:197], v[52:55]
	v_mfma_f32_16x16x32_bf16 v[44:47], v[178:181], v[194:197], v[44:47]
	v_mfma_f32_16x16x32_bf16 v[24:27], v[160:163], v[202:205], v[24:27]
	v_mfma_f32_16x16x32_bf16 v[16:19], v[178:181], v[202:205], v[16:19]
	v_mfma_f32_16x16x32_bf16 v[4:7], v[160:163], v[210:213], v[4:7]
	v_mfma_f32_16x16x32_bf16 v[0:3], v[178:181], v[210:213], v[0:3]
	v_mfma_f32_16x16x32_bf16 v[92:95], v[174:177], v[190:193], v[92:95]
	v_mfma_f32_16x16x32_bf16 v[76:79], v[182:185], v[190:193], v[76:79]
	v_mfma_f32_16x16x32_bf16 v[52:55], v[174:177], v[198:201], v[52:55]
	v_mfma_f32_16x16x32_bf16 v[44:47], v[182:185], v[198:201], v[44:47]
	v_mfma_f32_16x16x32_bf16 v[24:27], v[174:177], v[206:209], v[24:27]
	v_mfma_f32_16x16x32_bf16 v[16:19], v[182:185], v[206:209], v[16:19]
	v_mfma_f32_16x16x32_bf16 v[4:7], v[174:177], v[214:217], v[4:7]
	v_mfma_f32_16x16x32_bf16 v[0:3], v[182:185], v[214:217], v[0:3]
	s_setprio 0
	s_barrier
	s_add_i32 s41, 0, 0x18000
	s_add_i32 s69, 0, 0x1c000
	v_add_u32_e32 v156, s41, v168
	v_add_u32_e32 v173, s69, v168
	ds_read_b128 v[128:131], v156
	ds_read_b128 v[132:135], v156 offset:1024
	ds_read_b128 v[152:155], v156 offset:2048
	ds_read_b128 v[156:159], v156 offset:3072
	ds_read_b128 v[160:163], v173
	ds_read_b128 v[174:177], v173 offset:1024
	ds_read_b128 v[178:181], v173 offset:2048
	ds_read_b128 v[182:185], v173 offset:3072
	s_add_u32 s6, s38, 0xb0000
	s_addc_u32 s7, s39, 0
	s_mov_b32 m0, s46
	v_lshl_add_u64 v[226:227], s[6:7], 0, v[136:137]
	ds_read_b128 v[186:189], v171 offset:32768
	ds_read_b128 v[190:193], v171 offset:33792
	ds_read_b128 v[194:197], v171 offset:34816
	ds_read_b128 v[198:201], v171 offset:35840
	ds_read_b128 v[202:205], v171 offset:36864
	ds_read_b128 v[206:209], v171 offset:37888
	ds_read_b128 v[210:213], v171 offset:38912
	ds_read_b128 v[214:217], v171 offset:39936
	global_load_lds_dwordx4 v[226:227], off
	v_lshl_add_u64 v[226:227], s[6:7], 0, v[140:141]
	s_mov_b32 m0, s47
	s_nop 0
	global_load_lds_dwordx4 v[226:227], off
	s_waitcnt vmcnt(8)
	s_waitcnt lgkmcnt(0)
	s_barrier
	s_setprio 1
	s_waitcnt lgkmcnt(0)
	v_mfma_f32_16x16x32_bf16 v[56:59], v[128:131], v[186:189], v[56:59]
	v_mfma_f32_16x16x32_bf16 v[60:63], v[152:155], v[186:189], v[60:63]
	v_mfma_f32_16x16x32_bf16 v[84:87], v[128:131], v[194:197], v[84:87]
	v_mfma_f32_16x16x32_bf16 v[88:91], v[152:155], v[194:197], v[88:91]
	v_mfma_f32_16x16x32_bf16 v[112:115], v[128:131], v[202:205], v[112:115]
	v_mfma_f32_16x16x32_bf16 v[116:119], v[152:155], v[202:205], v[116:119]
	v_mfma_f32_16x16x32_bf16 v[120:123], v[128:131], v[210:213], v[120:123]
	v_mfma_f32_16x16x32_bf16 v[124:127], v[152:155], v[210:213], v[124:127]
	v_mfma_f32_16x16x32_bf16 v[56:59], v[132:135], v[190:193], v[56:59]
	v_mfma_f32_16x16x32_bf16 v[60:63], v[156:159], v[190:193], v[60:63]
	v_mfma_f32_16x16x32_bf16 v[84:87], v[132:135], v[198:201], v[84:87]
	v_mfma_f32_16x16x32_bf16 v[88:91], v[156:159], v[198:201], v[88:91]
	v_mfma_f32_16x16x32_bf16 v[112:115], v[132:135], v[206:209], v[112:115]
	v_mfma_f32_16x16x32_bf16 v[116:119], v[156:159], v[206:209], v[116:119]
	v_mfma_f32_16x16x32_bf16 v[120:123], v[132:135], v[214:217], v[120:123]
	v_mfma_f32_16x16x32_bf16 v[124:127], v[156:159], v[214:217], v[124:127]
	v_mfma_f32_16x16x32_bf16 v[20:23], v[160:163], v[186:189], v[20:23]
	v_mfma_f32_16x16x32_bf16 v[28:31], v[178:181], v[186:189], v[28:31]
	v_mfma_f32_16x16x32_bf16 v[40:43], v[160:163], v[194:197], v[40:43]
	v_mfma_f32_16x16x32_bf16 v[48:51], v[178:181], v[194:197], v[48:51]
	v_mfma_f32_16x16x32_bf16 v[64:67], v[160:163], v[202:205], v[64:67]
	v_mfma_f32_16x16x32_bf16 v[80:83], v[178:181], v[202:205], v[80:83]
	v_mfma_f32_16x16x32_bf16 v[96:99], v[160:163], v[210:213], v[96:99]
	v_mfma_f32_16x16x32_bf16 v[104:107], v[178:181], v[210:213], v[104:107]
	v_mfma_f32_16x16x32_bf16 v[20:23], v[174:177], v[190:193], v[20:23]
	v_mfma_f32_16x16x32_bf16 v[28:31], v[182:185], v[190:193], v[28:31]
	v_mfma_f32_16x16x32_bf16 v[40:43], v[174:177], v[198:201], v[40:43]
	v_mfma_f32_16x16x32_bf16 v[48:51], v[182:185], v[198:201], v[48:51]
	v_mfma_f32_16x16x32_bf16 v[64:67], v[174:177], v[206:209], v[64:67]
	v_mfma_f32_16x16x32_bf16 v[80:83], v[182:185], v[206:209], v[80:83]
	v_mfma_f32_16x16x32_bf16 v[96:99], v[174:177], v[214:217], v[96:99]
	v_mfma_f32_16x16x32_bf16 v[104:107], v[182:185], v[214:217], v[104:107]
	s_setprio 0
	s_barrier
; #define PG8_STAGE(bufoff, gbase, voff) do { _Pragma("unroll") for (int _i = 0; _i < 2; ++_i) \
;         __builtin_amdgcn_global_load_lds((const unsigned*)((const char*)(gbase) + (voff)[_i]), (LAS unsigned*)(lds + (bufoff) + ldsw + _i * 8192), 16, 0, 0); } while (0)
; #define PG8_LDA(dst, b, h) do { _Pragma("unroll") for (int m = 0; m < 4; ++m) _Pragma("unroll") for (int k = 0; k < 2; ++k) dst[m][k] = *(const LAS bf16x8*)(lds + PG8_SA(b, h) + aoff + m * 2048 + k * 1024); } while (0)
; #define PG8_MMA(ai, bj, At, Bt) do { __builtin_amdgcn_s_setprio(1); _Pragma("unroll") for (int m = 0; m < 4; ++m) _Pragma("unroll") for (int n = 0; n < 2; ++n) _Pragma("unroll") for (int k = 0; k < 2; ++k) \
;         acc[ai][bj][m][n] = __builtin_amdgcn_mfma_f32_16x16x32_bf16(Bt[n][k], At[m][k], acc[ai][bj][m][n], 0, 0, 0); __builtin_amdgcn_s_setprio(0); } while (0)
; #define PG8_WAIT_V(n) asm volatile("s_waitcnt vmcnt(" #n ")" ::: "memory")
; #define PG8_WAIT_L(n) asm volatile("s_waitcnt lgkmcnt(" #n ")" ::: "memory")
; #define PG8_BAR __builtin_amdgcn_s_barrier()
; #define PG8_SCHED __builtin_amdgcn_sched_barrier(0)
; template <class Epi, class Sched>
; __device__ __forceinline__ void gemm_phase(LAS unsigned char* lds, const Gemm g, const Sched& S, const Epi& E, int wid) {
;     ...
;             PG8_LDA(At, 1, 1); PG8_STAGE(PG8_SB(1, 0), b3, voffB); PG8_STAGE(PG8_SB(1, 1), b3 + hstep, voffB); PG8_STAGE(PG8_SA(1, 0), a3, voffA);
;             PG8_WAIT_V(8); PG8_WAIT_L(0); PG8_BAR; PG8_MMA(1, 0, At, B0); PG8_MMA(1, 1, At, B1); PG8_BAR; PG8_SCHED;
	s_add_i32 s6, s41, s75
	v_lshl_add_u64 v[218:219], v[218:219], 0, s[22:23]
	s_mov_b32 m0, s6
	ds_read_b128 v[186:189], v171 offset:49152
	ds_read_b128 v[190:193], v171 offset:50176
	ds_read_b128 v[194:197], v171 offset:51200
	ds_read_b128 v[198:201], v171 offset:52224
	ds_read_b128 v[202:205], v171 offset:53248
	ds_read_b128 v[206:209], v171 offset:54272
	ds_read_b128 v[210:213], v171 offset:55296
	ds_read_b128 v[214:217], v171 offset:56320
	global_load_lds_dwordx4 v[218:219], off
	s_add_i32 m0, s6, 0x2000
	s_add_u32 s6, s10, 0xb0080
	v_lshl_add_u64 v[218:219], v[220:221], 0, s[22:23]
	s_addc_u32 s7, s11, 0
	s_add_i32 s10, s69, s75
	global_load_lds_dwordx4 v[218:219], off
	v_lshl_add_u64 v[218:219], s[6:7], 0, v[138:139]
	s_mov_b32 m0, s10
	s_nop 0
	global_load_lds_dwordx4 v[218:219], off
	v_lshl_add_u64 v[218:219], s[6:7], 0, v[142:143]
	s_add_i32 m0, s10, 0x2000
	s_nop 0
	global_load_lds_dwordx4 v[218:219], off
	v_lshl_add_u64 v[218:219], v[222:223], 0, s[22:23]
	s_mov_b32 m0, s53
	s_nop 0
	global_load_lds_dwordx4 v[218:219], off
	v_lshl_add_u64 v[218:219], v[224:225], 0, s[22:23]
	s_mov_b32 m0, s54
	s_nop 0
	global_load_lds_dwordx4 v[218:219], off
	s_waitcnt vmcnt(8)
	s_waitcnt lgkmcnt(0)
	s_barrier
	s_setprio 1
	s_waitcnt lgkmcnt(0)
	v_mfma_f32_16x16x32_bf16 v[108:111], v[128:131], v[186:189], v[108:111]
	v_mfma_f32_16x16x32_bf16 v[100:103], v[152:155], v[186:189], v[100:103]
	v_mfma_f32_16x16x32_bf16 v[72:75], v[128:131], v[194:197], v[72:75]
	v_mfma_f32_16x16x32_bf16 v[68:71], v[152:155], v[194:197], v[68:71]
	v_mfma_f32_16x16x32_bf16 v[36:39], v[128:131], v[202:205], v[36:39]
	v_mfma_f32_16x16x32_bf16 v[32:35], v[152:155], v[202:205], v[32:35]
	v_mfma_f32_16x16x32_bf16 v[12:15], v[128:131], v[210:213], v[12:15]
	v_mfma_f32_16x16x32_bf16 v[8:11], v[152:155], v[210:213], v[8:11]
	v_mfma_f32_16x16x32_bf16 v[108:111], v[132:135], v[190:193], v[108:111]
	v_mfma_f32_16x16x32_bf16 v[100:103], v[156:159], v[190:193], v[100:103]
	v_mfma_f32_16x16x32_bf16 v[72:75], v[132:135], v[198:201], v[72:75]
	v_mfma_f32_16x16x32_bf16 v[68:71], v[156:159], v[198:201], v[68:71]
	v_mfma_f32_16x16x32_bf16 v[36:39], v[132:135], v[206:209], v[36:39]
	v_mfma_f32_16x16x32_bf16 v[32:35], v[156:159], v[206:209], v[32:35]
	v_mfma_f32_16x16x32_bf16 v[12:15], v[132:135], v[214:217], v[12:15]
	v_mfma_f32_16x16x32_bf16 v[8:11], v[156:159], v[214:217], v[8:11]
	v_mfma_f32_16x16x32_bf16 v[92:95], v[160:163], v[186:189], v[92:95]
	v_mfma_f32_16x16x32_bf16 v[76:79], v[178:181], v[186:189], v[76:79]
	v_mfma_f32_16x16x32_bf16 v[52:55], v[160:163], v[194:197], v[52:55]
	v_mfma_f32_16x16x32_bf16 v[44:47], v[178:181], v[194:197], v[44:47]
	v_mfma_f32_16x16x32_bf16 v[24:27], v[160:163], v[202:205], v[24:27]
	v_mfma_f32_16x16x32_bf16 v[16:19], v[178:181], v[202:205], v[16:19]
	v_mfma_f32_16x16x32_bf16 v[4:7], v[160:163], v[210:213], v[4:7]
	v_mfma_f32_16x16x32_bf16 v[0:3], v[178:181], v[210:213], v[0:3]
	v_mfma_f32_16x16x32_bf16 v[92:95], v[174:177], v[190:193], v[92:95]
	v_mfma_f32_16x16x32_bf16 v[76:79], v[182:185], v[190:193], v[76:79]
	v_mfma_f32_16x16x32_bf16 v[52:55], v[174:177], v[198:201], v[52:55]
	v_mfma_f32_16x16x32_bf16 v[44:47], v[182:185], v[198:201], v[44:47]
	v_mfma_f32_16x16x32_bf16 v[24:27], v[174:177], v[206:209], v[24:27]
	v_mfma_f32_16x16x32_bf16 v[16:19], v[182:185], v[206:209], v[16:19]
	v_mfma_f32_16x16x32_bf16 v[4:7], v[174:177], v[214:217], v[4:7]
	v_mfma_f32_16x16x32_bf16 v[0:3], v[182:185], v[214:217], v[0:3]
	s_setprio 0
	s_barrier
	s_add_i32 s40, s40, 2
	s_add_u32 s35, s35, 0x100
	s_addc_u32 s37, s37, 0
	s_cmp_gt_u32 s40, 41
	s_mov_b64 s[6:7], s[4:5]
	s_cbranch_scc0 .LBB0_573
	s_and_b64 vcc, exec, s[24:25]
	s_cbranch_vccz .LBB0_576
	s_barrier

; #define PG8_STAGE(bufoff, gbase, voff) do { _Pragma("unroll") for (int _i = 0; _i < 2; ++_i) \
;         __builtin_amdgcn_global_load_lds((const unsigned*)((const char*)(gbase) + (voff)[_i]), (LAS unsigned*)(lds + (bufoff) + ldsw + _i * 8192), 16, 0, 0); } while (0)
; #define PG8_LDA(dst, b, h) do { _Pragma("unroll") for (int m = 0; m < 4; ++m) _Pragma("unroll") for (int k = 0; k < 2; ++k) dst[m][k] = *(const LAS bf16x8*)(lds + PG8_SA(b, h) + aoff + m * 2048 + k * 1024); } while (0)
; #define PG8_LDB(dst, b, h) do { _Pragma("unroll") for (int n = 0; n < 2; ++n) _Pragma("unroll") for (int k = 0; k < 2; ++k) dst[n][k] = *(const LAS bf16x8*)(lds + PG8_SB(b, h) + boff + n * 2048 + k * 1024); } while (0)
; #define PG8_MMA(ai, bj, At, Bt) do { __builtin_amdgcn_s_setprio(1); _Pragma("unroll") for (int m = 0; m < 4; ++m) _Pragma("unroll") for (int n = 0; n < 2; ++n) _Pragma("unroll") for (int k = 0; k < 2; ++k) \
;         acc[ai][bj][m][n] = __builtin_amdgcn_mfma_f32_16x16x32_bf16(Bt[n][k], At[m][k], acc[ai][bj][m][n], 0, 0, 0); __builtin_amdgcn_s_setprio(0); } while (0)
; #define PG8_WAIT_V(n) asm volatile("s_waitcnt vmcnt(" #n ")" ::: "memory")
; #define PG8_WAIT_L(n) asm volatile("s_waitcnt lgkmcnt(" #n ")" ::: "memory")
; #define PG8_BAR __builtin_amdgcn_s_barrier()
; #define PG8_SCHED __builtin_amdgcn_sched_barrier(0)
; template <class Epi, class Sched>
; __device__ __forceinline__ void gemm_phase(LAS unsigned char* lds, const Gemm g, const Sched& S, const Epi& E, int wid) {
;     ...
;             PG8_LDB(B0, 0, 0); PG8_LDB(B1, 0, 1); PG8_SCHED; PG8_LDA(At, 0, 0); PG8_STAGE(PG8_SA(1, 1), a1 + hstep, voffA);
;             PG8_WAIT_V(8); PG8_WAIT_L(0); PG8_BAR; PG8_MMA(0, 0, At, B0); PG8_MMA(0, 1, At, B1); PG8_BAR; PG8_SCHED;
;             PG8_LDA(At, 0, 1); PG8_STAGE(PG8_SB(0, 0), b2, voffB); PG8_STAGE(PG8_SB(0, 1), b2 + hstep, voffB); PG8_STAGE(PG8_SA(0, 0), a2, voffA);
.LBB0_743:
	ds_read_b128 v[150:153], v172
	ds_read_b128 v[154:157], v172 offset:1024
	ds_read_b128 v[158:161], v172 offset:2048
	ds_read_b128 v[162:165], v172 offset:3072
	ds_read_b128 v[176:179], v173
	ds_read_b128 v[180:183], v173 offset:1024
	ds_read_b128 v[184:187], v173 offset:2048
	ds_read_b128 v[188:191], v173 offset:3072
	s_add_u32 s4, s6, 0xfffc0080
	s_addc_u32 s5, s7, -1
	s_cmp_eq_u32 s45, 12
	s_cselect_b32 s15, s13, s5
	s_cselect_b32 s14, s37, s4
	s_cselect_b32 s5, s35, s44
	s_cselect_b32 s4, s42, s43
	v_lshl_add_u64 v[224:225], s[6:7], 0, v[142:143]
	s_add_i32 m0, s23, 0xc000
	ds_read_b128 v[192:195], v174
	ds_read_b128 v[196:199], v174 offset:1024
	ds_read_b128 v[200:203], v174 offset:2048
	ds_read_b128 v[204:207], v174 offset:3072
	ds_read_b128 v[208:211], v174 offset:4096
	ds_read_b128 v[212:215], v174 offset:5120
	ds_read_b128 v[216:219], v174 offset:6144
	ds_read_b128 v[220:223], v174 offset:7168
	global_load_lds_dwordx4 v[224:225], off
	v_lshl_add_u64 v[224:225], s[6:7], 0, v[144:145]
	s_add_i32 m0, s23, 0xe000
	s_nop 0
	global_load_lds_dwordx4 v[224:225], off
	s_waitcnt vmcnt(8)
	s_waitcnt lgkmcnt(0)
	s_barrier
	s_setprio 1
	s_waitcnt lgkmcnt(0)
	v_mfma_f32_16x16x32_bf16 v[60:63], v[150:153], v[192:195], v[60:63]
	v_mfma_f32_16x16x32_bf16 v[56:59], v[158:161], v[192:195], v[56:59]
	v_mfma_f32_16x16x32_bf16 v[52:55], v[150:153], v[200:203], v[52:55]
	v_mfma_f32_16x16x32_bf16 v[48:51], v[158:161], v[200:203], v[48:51]
	v_mfma_f32_16x16x32_bf16 v[44:47], v[150:153], v[208:211], v[44:47]
	v_mfma_f32_16x16x32_bf16 v[40:43], v[158:161], v[208:211], v[40:43]
	v_mfma_f32_16x16x32_bf16 v[36:39], v[150:153], v[216:219], v[36:39]
	v_mfma_f32_16x16x32_bf16 v[32:35], v[158:161], v[216:219], v[32:35]
	v_mfma_f32_16x16x32_bf16 v[60:63], v[154:157], v[196:199], v[60:63]
	v_mfma_f32_16x16x32_bf16 v[56:59], v[162:165], v[196:199], v[56:59]
	v_mfma_f32_16x16x32_bf16 v[52:55], v[154:157], v[204:207], v[52:55]
	v_mfma_f32_16x16x32_bf16 v[48:51], v[162:165], v[204:207], v[48:51]
	v_mfma_f32_16x16x32_bf16 v[44:47], v[154:157], v[212:215], v[44:47]
	v_mfma_f32_16x16x32_bf16 v[40:43], v[162:165], v[212:215], v[40:43]
	v_mfma_f32_16x16x32_bf16 v[36:39], v[154:157], v[220:223], v[36:39]
	v_mfma_f32_16x16x32_bf16 v[32:35], v[162:165], v[220:223], v[32:35]
	v_mfma_f32_16x16x32_bf16 v[124:127], v[176:179], v[192:195], v[124:127]
	v_mfma_f32_16x16x32_bf16 v[120:123], v[184:187], v[192:195], v[120:123]
	v_mfma_f32_16x16x32_bf16 v[116:119], v[176:179], v[200:203], v[116:119]
	v_mfma_f32_16x16x32_bf16 v[112:115], v[184:187], v[200:203], v[112:115]
	v_mfma_f32_16x16x32_bf16 v[108:111], v[176:179], v[208:211], v[108:111]
	v_mfma_f32_16x16x32_bf16 v[104:107], v[184:187], v[208:211], v[104:107]
	v_mfma_f32_16x16x32_bf16 v[100:103], v[176:179], v[216:219], v[100:103]
	v_mfma_f32_16x16x32_bf16 v[96:99], v[184:187], v[216:219], v[96:99]
	v_mfma_f32_16x16x32_bf16 v[124:127], v[180:183], v[196:199], v[124:127]
	v_mfma_f32_16x16x32_bf16 v[120:123], v[188:191], v[196:199], v[120:123]
	v_mfma_f32_16x16x32_bf16 v[116:119], v[180:183], v[204:207], v[116:119]
	v_mfma_f32_16x16x32_bf16 v[112:115], v[188:191], v[204:207], v[112:115]
	v_mfma_f32_16x16x32_bf16 v[108:111], v[180:183], v[212:215], v[108:111]
	v_mfma_f32_16x16x32_bf16 v[104:107], v[188:191], v[212:215], v[104:107]
	v_mfma_f32_16x16x32_bf16 v[100:103], v[180:183], v[220:223], v[100:103]
	v_mfma_f32_16x16x32_bf16 v[96:99], v[188:191], v[220:223], v[96:99]
	s_setprio 0
	s_barrier
	s_add_i32 s46, s66, s75
	v_lshl_add_u64 v[224:225], s[4:5], 0, v[130:131]
	s_mov_b32 m0, s46
	ds_read_b128 v[192:195], v174 offset:16384
	ds_read_b128 v[196:199], v174 offset:17408
	ds_read_b128 v[200:203], v174 offset:18432
	ds_read_b128 v[204:207], v174 offset:19456
	ds_read_b128 v[208:211], v174 offset:20480
	ds_read_b128 v[212:215], v174 offset:21504
	ds_read_b128 v[216:219], v174 offset:22528
	ds_read_b128 v[220:223], v174 offset:23552
	global_load_lds_dwordx4 v[224:225], off
	s_add_i32 m0, s46, 0x2000
	s_add_u32 s46, s4, 0x40000
	v_lshl_add_u64 v[226:227], s[4:5], 0, v[134:135]
	s_addc_u32 s47, s5, 0
	s_add_i32 s48, s67, s75
	global_load_lds_dwordx4 v[226:227], off
	v_lshl_add_u64 v[228:229], s[46:47], 0, v[130:131]
	s_mov_b32 m0, s48
	v_lshl_add_u64 v[230:231], s[14:15], 0, v[132:133]
	global_load_lds_dwordx4 v[228:229], off
	v_lshl_add_u64 v[228:229], s[46:47], 0, v[134:135]
	s_add_i32 m0, s48, 0x2000
	s_nop 0
	global_load_lds_dwordx4 v[228:229], off
	v_lshl_add_u64 v[228:229], s[14:15], 0, v[128:129]
	s_mov_b32 m0, s23
	s_nop 0
	global_load_lds_dwordx4 v[228:229], off
	s_mov_b32 m0, s56
	s_nop 0
	global_load_lds_dwordx4 v[230:231], off
	s_waitcnt vmcnt(8)
	s_waitcnt lgkmcnt(0)
	s_barrier
; #define PG8_STAGE(bufoff, gbase, voff) do { _Pragma("unroll") for (int _i = 0; _i < 2; ++_i) \
;         __builtin_amdgcn_global_load_lds((const unsigned*)((const char*)(gbase) + (voff)[_i]), (LAS unsigned*)(lds + (bufoff) + ldsw + _i * 8192), 16, 0, 0); } while (0)
; #define PG8_LDA(dst, b, h) do { _Pragma("unroll") for (int m = 0; m < 4; ++m) _Pragma("unroll") for (int k = 0; k < 2; ++k) dst[m][k] = *(const LAS bf16x8*)(lds + PG8_SA(b, h) + aoff + m * 2048 + k * 1024); } while (0)
; #define PG8_LDB(dst, b, h) do { _Pragma("unroll") for (int n = 0; n < 2; ++n) _Pragma("unroll") for (int k = 0; k < 2; ++k) dst[n][k] = *(const LAS bf16x8*)(lds + PG8_SB(b, h) + boff + n * 2048 + k * 1024); } while (0)
; #define PG8_MMA(ai, bj, At, Bt) do { __builtin_amdgcn_s_setprio(1); _Pragma("unroll") for (int m = 0; m < 4; ++m) _Pragma("unroll") for (int n = 0; n < 2; ++n) _Pragma("unroll") for (int k = 0; k < 2; ++k) \
;         acc[ai][bj][m][n] = __builtin_amdgcn_mfma_f32_16x16x32_bf16(Bt[n][k], At[m][k], acc[ai][bj][m][n], 0, 0, 0); __builtin_amdgcn_s_setprio(0); } while (0)
; #define PG8_WAIT_V(n) asm volatile("s_waitcnt vmcnt(" #n ")" ::: "memory")
; #define PG8_WAIT_L(n) asm volatile("s_waitcnt lgkmcnt(" #n ")" ::: "memory")
; #define PG8_BAR __builtin_amdgcn_s_barrier()
; #define PG8_SCHED __builtin_amdgcn_sched_barrier(0)
; template <class Epi, class Sched>
; __device__ __forceinline__ void gemm_phase(LAS unsigned char* lds, const Gemm g, const Sched& S, const Epi& E, int wid) {
;     ...
;             PG8_WAIT_V(8); PG8_WAIT_L(0); PG8_BAR; PG8_MMA(1, 0, At, B0); PG8_MMA(1, 1, At, B1); PG8_BAR; PG8_SCHED;
;             PG8_LDB(B0, 1, 0); PG8_LDB(B1, 1, 1); PG8_SCHED; PG8_LDA(At, 1, 0); PG8_STAGE(PG8_SA(0, 1), a2 + hstep, voffA);
;             PG8_WAIT_V(8); PG8_WAIT_L(0); PG8_BAR; PG8_MMA(0, 0, At, B0); PG8_MMA(0, 1, At, B1); PG8_BAR; PG8_SCHED;
	s_setprio 1
	s_waitcnt lgkmcnt(0)
	v_mfma_f32_16x16x32_bf16 v[28:31], v[150:153], v[192:195], v[28:31]
	v_mfma_f32_16x16x32_bf16 v[24:27], v[158:161], v[192:195], v[24:27]
	v_mfma_f32_16x16x32_bf16 v[20:23], v[150:153], v[200:203], v[20:23]
	v_mfma_f32_16x16x32_bf16 v[16:19], v[158:161], v[200:203], v[16:19]
	v_mfma_f32_16x16x32_bf16 v[12:15], v[150:153], v[208:211], v[12:15]
	v_mfma_f32_16x16x32_bf16 v[8:11], v[158:161], v[208:211], v[8:11]
	v_mfma_f32_16x16x32_bf16 v[4:7], v[150:153], v[216:219], v[4:7]
	v_mfma_f32_16x16x32_bf16 v[0:3], v[158:161], v[216:219], v[0:3]
	v_mfma_f32_16x16x32_bf16 v[28:31], v[154:157], v[196:199], v[28:31]
	v_mfma_f32_16x16x32_bf16 v[24:27], v[162:165], v[196:199], v[24:27]
	v_mfma_f32_16x16x32_bf16 v[20:23], v[154:157], v[204:207], v[20:23]
	v_mfma_f32_16x16x32_bf16 v[16:19], v[162:165], v[204:207], v[16:19]
	v_mfma_f32_16x16x32_bf16 v[12:15], v[154:157], v[212:215], v[12:15]
	v_mfma_f32_16x16x32_bf16 v[8:11], v[162:165], v[212:215], v[8:11]
	v_mfma_f32_16x16x32_bf16 v[4:7], v[154:157], v[220:223], v[4:7]
	v_mfma_f32_16x16x32_bf16 v[0:3], v[162:165], v[220:223], v[0:3]
	v_mfma_f32_16x16x32_bf16 v[92:95], v[176:179], v[192:195], v[92:95]
	v_mfma_f32_16x16x32_bf16 v[88:91], v[184:187], v[192:195], v[88:91]
	v_mfma_f32_16x16x32_bf16 v[84:87], v[176:179], v[200:203], v[84:87]
	v_mfma_f32_16x16x32_bf16 v[80:83], v[184:187], v[200:203], v[80:83]
	v_mfma_f32_16x16x32_bf16 v[76:79], v[176:179], v[208:211], v[76:79]
	v_mfma_f32_16x16x32_bf16 v[72:75], v[184:187], v[208:211], v[72:75]
	v_mfma_f32_16x16x32_bf16 v[68:71], v[176:179], v[216:219], v[68:71]
	v_mfma_f32_16x16x32_bf16 v[64:67], v[184:187], v[216:219], v[64:67]
	v_mfma_f32_16x16x32_bf16 v[92:95], v[180:183], v[196:199], v[92:95]
	v_mfma_f32_16x16x32_bf16 v[88:91], v[188:191], v[196:199], v[88:91]
	v_mfma_f32_16x16x32_bf16 v[84:87], v[180:183], v[204:207], v[84:87]
	v_mfma_f32_16x16x32_bf16 v[80:83], v[188:191], v[204:207], v[80:83]
	v_mfma_f32_16x16x32_bf16 v[76:79], v[180:183], v[212:215], v[76:79]
	v_mfma_f32_16x16x32_bf16 v[72:75], v[188:191], v[212:215], v[72:75]
	v_mfma_f32_16x16x32_bf16 v[68:71], v[180:183], v[220:223], v[68:71]
	v_mfma_f32_16x16x32_bf16 v[64:67], v[188:191], v[220:223], v[64:67]
	s_setprio 0
	s_barrier
	s_add_i32 s46, 0, 0x18000
	v_add_u32_e32 v136, s46, v170
	s_add_i32 s47, 0, 0x1c000
	ds_read_b128 v[150:153], v136
	ds_read_b128 v[154:157], v136 offset:1024
	ds_read_b128 v[158:161], v136 offset:2048
	ds_read_b128 v[162:165], v136 offset:3072
	v_add_u32_e32 v136, s47, v170
	ds_read_b128 v[176:179], v136
	ds_read_b128 v[180:183], v136 offset:1024
	ds_read_b128 v[184:187], v136 offset:2048
	ds_read_b128 v[188:191], v136 offset:3072
	s_add_u32 s14, s14, 0x40000
	s_addc_u32 s15, s15, 0
	s_mov_b32 m0, s57
	v_lshl_add_u64 v[232:233], s[14:15], 0, v[128:129]
	ds_read_b128 v[192:195], v174 offset:32768
	ds_read_b128 v[196:199], v174 offset:33792
	ds_read_b128 v[200:203], v174 offset:34816
	ds_read_b128 v[204:207], v174 offset:35840
	ds_read_b128 v[208:211], v174 offset:36864
	ds_read_b128 v[212:215], v174 offset:37888
	ds_read_b128 v[216:219], v174 offset:38912
	ds_read_b128 v[220:223], v174 offset:39936
	global_load_lds_dwordx4 v[232:233], off
	v_lshl_add_u64 v[232:233], s[14:15], 0, v[132:133]
	s_mov_b32 m0, s58
	s_nop 0
	global_load_lds_dwordx4 v[232:233], off
	s_waitcnt vmcnt(8)
	s_waitcnt lgkmcnt(0)
	s_barrier
	s_setprio 1
	s_waitcnt lgkmcnt(0)
	v_mfma_f32_16x16x32_bf16 v[60:63], v[150:153], v[192:195], v[60:63]
	v_mfma_f32_16x16x32_bf16 v[56:59], v[158:161], v[192:195], v[56:59]
	v_mfma_f32_16x16x32_bf16 v[52:55], v[150:153], v[200:203], v[52:55]
	v_mfma_f32_16x16x32_bf16 v[48:51], v[158:161], v[200:203], v[48:51]
	v_mfma_f32_16x16x32_bf16 v[44:47], v[150:153], v[208:211], v[44:47]
	v_mfma_f32_16x16x32_bf16 v[40:43], v[158:161], v[208:211], v[40:43]
	v_mfma_f32_16x16x32_bf16 v[36:39], v[150:153], v[216:219], v[36:39]
	v_mfma_f32_16x16x32_bf16 v[32:35], v[158:161], v[216:219], v[32:35]
	v_mfma_f32_16x16x32_bf16 v[60:63], v[154:157], v[196:199], v[60:63]
	v_mfma_f32_16x16x32_bf16 v[56:59], v[162:165], v[196:199], v[56:59]
	v_mfma_f32_16x16x32_bf16 v[52:55], v[154:157], v[204:207], v[52:55]
	v_mfma_f32_16x16x32_bf16 v[48:51], v[162:165], v[204:207], v[48:51]
	v_mfma_f32_16x16x32_bf16 v[44:47], v[154:157], v[212:215], v[44:47]
	v_mfma_f32_16x16x32_bf16 v[40:43], v[162:165], v[212:215], v[40:43]
	v_mfma_f32_16x16x32_bf16 v[36:39], v[154:157], v[220:223], v[36:39]
	v_mfma_f32_16x16x32_bf16 v[32:35], v[162:165], v[220:223], v[32:35]
	v_mfma_f32_16x16x32_bf16 v[124:127], v[176:179], v[192:195], v[124:127]
	v_mfma_f32_16x16x32_bf16 v[120:123], v[184:187], v[192:195], v[120:123]
	v_mfma_f32_16x16x32_bf16 v[116:119], v[176:179], v[200:203], v[116:119]
	v_mfma_f32_16x16x32_bf16 v[112:115], v[184:187], v[200:203], v[112:115]
	v_mfma_f32_16x16x32_bf16 v[108:111], v[176:179], v[208:211], v[108:111]
	v_mfma_f32_16x16x32_bf16 v[104:107], v[184:187], v[208:211], v[104:107]
	v_mfma_f32_16x16x32_bf16 v[100:103], v[176:179], v[216:219], v[100:103]
	v_mfma_f32_16x16x32_bf16 v[96:99], v[184:187], v[216:219], v[96:99]
	v_mfma_f32_16x16x32_bf16 v[124:127], v[180:183], v[196:199], v[124:127]
	v_mfma_f32_16x16x32_bf16 v[120:123], v[188:191], v[196:199], v[120:123]
	v_mfma_f32_16x16x32_bf16 v[116:119], v[180:183], v[204:207], v[116:119]
	v_mfma_f32_16x16x32_bf16 v[112:115], v[188:191], v[204:207], v[112:115]
	v_mfma_f32_16x16x32_bf16 v[108:111], v[180:183], v[212:215], v[108:111]
	v_mfma_f32_16x16x32_bf16 v[104:107], v[188:191], v[212:215], v[104:107]
	v_mfma_f32_16x16x32_bf16 v[100:103], v[180:183], v[220:223], v[100:103]
	v_mfma_f32_16x16x32_bf16 v[96:99], v[188:191], v[220:223], v[96:99]
	s_setprio 0
	s_barrier
; #define PG8_STAGE(bufoff, gbase, voff) do { _Pragma("unroll") for (int _i = 0; _i < 2; ++_i) \
;         __builtin_amdgcn_global_load_lds((const unsigned*)((const char*)(gbase) + (voff)[_i]), (LAS unsigned*)(lds + (bufoff) + ldsw + _i * 8192), 16, 0, 0); } while (0)
; #define PG8_LDA(dst, b, h) do { _Pragma("unroll") for (int m = 0; m < 4; ++m) _Pragma("unroll") for (int k = 0; k < 2; ++k) dst[m][k] = *(const LAS bf16x8*)(lds + PG8_SA(b, h) + aoff + m * 2048 + k * 1024); } while (0)
; #define PG8_MMA(ai, bj, At, Bt) do { __builtin_amdgcn_s_setprio(1); _Pragma("unroll") for (int m = 0; m < 4; ++m) _Pragma("unroll") for (int n = 0; n < 2; ++n) _Pragma("unroll") for (int k = 0; k < 2; ++k) \
;         acc[ai][bj][m][n] = __builtin_amdgcn_mfma_f32_16x16x32_bf16(Bt[n][k], At[m][k], acc[ai][bj][m][n], 0, 0, 0); __builtin_amdgcn_s_setprio(0); } while (0)
; #define PG8_WAIT_V(n) asm volatile("s_waitcnt vmcnt(" #n ")" ::: "memory")
; #define PG8_WAIT_L(n) asm volatile("s_waitcnt lgkmcnt(" #n ")" ::: "memory")
; #define PG8_BAR __builtin_amdgcn_s_barrier()
; #define PG8_SCHED __builtin_amdgcn_sched_barrier(0)
; template <class Epi, class Sched>
; __device__ __forceinline__ void gemm_phase(LAS unsigned char* lds, const Gemm g, const Sched& S, const Epi& E, int wid) {
;     ...
;             PG8_LDA(At, 1, 1); PG8_STAGE(PG8_SB(1, 0), b3, voffB); PG8_STAGE(PG8_SB(1, 1), b3 + hstep, voffB); PG8_STAGE(PG8_SA(1, 0), a3, voffA);
;             PG8_WAIT_V(8); PG8_WAIT_L(0); PG8_BAR; PG8_MMA(1, 0, At, B0); PG8_MMA(1, 1, At, B1); PG8_BAR; PG8_SCHED;
	s_add_i32 s14, s46, s75
	v_lshl_add_u64 v[224:225], v[224:225], 0, s[20:21]
	s_mov_b32 m0, s14
	ds_read_b128 v[192:195], v174 offset:49152
	ds_read_b128 v[196:199], v174 offset:50176
	ds_read_b128 v[200:203], v174 offset:51200
	ds_read_b128 v[204:207], v174 offset:52224
	ds_read_b128 v[208:211], v174 offset:53248
	ds_read_b128 v[212:215], v174 offset:54272
	ds_read_b128 v[216:219], v174 offset:55296
	ds_read_b128 v[220:223], v174 offset:56320
	global_load_lds_dwordx4 v[224:225], off
	s_add_i32 m0, s14, 0x2000
	s_add_u32 s4, s4, 0x40080
	v_lshl_add_u64 v[224:225], v[226:227], 0, s[20:21]
	s_addc_u32 s5, s5, 0
	s_add_i32 s14, s47, s75
	global_load_lds_dwordx4 v[224:225], off
	v_lshl_add_u64 v[224:225], s[4:5], 0, v[130:131]
	s_mov_b32 m0, s14
	s_nop 0
	global_load_lds_dwordx4 v[224:225], off
	v_lshl_add_u64 v[224:225], s[4:5], 0, v[134:135]
	s_add_i32 m0, s14, 0x2000
	s_nop 0
	global_load_lds_dwordx4 v[224:225], off
	v_lshl_add_u64 v[224:225], v[228:229], 0, s[20:21]
	s_mov_b32 m0, s61
	s_nop 0
	global_load_lds_dwordx4 v[224:225], off
	v_lshl_add_u64 v[224:225], v[230:231], 0, s[20:21]
	s_mov_b32 m0, s62
	s_nop 0
	global_load_lds_dwordx4 v[224:225], off
	s_waitcnt vmcnt(8)
	s_waitcnt lgkmcnt(0)
	s_barrier
	s_setprio 1
	s_waitcnt lgkmcnt(0)
	v_mfma_f32_16x16x32_bf16 v[28:31], v[150:153], v[192:195], v[28:31]
	v_mfma_f32_16x16x32_bf16 v[24:27], v[158:161], v[192:195], v[24:27]
	v_mfma_f32_16x16x32_bf16 v[20:23], v[150:153], v[200:203], v[20:23]
	v_mfma_f32_16x16x32_bf16 v[16:19], v[158:161], v[200:203], v[16:19]
	v_mfma_f32_16x16x32_bf16 v[12:15], v[150:153], v[208:211], v[12:15]
	v_mfma_f32_16x16x32_bf16 v[8:11], v[158:161], v[208:211], v[8:11]
	v_mfma_f32_16x16x32_bf16 v[4:7], v[150:153], v[216:219], v[4:7]
	v_mfma_f32_16x16x32_bf16 v[0:3], v[158:161], v[216:219], v[0:3]
	v_mfma_f32_16x16x32_bf16 v[28:31], v[154:157], v[196:199], v[28:31]
	v_mfma_f32_16x16x32_bf16 v[24:27], v[162:165], v[196:199], v[24:27]
	v_mfma_f32_16x16x32_bf16 v[20:23], v[154:157], v[204:207], v[20:23]
	v_mfma_f32_16x16x32_bf16 v[16:19], v[162:165], v[204:207], v[16:19]
	v_mfma_f32_16x16x32_bf16 v[12:15], v[154:157], v[212:215], v[12:15]
	v_mfma_f32_16x16x32_bf16 v[8:11], v[162:165], v[212:215], v[8:11]
	v_mfma_f32_16x16x32_bf16 v[4:7], v[154:157], v[220:223], v[4:7]
	v_mfma_f32_16x16x32_bf16 v[0:3], v[162:165], v[220:223], v[0:3]
	v_mfma_f32_16x16x32_bf16 v[92:95], v[176:179], v[192:195], v[92:95]
	v_mfma_f32_16x16x32_bf16 v[88:91], v[184:187], v[192:195], v[88:91]
	v_mfma_f32_16x16x32_bf16 v[84:87], v[176:179], v[200:203], v[84:87]
	v_mfma_f32_16x16x32_bf16 v[80:83], v[184:187], v[200:203], v[80:83]
	v_mfma_f32_16x16x32_bf16 v[76:79], v[176:179], v[208:211], v[76:79]
	v_mfma_f32_16x16x32_bf16 v[72:75], v[184:187], v[208:211], v[72:75]
	v_mfma_f32_16x16x32_bf16 v[68:71], v[176:179], v[216:219], v[68:71]
	v_mfma_f32_16x16x32_bf16 v[64:67], v[184:187], v[216:219], v[64:67]
	v_mfma_f32_16x16x32_bf16 v[92:95], v[180:183], v[196:199], v[92:95]
	v_mfma_f32_16x16x32_bf16 v[88:91], v[188:191], v[196:199], v[88:91]
	v_mfma_f32_16x16x32_bf16 v[84:87], v[180:183], v[204:207], v[84:87]
	v_mfma_f32_16x16x32_bf16 v[80:83], v[188:191], v[204:207], v[80:83]
	v_mfma_f32_16x16x32_bf16 v[76:79], v[180:183], v[212:215], v[76:79]
	v_mfma_f32_16x16x32_bf16 v[72:75], v[188:191], v[212:215], v[72:75]
	v_mfma_f32_16x16x32_bf16 v[68:71], v[180:183], v[220:223], v[68:71]
	v_mfma_f32_16x16x32_bf16 v[64:67], v[188:191], v[220:223], v[64:67]
	s_setprio 0
	s_barrier
	s_add_i32 s45, s45, 2
	s_add_u32 s6, s6, 0x100
	s_addc_u32 s7, s7, 0
	s_add_u32 s43, s43, 0x100
	s_addc_u32 s44, s44, 0
	s_cmp_gt_u32 s45, 13
	s_cbranch_scc0 .LBB0_743
	s_and_b64 vcc, exec, s[24:25]
	s_cbranch_vccz .LBB0_746
	s_barrier

; #define PG8_STAGE(bufoff, gbase, voff) do { _Pragma("unroll") for (int _i = 0; _i < 2; ++_i) \
;         __builtin_amdgcn_global_load_lds((const unsigned*)((const char*)(gbase) + (voff)[_i]), (LAS unsigned*)(lds + (bufoff) + ldsw + _i * 8192), 16, 0, 0); } while (0)
; #define PG8_LDA(dst, b, h) do { _Pragma("unroll") for (int m = 0; m < 4; ++m) _Pragma("unroll") for (int k = 0; k < 2; ++k) dst[m][k] = *(const LAS bf16x8*)(lds + PG8_SA(b, h) + aoff + m * 2048 + k * 1024); } while (0)
; #define PG8_LDB(dst, b, h) do { _Pragma("unroll") for (int n = 0; n < 2; ++n) _Pragma("unroll") for (int k = 0; k < 2; ++k) dst[n][k] = *(const LAS bf16x8*)(lds + PG8_SB(b, h) + boff + n * 2048 + k * 1024); } while (0)
; #define PG8_MMA(ai, bj, At, Bt) do { __builtin_amdgcn_s_setprio(1); _Pragma("unroll") for (int m = 0; m < 4; ++m) _Pragma("unroll") for (int n = 0; n < 2; ++n) _Pragma("unroll") for (int k = 0; k < 2; ++k) \
;         acc[ai][bj][m][n] = __builtin_amdgcn_mfma_f32_16x16x32_bf16(Bt[n][k], At[m][k], acc[ai][bj][m][n], 0, 0, 0); __builtin_amdgcn_s_setprio(0); } while (0)
; #define PG8_WAIT_V(n) asm volatile("s_waitcnt vmcnt(" #n ")" ::: "memory")
; #define PG8_WAIT_L(n) asm volatile("s_waitcnt lgkmcnt(" #n ")" ::: "memory")
; #define PG8_BAR __builtin_amdgcn_s_barrier()
; #define PG8_SCHED __builtin_amdgcn_sched_barrier(0)
; template <class Epi, class Sched>
; __device__ __forceinline__ void gemm_phase(LAS unsigned char* lds, const Gemm g, const Sched& S, const Epi& E, int wid) {
;     ...
;             PG8_LDB(B0, 0, 0); PG8_LDB(B1, 0, 1); PG8_SCHED; PG8_LDA(At, 0, 0); PG8_STAGE(PG8_SA(1, 1), a1 + hstep, voffA);
;             PG8_WAIT_V(8); PG8_WAIT_L(0); PG8_BAR; PG8_MMA(0, 0, At, B0); PG8_MMA(0, 1, At, B1); PG8_BAR; PG8_SCHED;
;             PG8_LDA(At, 0, 1); PG8_STAGE(PG8_SB(0, 0), b2, voffB); PG8_STAGE(PG8_SB(0, 1), b2 + hstep, voffB); PG8_STAGE(PG8_SA(0, 0), a2, voffA);
.LBB0_1909:
	v_add_u32_e32 v1, s48, v165
	ds_read_b128 v[132:135], v1
	ds_read_b128 v[136:139], v1 offset:1024
	ds_read_b128 v[140:143], v1 offset:2048
	ds_read_b128 v[176:179], v1 offset:3072
	v_add_u32_e32 v1, s49, v165
	ds_read_b128 v[180:183], v1
	ds_read_b128 v[184:187], v1 offset:1024
	ds_read_b128 v[188:191], v1 offset:2048
	ds_read_b128 v[192:195], v1 offset:3072
	s_add_u32 s36, s4, 0xfffc0080
	s_addc_u32 s37, s5, -1
	s_cmp_eq_u32 s56, 12
	s_cselect_b32 s41, s29, s37
	s_cselect_b32 s40, s39, s36
	s_cselect_b32 s37, s27, s55
	s_cselect_b32 s36, s53, s54
	v_lshl_add_u64 v[2:3], s[4:5], 0, v[156:157]
	s_add_i32 m0, s3, 0xc000
	ds_read_b128 v[196:199], v175
	ds_read_b128 v[200:203], v175 offset:1024
	ds_read_b128 v[204:207], v175 offset:2048
	ds_read_b128 v[208:211], v175 offset:3072
	ds_read_b128 v[212:215], v175 offset:4096
	ds_read_b128 v[216:219], v175 offset:5120
	ds_read_b128 v[220:223], v175 offset:6144
	ds_read_b128 v[224:227], v175 offset:7168
	global_load_lds_dwordx4 v[2:3], off
	v_lshl_add_u64 v[2:3], s[4:5], 0, v[158:159]
	s_add_i32 m0, s3, 0xe000
	s_nop 0
	global_load_lds_dwordx4 v[2:3], off
	s_waitcnt vmcnt(8)
	s_waitcnt lgkmcnt(0)
	s_barrier
	s_setprio 1
	s_waitcnt lgkmcnt(0)
	v_mfma_f32_16x16x32_bf16 v[128:131], v[132:135], v[196:199], v[128:131]
	v_mfma_f32_16x16x32_bf16 v[124:127], v[140:143], v[196:199], v[124:127]
	v_mfma_f32_16x16x32_bf16 v[120:123], v[132:135], v[204:207], v[120:123]
	v_mfma_f32_16x16x32_bf16 v[116:119], v[140:143], v[204:207], v[116:119]
	v_mfma_f32_16x16x32_bf16 v[112:115], v[132:135], v[212:215], v[112:115]
	v_mfma_f32_16x16x32_bf16 v[108:111], v[140:143], v[212:215], v[108:111]
	v_mfma_f32_16x16x32_bf16 v[104:107], v[132:135], v[220:223], v[104:107]
	v_mfma_f32_16x16x32_bf16 v[100:103], v[140:143], v[220:223], v[100:103]
	v_mfma_f32_16x16x32_bf16 v[128:131], v[136:139], v[200:203], v[128:131]
	v_mfma_f32_16x16x32_bf16 v[124:127], v[176:179], v[200:203], v[124:127]
	v_mfma_f32_16x16x32_bf16 v[120:123], v[136:139], v[208:211], v[120:123]
	v_mfma_f32_16x16x32_bf16 v[116:119], v[176:179], v[208:211], v[116:119]
	v_mfma_f32_16x16x32_bf16 v[112:115], v[136:139], v[216:219], v[112:115]
	v_mfma_f32_16x16x32_bf16 v[108:111], v[176:179], v[216:219], v[108:111]
	v_mfma_f32_16x16x32_bf16 v[104:107], v[136:139], v[224:227], v[104:107]
	v_mfma_f32_16x16x32_bf16 v[100:103], v[176:179], v[224:227], v[100:103]
	v_mfma_f32_16x16x32_bf16 v[96:99], v[180:183], v[196:199], v[96:99]
	v_mfma_f32_16x16x32_bf16 v[92:95], v[188:191], v[196:199], v[92:95]
	v_mfma_f32_16x16x32_bf16 v[88:91], v[180:183], v[204:207], v[88:91]
	v_mfma_f32_16x16x32_bf16 v[84:87], v[188:191], v[204:207], v[84:87]
	v_mfma_f32_16x16x32_bf16 v[80:83], v[180:183], v[212:215], v[80:83]
	v_mfma_f32_16x16x32_bf16 v[76:79], v[188:191], v[212:215], v[76:79]
	v_mfma_f32_16x16x32_bf16 v[72:75], v[180:183], v[220:223], v[72:75]
	v_mfma_f32_16x16x32_bf16 v[68:71], v[188:191], v[220:223], v[68:71]
	v_mfma_f32_16x16x32_bf16 v[96:99], v[184:187], v[200:203], v[96:99]
	v_mfma_f32_16x16x32_bf16 v[92:95], v[192:195], v[200:203], v[92:95]
	v_mfma_f32_16x16x32_bf16 v[88:91], v[184:187], v[208:211], v[88:91]
	v_mfma_f32_16x16x32_bf16 v[84:87], v[192:195], v[208:211], v[84:87]
	v_mfma_f32_16x16x32_bf16 v[80:83], v[184:187], v[216:219], v[80:83]
	v_mfma_f32_16x16x32_bf16 v[76:79], v[192:195], v[216:219], v[76:79]
	v_mfma_f32_16x16x32_bf16 v[72:75], v[184:187], v[224:227], v[72:75]
	v_mfma_f32_16x16x32_bf16 v[68:71], v[192:195], v[224:227], v[68:71]
	s_setprio 0
	s_barrier
	s_add_i32 s57, s48, s75
	v_lshl_add_u64 v[228:229], s[36:37], 0, v[146:147]
	s_mov_b32 m0, s57
	ds_read_b128 v[196:199], v175 offset:16384
	ds_read_b128 v[200:203], v175 offset:17408
	ds_read_b128 v[204:207], v175 offset:18432
	ds_read_b128 v[208:211], v175 offset:19456
	ds_read_b128 v[212:215], v175 offset:20480
	ds_read_b128 v[216:219], v175 offset:21504
	ds_read_b128 v[220:223], v175 offset:22528
	ds_read_b128 v[224:227], v175 offset:23552
	global_load_lds_dwordx4 v[228:229], off
	s_add_i32 m0, s57, 0x2000
	s_add_u32 s58, s36, 0x40000
	v_lshl_add_u64 v[230:231], s[36:37], 0, v[150:151]
	s_addc_u32 s59, s37, 0
	s_add_i32 s57, s49, s75
	global_load_lds_dwordx4 v[230:231], off
	v_lshl_add_u64 v[2:3], s[58:59], 0, v[146:147]
	s_mov_b32 m0, s57
	v_lshl_add_u64 v[232:233], s[40:41], 0, v[144:145]
	global_load_lds_dwordx4 v[2:3], off
	v_lshl_add_u64 v[2:3], s[58:59], 0, v[150:151]
	s_add_i32 m0, s57, 0x2000
	v_lshl_add_u64 v[234:235], s[40:41], 0, v[148:149]
	global_load_lds_dwordx4 v[2:3], off
	s_mov_b32 m0, s3
	s_nop 0
	global_load_lds_dwordx4 v[232:233], off
	s_mov_b32 m0, s42
	s_nop 0
	global_load_lds_dwordx4 v[234:235], off
	s_waitcnt vmcnt(8)
	s_waitcnt lgkmcnt(0)
	s_barrier
; #define PG8_STAGE(bufoff, gbase, voff) do { _Pragma("unroll") for (int _i = 0; _i < 2; ++_i) \
;         __builtin_amdgcn_global_load_lds((const unsigned*)((const char*)(gbase) + (voff)[_i]), (LAS unsigned*)(lds + (bufoff) + ldsw + _i * 8192), 16, 0, 0); } while (0)
; #define PG8_LDA(dst, b, h) do { _Pragma("unroll") for (int m = 0; m < 4; ++m) _Pragma("unroll") for (int k = 0; k < 2; ++k) dst[m][k] = *(const LAS bf16x8*)(lds + PG8_SA(b, h) + aoff + m * 2048 + k * 1024); } while (0)
; #define PG8_LDB(dst, b, h) do { _Pragma("unroll") for (int n = 0; n < 2; ++n) _Pragma("unroll") for (int k = 0; k < 2; ++k) dst[n][k] = *(const LAS bf16x8*)(lds + PG8_SB(b, h) + boff + n * 2048 + k * 1024); } while (0)
; #define PG8_MMA(ai, bj, At, Bt) do { __builtin_amdgcn_s_setprio(1); _Pragma("unroll") for (int m = 0; m < 4; ++m) _Pragma("unroll") for (int n = 0; n < 2; ++n) _Pragma("unroll") for (int k = 0; k < 2; ++k) \
;         acc[ai][bj][m][n] = __builtin_amdgcn_mfma_f32_16x16x32_bf16(Bt[n][k], At[m][k], acc[ai][bj][m][n], 0, 0, 0); __builtin_amdgcn_s_setprio(0); } while (0)
; #define PG8_WAIT_V(n) asm volatile("s_waitcnt vmcnt(" #n ")" ::: "memory")
; #define PG8_WAIT_L(n) asm volatile("s_waitcnt lgkmcnt(" #n ")" ::: "memory")
; #define PG8_BAR __builtin_amdgcn_s_barrier()
; #define PG8_SCHED __builtin_amdgcn_sched_barrier(0)
; template <class Epi, class Sched>
; __device__ __forceinline__ void gemm_phase(LAS unsigned char* lds, const Gemm g, const Sched& S, const Epi& E, int wid) {
;     ...
;             PG8_WAIT_V(8); PG8_WAIT_L(0); PG8_BAR; PG8_MMA(1, 0, At, B0); PG8_MMA(1, 1, At, B1); PG8_BAR; PG8_SCHED;
;             PG8_LDB(B0, 1, 0); PG8_LDB(B1, 1, 1); PG8_SCHED; PG8_LDA(At, 1, 0); PG8_STAGE(PG8_SA(0, 1), a2 + hstep, voffA);
;             PG8_WAIT_V(8); PG8_WAIT_L(0); PG8_BAR; PG8_MMA(0, 0, At, B0); PG8_MMA(0, 1, At, B1); PG8_BAR; PG8_SCHED;
	s_setprio 1
	s_waitcnt lgkmcnt(0)
	v_mfma_f32_16x16x32_bf16 v[64:67], v[132:135], v[196:199], v[64:67]
	v_mfma_f32_16x16x32_bf16 v[60:63], v[140:143], v[196:199], v[60:63]
	v_mfma_f32_16x16x32_bf16 v[56:59], v[132:135], v[204:207], v[56:59]
	v_mfma_f32_16x16x32_bf16 v[52:55], v[140:143], v[204:207], v[52:55]
	v_mfma_f32_16x16x32_bf16 v[48:51], v[132:135], v[212:215], v[48:51]
	v_mfma_f32_16x16x32_bf16 v[44:47], v[140:143], v[212:215], v[44:47]
	v_mfma_f32_16x16x32_bf16 v[40:43], v[132:135], v[220:223], v[40:43]
	v_mfma_f32_16x16x32_bf16 v[36:39], v[140:143], v[220:223], v[36:39]
	v_mfma_f32_16x16x32_bf16 v[64:67], v[136:139], v[200:203], v[64:67]
	v_mfma_f32_16x16x32_bf16 v[60:63], v[176:179], v[200:203], v[60:63]
	v_mfma_f32_16x16x32_bf16 v[56:59], v[136:139], v[208:211], v[56:59]
	v_mfma_f32_16x16x32_bf16 v[52:55], v[176:179], v[208:211], v[52:55]
	v_mfma_f32_16x16x32_bf16 v[48:51], v[136:139], v[216:219], v[48:51]
	v_mfma_f32_16x16x32_bf16 v[44:47], v[176:179], v[216:219], v[44:47]
	v_mfma_f32_16x16x32_bf16 v[40:43], v[136:139], v[224:227], v[40:43]
	v_mfma_f32_16x16x32_bf16 v[36:39], v[176:179], v[224:227], v[36:39]
	v_mfma_f32_16x16x32_bf16 v[32:35], v[180:183], v[196:199], v[32:35]
	v_mfma_f32_16x16x32_bf16 v[28:31], v[188:191], v[196:199], v[28:31]
	v_mfma_f32_16x16x32_bf16 v[24:27], v[180:183], v[204:207], v[24:27]
	v_mfma_f32_16x16x32_bf16 v[20:23], v[188:191], v[204:207], v[20:23]
	v_mfma_f32_16x16x32_bf16 v[16:19], v[180:183], v[212:215], v[16:19]
	v_mfma_f32_16x16x32_bf16 v[12:15], v[188:191], v[212:215], v[12:15]
	v_mfma_f32_16x16x32_bf16 v[8:11], v[180:183], v[220:223], v[8:11]
	v_mfma_f32_16x16x32_bf16 v[2:5], v[188:191], v[220:223], v[4:7]
	v_mfma_f32_16x16x32_bf16 v[32:35], v[184:187], v[200:203], v[32:35]
	v_mfma_f32_16x16x32_bf16 v[28:31], v[192:195], v[200:203], v[28:31]
	v_mfma_f32_16x16x32_bf16 v[24:27], v[184:187], v[208:211], v[24:27]
	v_mfma_f32_16x16x32_bf16 v[20:23], v[192:195], v[208:211], v[20:23]
	v_mfma_f32_16x16x32_bf16 v[16:19], v[184:187], v[216:219], v[16:19]
	v_mfma_f32_16x16x32_bf16 v[12:15], v[192:195], v[216:219], v[12:15]
	v_mfma_f32_16x16x32_bf16 v[8:11], v[184:187], v[224:227], v[8:11]
	v_mfma_f32_16x16x32_bf16 v[2:5], v[192:195], v[224:227], v[2:5]
	s_setprio 0
	s_barrier
	s_add_i32 s57, 0, 0x18000
	v_add_u32_e32 v1, s57, v165
	s_add_i32 s58, 0, 0x1c000
	ds_read_b128 v[132:135], v1
	ds_read_b128 v[136:139], v1 offset:1024
	ds_read_b128 v[140:143], v1 offset:2048
	ds_read_b128 v[176:179], v1 offset:3072
	v_add_u32_e32 v1, s58, v165
	ds_read_b128 v[180:183], v1
	ds_read_b128 v[184:187], v1 offset:1024
	ds_read_b128 v[188:191], v1 offset:2048
	ds_read_b128 v[192:195], v1 offset:3072
	s_add_u32 s40, s40, 0x40000
	s_addc_u32 s41, s41, 0
	s_mov_b32 m0, s43
	v_lshl_add_u64 v[6:7], s[40:41], 0, v[144:145]
	ds_read_b128 v[196:199], v175 offset:32768
	ds_read_b128 v[200:203], v175 offset:33792
	ds_read_b128 v[204:207], v175 offset:34816
	ds_read_b128 v[208:211], v175 offset:35840
	ds_read_b128 v[212:215], v175 offset:36864
	ds_read_b128 v[216:219], v175 offset:37888
	ds_read_b128 v[220:223], v175 offset:38912
	ds_read_b128 v[224:227], v175 offset:39936
	global_load_lds_dwordx4 v[6:7], off
	v_lshl_add_u64 v[6:7], s[40:41], 0, v[148:149]
	s_mov_b32 m0, s44
	s_nop 0
	global_load_lds_dwordx4 v[6:7], off
	s_waitcnt vmcnt(8)
	s_waitcnt lgkmcnt(0)
	s_barrier
	s_setprio 1
	s_waitcnt lgkmcnt(0)
	v_mfma_f32_16x16x32_bf16 v[128:131], v[132:135], v[196:199], v[128:131]
	v_mfma_f32_16x16x32_bf16 v[124:127], v[140:143], v[196:199], v[124:127]
	v_mfma_f32_16x16x32_bf16 v[120:123], v[132:135], v[204:207], v[120:123]
	v_mfma_f32_16x16x32_bf16 v[116:119], v[140:143], v[204:207], v[116:119]
	v_mfma_f32_16x16x32_bf16 v[112:115], v[132:135], v[212:215], v[112:115]
	v_mfma_f32_16x16x32_bf16 v[108:111], v[140:143], v[212:215], v[108:111]
	v_mfma_f32_16x16x32_bf16 v[104:107], v[132:135], v[220:223], v[104:107]
	v_mfma_f32_16x16x32_bf16 v[100:103], v[140:143], v[220:223], v[100:103]
	v_mfma_f32_16x16x32_bf16 v[128:131], v[136:139], v[200:203], v[128:131]
	v_mfma_f32_16x16x32_bf16 v[124:127], v[176:179], v[200:203], v[124:127]
	v_mfma_f32_16x16x32_bf16 v[120:123], v[136:139], v[208:211], v[120:123]
	v_mfma_f32_16x16x32_bf16 v[116:119], v[176:179], v[208:211], v[116:119]
	v_mfma_f32_16x16x32_bf16 v[112:115], v[136:139], v[216:219], v[112:115]
	v_mfma_f32_16x16x32_bf16 v[108:111], v[176:179], v[216:219], v[108:111]
	v_mfma_f32_16x16x32_bf16 v[104:107], v[136:139], v[224:227], v[104:107]
	v_mfma_f32_16x16x32_bf16 v[100:103], v[176:179], v[224:227], v[100:103]
	v_mfma_f32_16x16x32_bf16 v[96:99], v[180:183], v[196:199], v[96:99]
	v_mfma_f32_16x16x32_bf16 v[92:95], v[188:191], v[196:199], v[92:95]
	v_mfma_f32_16x16x32_bf16 v[88:91], v[180:183], v[204:207], v[88:91]
	v_mfma_f32_16x16x32_bf16 v[84:87], v[188:191], v[204:207], v[84:87]
	v_mfma_f32_16x16x32_bf16 v[80:83], v[180:183], v[212:215], v[80:83]
	v_mfma_f32_16x16x32_bf16 v[76:79], v[188:191], v[212:215], v[76:79]
	v_mfma_f32_16x16x32_bf16 v[72:75], v[180:183], v[220:223], v[72:75]
	v_mfma_f32_16x16x32_bf16 v[68:71], v[188:191], v[220:223], v[68:71]
	v_mfma_f32_16x16x32_bf16 v[96:99], v[184:187], v[200:203], v[96:99]
	v_mfma_f32_16x16x32_bf16 v[92:95], v[192:195], v[200:203], v[92:95]
	v_mfma_f32_16x16x32_bf16 v[88:91], v[184:187], v[208:211], v[88:91]
	v_mfma_f32_16x16x32_bf16 v[84:87], v[192:195], v[208:211], v[84:87]
	v_mfma_f32_16x16x32_bf16 v[80:83], v[184:187], v[216:219], v[80:83]
	v_mfma_f32_16x16x32_bf16 v[76:79], v[192:195], v[216:219], v[76:79]
	v_mfma_f32_16x16x32_bf16 v[72:75], v[184:187], v[224:227], v[72:75]
	v_mfma_f32_16x16x32_bf16 v[68:71], v[192:195], v[224:227], v[68:71]
	s_setprio 0
	s_barrier
; #define PG8_STAGE(bufoff, gbase, voff) do { _Pragma("unroll") for (int _i = 0; _i < 2; ++_i) \
;         __builtin_amdgcn_global_load_lds((const unsigned*)((const char*)(gbase) + (voff)[_i]), (LAS unsigned*)(lds + (bufoff) + ldsw + _i * 8192), 16, 0, 0); } while (0)
; #define PG8_LDA(dst, b, h) do { _Pragma("unroll") for (int m = 0; m < 4; ++m) _Pragma("unroll") for (int k = 0; k < 2; ++k) dst[m][k] = *(const LAS bf16x8*)(lds + PG8_SA(b, h) + aoff + m * 2048 + k * 1024); } while (0)
; #define PG8_MMA(ai, bj, At, Bt) do { __builtin_amdgcn_s_setprio(1); _Pragma("unroll") for (int m = 0; m < 4; ++m) _Pragma("unroll") for (int n = 0; n < 2; ++n) _Pragma("unroll") for (int k = 0; k < 2; ++k) \
;         acc[ai][bj][m][n] = __builtin_amdgcn_mfma_f32_16x16x32_bf16(Bt[n][k], At[m][k], acc[ai][bj][m][n], 0, 0, 0); __builtin_amdgcn_s_setprio(0); } while (0)
; #define PG8_WAIT_V(n) asm volatile("s_waitcnt vmcnt(" #n ")" ::: "memory")
; #define PG8_WAIT_L(n) asm volatile("s_waitcnt lgkmcnt(" #n ")" ::: "memory")
; #define PG8_BAR __builtin_amdgcn_s_barrier()
; #define PG8_SCHED __builtin_amdgcn_sched_barrier(0)
; template <class Epi, class Sched>
; __device__ __forceinline__ void gemm_phase(LAS unsigned char* lds, const Gemm g, const Sched& S, const Epi& E, int wid) {
;     ...
;             PG8_LDA(At, 1, 1); PG8_STAGE(PG8_SB(1, 0), b3, voffB); PG8_STAGE(PG8_SB(1, 1), b3 + hstep, voffB); PG8_STAGE(PG8_SA(1, 0), a3, voffA);
;             PG8_WAIT_V(8); PG8_WAIT_L(0); PG8_BAR; PG8_MMA(1, 0, At, B0); PG8_MMA(1, 1, At, B1); PG8_BAR; PG8_SCHED;
	s_add_i32 s40, s57, s75
	v_lshl_add_u64 v[6:7], v[228:229], 0, s[22:23]
	s_mov_b32 m0, s40
	ds_read_b128 v[196:199], v175 offset:49152
	ds_read_b128 v[200:203], v175 offset:50176
	ds_read_b128 v[204:207], v175 offset:51200
	ds_read_b128 v[208:211], v175 offset:52224
	ds_read_b128 v[212:215], v175 offset:53248
	ds_read_b128 v[216:219], v175 offset:54272
	ds_read_b128 v[220:223], v175 offset:55296
	ds_read_b128 v[224:227], v175 offset:56320
	global_load_lds_dwordx4 v[6:7], off
	s_add_i32 m0, s40, 0x2000
	s_add_u32 s36, s36, 0x40080
	v_lshl_add_u64 v[6:7], v[230:231], 0, s[22:23]
	s_addc_u32 s37, s37, 0
	s_add_i32 s40, s58, s75
	global_load_lds_dwordx4 v[6:7], off
	v_lshl_add_u64 v[6:7], s[36:37], 0, v[146:147]
	s_mov_b32 m0, s40
	s_nop 0
	global_load_lds_dwordx4 v[6:7], off
	v_lshl_add_u64 v[6:7], s[36:37], 0, v[150:151]
	s_add_i32 m0, s40, 0x2000
	s_nop 0
	global_load_lds_dwordx4 v[6:7], off
	v_lshl_add_u64 v[6:7], v[232:233], 0, s[22:23]
	s_mov_b32 m0, s45
	s_nop 0
	global_load_lds_dwordx4 v[6:7], off
	v_lshl_add_u64 v[6:7], v[234:235], 0, s[22:23]
	s_mov_b32 m0, s46
	s_nop 0
	global_load_lds_dwordx4 v[6:7], off
	s_waitcnt vmcnt(8)
	s_waitcnt lgkmcnt(0)
	s_barrier
	s_setprio 1
	s_waitcnt lgkmcnt(0)
	v_mfma_f32_16x16x32_bf16 v[64:67], v[132:135], v[196:199], v[64:67]
	v_mfma_f32_16x16x32_bf16 v[60:63], v[140:143], v[196:199], v[60:63]
	v_mfma_f32_16x16x32_bf16 v[56:59], v[132:135], v[204:207], v[56:59]
	v_mfma_f32_16x16x32_bf16 v[52:55], v[140:143], v[204:207], v[52:55]
	v_mfma_f32_16x16x32_bf16 v[48:51], v[132:135], v[212:215], v[48:51]
	v_mfma_f32_16x16x32_bf16 v[44:47], v[140:143], v[212:215], v[44:47]
	v_mfma_f32_16x16x32_bf16 v[40:43], v[132:135], v[220:223], v[40:43]
	v_mfma_f32_16x16x32_bf16 v[36:39], v[140:143], v[220:223], v[36:39]
	v_mfma_f32_16x16x32_bf16 v[64:67], v[136:139], v[200:203], v[64:67]
	v_mfma_f32_16x16x32_bf16 v[60:63], v[176:179], v[200:203], v[60:63]
	v_mfma_f32_16x16x32_bf16 v[56:59], v[136:139], v[208:211], v[56:59]
	v_mfma_f32_16x16x32_bf16 v[52:55], v[176:179], v[208:211], v[52:55]
	v_mfma_f32_16x16x32_bf16 v[48:51], v[136:139], v[216:219], v[48:51]
	v_mfma_f32_16x16x32_bf16 v[44:47], v[176:179], v[216:219], v[44:47]
	v_mfma_f32_16x16x32_bf16 v[40:43], v[136:139], v[224:227], v[40:43]
	v_mfma_f32_16x16x32_bf16 v[36:39], v[176:179], v[224:227], v[36:39]
	v_mfma_f32_16x16x32_bf16 v[32:35], v[180:183], v[196:199], v[32:35]
	v_mfma_f32_16x16x32_bf16 v[28:31], v[188:191], v[196:199], v[28:31]
	v_mfma_f32_16x16x32_bf16 v[24:27], v[180:183], v[204:207], v[24:27]
	v_mfma_f32_16x16x32_bf16 v[20:23], v[188:191], v[204:207], v[20:23]
	v_mfma_f32_16x16x32_bf16 v[16:19], v[180:183], v[212:215], v[16:19]
	v_mfma_f32_16x16x32_bf16 v[12:15], v[188:191], v[212:215], v[12:15]
	v_mfma_f32_16x16x32_bf16 v[6:9], v[180:183], v[220:223], v[8:11]
	v_mfma_f32_16x16x32_bf16 v[2:5], v[188:191], v[220:223], v[2:5]
	v_mfma_f32_16x16x32_bf16 v[32:35], v[184:187], v[200:203], v[32:35]
	v_mfma_f32_16x16x32_bf16 v[28:31], v[192:195], v[200:203], v[28:31]
	v_mfma_f32_16x16x32_bf16 v[24:27], v[184:187], v[208:211], v[24:27]
	v_mfma_f32_16x16x32_bf16 v[20:23], v[192:195], v[208:211], v[20:23]
	v_mfma_f32_16x16x32_bf16 v[16:19], v[184:187], v[216:219], v[16:19]
	v_mfma_f32_16x16x32_bf16 v[12:15], v[192:195], v[216:219], v[12:15]
	v_mfma_f32_16x16x32_bf16 v[8:11], v[184:187], v[224:227], v[6:9]
	v_mfma_f32_16x16x32_bf16 v[4:7], v[192:195], v[224:227], v[2:5]
	s_setprio 0
	s_barrier
	s_add_i32 s56, s56, 2
	s_add_u32 s4, s4, 0x100
	s_addc_u32 s5, s5, 0
	s_add_u32 s54, s54, 0x100
	s_addc_u32 s55, s55, 0
	s_cmp_gt_u32 s56, 13
	s_cbranch_scc0 .LBB0_1909
	s_and_b64 vcc, exec, s[24:25]
	s_cbranch_vccz .LBB0_1912
	s_barrier

; #define PG8_STAGE(bufoff, gbase, voff) do { _Pragma("unroll") for (int _i = 0; _i < 2; ++_i) \
;         __builtin_amdgcn_global_load_lds((const unsigned*)((const char*)(gbase) + (voff)[_i]), (LAS unsigned*)(lds + (bufoff) + ldsw + _i * 8192), 16, 0, 0); } while (0)
; #define PG8_LDA(dst, b, h) do { _Pragma("unroll") for (int m = 0; m < 4; ++m) _Pragma("unroll") for (int k = 0; k < 2; ++k) dst[m][k] = *(const LAS bf16x8*)(lds + PG8_SA(b, h) + aoff + m * 2048 + k * 1024); } while (0)
; #define PG8_LDB(dst, b, h) do { _Pragma("unroll") for (int n = 0; n < 2; ++n) _Pragma("unroll") for (int k = 0; k < 2; ++k) dst[n][k] = *(const LAS bf16x8*)(lds + PG8_SB(b, h) + boff + n * 2048 + k * 1024); } while (0)
; #define PG8_MMA(ai, bj, At, Bt) do { __builtin_amdgcn_s_setprio(1); _Pragma("unroll") for (int m = 0; m < 4; ++m) _Pragma("unroll") for (int n = 0; n < 2; ++n) _Pragma("unroll") for (int k = 0; k < 2; ++k) \
;         acc[ai][bj][m][n] = __builtin_amdgcn_mfma_f32_16x16x32_bf16(Bt[n][k], At[m][k], acc[ai][bj][m][n], 0, 0, 0); __builtin_amdgcn_s_setprio(0); } while (0)
; #define PG8_WAIT_V(n) asm volatile("s_waitcnt vmcnt(" #n ")" ::: "memory")
; #define PG8_WAIT_L(n) asm volatile("s_waitcnt lgkmcnt(" #n ")" ::: "memory")
; #define PG8_BAR __builtin_amdgcn_s_barrier()
; #define PG8_SCHED __builtin_amdgcn_sched_barrier(0)
; template <class Epi, class Sched>
; __device__ __forceinline__ void gemm_phase(LAS unsigned char* lds, const Gemm g, const Sched& S, const Epi& E, int wid) {
;     ...
;             PG8_LDB(B0, 0, 0); PG8_LDB(B1, 0, 1); PG8_SCHED; PG8_LDA(At, 0, 0); PG8_STAGE(PG8_SA(1, 1), a1 + hstep, voffA);
;             PG8_WAIT_V(8); PG8_WAIT_L(0); PG8_BAR; PG8_MMA(0, 0, At, B0); PG8_MMA(0, 1, At, B1); PG8_BAR; PG8_SCHED;
;             PG8_LDA(At, 0, 1); PG8_STAGE(PG8_SB(0, 0), b2, voffB); PG8_STAGE(PG8_SB(0, 1), b2 + hstep, voffB); PG8_STAGE(PG8_SA(0, 0), a2, voffA);
.LBB0_2014:
	ds_read_b128 v[128:131], v169
	ds_read_b128 v[132:135], v169 offset:1024
	ds_read_b128 v[152:155], v169 offset:2048
	ds_read_b128 v[156:159], v169 offset:3072
	ds_read_b128 v[160:163], v170
	ds_read_b128 v[174:177], v170 offset:1024
	ds_read_b128 v[178:181], v170 offset:2048
	ds_read_b128 v[182:185], v170 offset:3072
	s_add_u32 s4, s6, 0xfffc0080
	s_addc_u32 s5, s7, -1
	s_cmp_eq_u32 s44, 12
	s_cselect_b32 s11, s31, s5
	s_cselect_b32 s10, s39, s4
	s_cselect_b32 s5, s29, s43
	s_cselect_b32 s4, s41, s42
	v_lshl_add_u64 v[218:219], s[6:7], 0, v[144:145]
	s_add_i32 m0, s3, 0xc000
	ds_read_b128 v[186:189], v171
	ds_read_b128 v[190:193], v171 offset:1024
	ds_read_b128 v[194:197], v171 offset:2048
	ds_read_b128 v[198:201], v171 offset:3072
	ds_read_b128 v[202:205], v171 offset:4096
	ds_read_b128 v[206:209], v171 offset:5120
	ds_read_b128 v[210:213], v171 offset:6144
	ds_read_b128 v[214:217], v171 offset:7168
	global_load_lds_dwordx4 v[218:219], off
	v_lshl_add_u64 v[218:219], s[6:7], 0, v[146:147]
	s_add_i32 m0, s3, 0xe000
	s_nop 0
	global_load_lds_dwordx4 v[218:219], off
	s_waitcnt vmcnt(8)
	s_waitcnt lgkmcnt(0)
	s_barrier
	s_setprio 1
	s_waitcnt lgkmcnt(0)
	v_mfma_f32_16x16x32_bf16 v[56:59], v[128:131], v[186:189], v[56:59]
	v_mfma_f32_16x16x32_bf16 v[64:67], v[152:155], v[186:189], v[64:67]
	v_mfma_f32_16x16x32_bf16 v[84:87], v[128:131], v[194:197], v[84:87]
	v_mfma_f32_16x16x32_bf16 v[92:95], v[152:155], v[194:197], v[92:95]
	v_mfma_f32_16x16x32_bf16 v[112:115], v[128:131], v[202:205], v[112:115]
	v_mfma_f32_16x16x32_bf16 v[116:119], v[152:155], v[202:205], v[116:119]
	v_mfma_f32_16x16x32_bf16 v[120:123], v[128:131], v[210:213], v[120:123]
	v_mfma_f32_16x16x32_bf16 v[124:127], v[152:155], v[210:213], v[124:127]
	v_mfma_f32_16x16x32_bf16 v[56:59], v[132:135], v[190:193], v[56:59]
	v_mfma_f32_16x16x32_bf16 v[64:67], v[156:159], v[190:193], v[64:67]
	v_mfma_f32_16x16x32_bf16 v[84:87], v[132:135], v[198:201], v[84:87]
	v_mfma_f32_16x16x32_bf16 v[92:95], v[156:159], v[198:201], v[92:95]
	v_mfma_f32_16x16x32_bf16 v[112:115], v[132:135], v[206:209], v[112:115]
	v_mfma_f32_16x16x32_bf16 v[116:119], v[156:159], v[206:209], v[116:119]
	v_mfma_f32_16x16x32_bf16 v[120:123], v[132:135], v[214:217], v[120:123]
	v_mfma_f32_16x16x32_bf16 v[124:127], v[156:159], v[214:217], v[124:127]
	v_mfma_f32_16x16x32_bf16 v[20:23], v[160:163], v[186:189], v[20:23]
	v_mfma_f32_16x16x32_bf16 v[28:31], v[178:181], v[186:189], v[28:31]
	v_mfma_f32_16x16x32_bf16 v[36:39], v[160:163], v[194:197], v[36:39]
	v_mfma_f32_16x16x32_bf16 v[48:51], v[178:181], v[194:197], v[48:51]
	v_mfma_f32_16x16x32_bf16 v[60:63], v[160:163], v[202:205], v[60:63]
	v_mfma_f32_16x16x32_bf16 v[80:83], v[178:181], v[202:205], v[80:83]
	v_mfma_f32_16x16x32_bf16 v[96:99], v[160:163], v[210:213], v[96:99]
	v_mfma_f32_16x16x32_bf16 v[104:107], v[178:181], v[210:213], v[104:107]
	v_mfma_f32_16x16x32_bf16 v[20:23], v[174:177], v[190:193], v[20:23]
	v_mfma_f32_16x16x32_bf16 v[28:31], v[182:185], v[190:193], v[28:31]
	v_mfma_f32_16x16x32_bf16 v[36:39], v[174:177], v[198:201], v[36:39]
	v_mfma_f32_16x16x32_bf16 v[48:51], v[182:185], v[198:201], v[48:51]
	v_mfma_f32_16x16x32_bf16 v[60:63], v[174:177], v[206:209], v[60:63]
	v_mfma_f32_16x16x32_bf16 v[80:83], v[182:185], v[206:209], v[80:83]
	v_mfma_f32_16x16x32_bf16 v[96:99], v[174:177], v[214:217], v[96:99]
	v_mfma_f32_16x16x32_bf16 v[104:107], v[182:185], v[214:217], v[104:107]
	s_setprio 0
	s_barrier
	s_add_i32 s45, s62, s75
	v_lshl_add_u64 v[218:219], s[4:5], 0, v[138:139]
	s_mov_b32 m0, s45
	ds_read_b128 v[186:189], v171 offset:16384
	ds_read_b128 v[190:193], v171 offset:17408
	ds_read_b128 v[194:197], v171 offset:18432
	ds_read_b128 v[198:201], v171 offset:19456
	ds_read_b128 v[202:205], v171 offset:20480
	ds_read_b128 v[206:209], v171 offset:21504
	ds_read_b128 v[210:213], v171 offset:22528
	ds_read_b128 v[214:217], v171 offset:23552
	global_load_lds_dwordx4 v[218:219], off
	s_add_i32 m0, s45, 0x2000
	s_add_u32 s68, s4, 0x40000
	v_lshl_add_u64 v[220:221], s[4:5], 0, v[142:143]
	s_addc_u32 s69, s5, 0
	s_add_i32 s45, s63, s75
	global_load_lds_dwordx4 v[220:221], off
	v_lshl_add_u64 v[222:223], s[68:69], 0, v[138:139]
	s_mov_b32 m0, s45
	v_lshl_add_u64 v[224:225], s[10:11], 0, v[140:141]
	global_load_lds_dwordx4 v[222:223], off
	v_lshl_add_u64 v[222:223], s[68:69], 0, v[142:143]
	s_add_i32 m0, s45, 0x2000
	s_nop 0
	global_load_lds_dwordx4 v[222:223], off
	v_lshl_add_u64 v[222:223], s[10:11], 0, v[136:137]
	s_mov_b32 m0, s3
	s_nop 0
	global_load_lds_dwordx4 v[222:223], off
	s_mov_b32 m0, s46
	s_nop 0
	global_load_lds_dwordx4 v[224:225], off
	s_waitcnt vmcnt(8)
	s_waitcnt lgkmcnt(0)
	s_barrier
; #define PG8_STAGE(bufoff, gbase, voff) do { _Pragma("unroll") for (int _i = 0; _i < 2; ++_i) \
;         __builtin_amdgcn_global_load_lds((const unsigned*)((const char*)(gbase) + (voff)[_i]), (LAS unsigned*)(lds + (bufoff) + ldsw + _i * 8192), 16, 0, 0); } while (0)
; #define PG8_LDA(dst, b, h) do { _Pragma("unroll") for (int m = 0; m < 4; ++m) _Pragma("unroll") for (int k = 0; k < 2; ++k) dst[m][k] = *(const LAS bf16x8*)(lds + PG8_SA(b, h) + aoff + m * 2048 + k * 1024); } while (0)
; #define PG8_LDB(dst, b, h) do { _Pragma("unroll") for (int n = 0; n < 2; ++n) _Pragma("unroll") for (int k = 0; k < 2; ++k) dst[n][k] = *(const LAS bf16x8*)(lds + PG8_SB(b, h) + boff + n * 2048 + k * 1024); } while (0)
; #define PG8_MMA(ai, bj, At, Bt) do { __builtin_amdgcn_s_setprio(1); _Pragma("unroll") for (int m = 0; m < 4; ++m) _Pragma("unroll") for (int n = 0; n < 2; ++n) _Pragma("unroll") for (int k = 0; k < 2; ++k) \
;         acc[ai][bj][m][n] = __builtin_amdgcn_mfma_f32_16x16x32_bf16(Bt[n][k], At[m][k], acc[ai][bj][m][n], 0, 0, 0); __builtin_amdgcn_s_setprio(0); } while (0)
; #define PG8_WAIT_V(n) asm volatile("s_waitcnt vmcnt(" #n ")" ::: "memory")
; #define PG8_WAIT_L(n) asm volatile("s_waitcnt lgkmcnt(" #n ")" ::: "memory")
; #define PG8_BAR __builtin_amdgcn_s_barrier()
; #define PG8_SCHED __builtin_amdgcn_sched_barrier(0)
; template <class Epi, class Sched>
; __device__ __forceinline__ void gemm_phase(LAS unsigned char* lds, const Gemm g, const Sched& S, const Epi& E, int wid) {
;     ...
;             PG8_WAIT_V(8); PG8_WAIT_L(0); PG8_BAR; PG8_MMA(1, 0, At, B0); PG8_MMA(1, 1, At, B1); PG8_BAR; PG8_SCHED;
;             PG8_LDB(B0, 1, 0); PG8_LDB(B1, 1, 1); PG8_SCHED; PG8_LDA(At, 1, 0); PG8_STAGE(PG8_SA(0, 1), a2 + hstep, voffA);
;             PG8_WAIT_V(8); PG8_WAIT_L(0); PG8_BAR; PG8_MMA(0, 0, At, B0); PG8_MMA(0, 1, At, B1); PG8_BAR; PG8_SCHED;
	s_setprio 1
	s_waitcnt lgkmcnt(0)
	v_mfma_f32_16x16x32_bf16 v[108:111], v[128:131], v[186:189], v[108:111]
	v_mfma_f32_16x16x32_bf16 v[100:103], v[152:155], v[186:189], v[100:103]
	v_mfma_f32_16x16x32_bf16 v[72:75], v[128:131], v[194:197], v[72:75]
	v_mfma_f32_16x16x32_bf16 v[68:71], v[152:155], v[194:197], v[68:71]
	v_mfma_f32_16x16x32_bf16 v[40:43], v[128:131], v[202:205], v[40:43]
	v_mfma_f32_16x16x32_bf16 v[32:35], v[152:155], v[202:205], v[32:35]
	v_mfma_f32_16x16x32_bf16 v[12:15], v[128:131], v[210:213], v[12:15]
	v_mfma_f32_16x16x32_bf16 v[8:11], v[152:155], v[210:213], v[8:11]
	v_mfma_f32_16x16x32_bf16 v[108:111], v[132:135], v[190:193], v[108:111]
	v_mfma_f32_16x16x32_bf16 v[100:103], v[156:159], v[190:193], v[100:103]
	v_mfma_f32_16x16x32_bf16 v[72:75], v[132:135], v[198:201], v[72:75]
	v_mfma_f32_16x16x32_bf16 v[68:71], v[156:159], v[198:201], v[68:71]
	v_mfma_f32_16x16x32_bf16 v[40:43], v[132:135], v[206:209], v[40:43]
	v_mfma_f32_16x16x32_bf16 v[32:35], v[156:159], v[206:209], v[32:35]
	v_mfma_f32_16x16x32_bf16 v[12:15], v[132:135], v[214:217], v[12:15]
	v_mfma_f32_16x16x32_bf16 v[8:11], v[156:159], v[214:217], v[8:11]
	v_mfma_f32_16x16x32_bf16 v[88:91], v[160:163], v[186:189], v[88:91]
	v_mfma_f32_16x16x32_bf16 v[76:79], v[178:181], v[186:189], v[76:79]
	v_mfma_f32_16x16x32_bf16 v[52:55], v[160:163], v[194:197], v[52:55]
	v_mfma_f32_16x16x32_bf16 v[44:47], v[178:181], v[194:197], v[44:47]
	v_mfma_f32_16x16x32_bf16 v[24:27], v[160:163], v[202:205], v[24:27]
	v_mfma_f32_16x16x32_bf16 v[16:19], v[178:181], v[202:205], v[16:19]
	v_mfma_f32_16x16x32_bf16 v[4:7], v[160:163], v[210:213], v[4:7]
	v_mfma_f32_16x16x32_bf16 v[0:3], v[178:181], v[210:213], v[0:3]
	v_mfma_f32_16x16x32_bf16 v[88:91], v[174:177], v[190:193], v[88:91]
	v_mfma_f32_16x16x32_bf16 v[76:79], v[182:185], v[190:193], v[76:79]
	v_mfma_f32_16x16x32_bf16 v[52:55], v[174:177], v[198:201], v[52:55]
	v_mfma_f32_16x16x32_bf16 v[44:47], v[182:185], v[198:201], v[44:47]
	v_mfma_f32_16x16x32_bf16 v[24:27], v[174:177], v[206:209], v[24:27]
	v_mfma_f32_16x16x32_bf16 v[16:19], v[182:185], v[206:209], v[16:19]
	v_mfma_f32_16x16x32_bf16 v[4:7], v[174:177], v[214:217], v[4:7]
	v_mfma_f32_16x16x32_bf16 v[0:3], v[182:185], v[214:217], v[0:3]
	s_setprio 0
	s_barrier
	s_add_i32 s45, 0, 0x18000
	s_add_i32 s68, 0, 0x1c000
	v_add_u32_e32 v156, s45, v168
	v_add_u32_e32 v173, s68, v168
	ds_read_b128 v[128:131], v156
	ds_read_b128 v[132:135], v156 offset:1024
	ds_read_b128 v[152:155], v156 offset:2048
	ds_read_b128 v[156:159], v156 offset:3072
	ds_read_b128 v[160:163], v173
	ds_read_b128 v[174:177], v173 offset:1024
	ds_read_b128 v[178:181], v173 offset:2048
	ds_read_b128 v[182:185], v173 offset:3072
	s_add_u32 s10, s10, 0x40000
	s_addc_u32 s11, s11, 0
	s_mov_b32 m0, s47
	v_lshl_add_u64 v[226:227], s[10:11], 0, v[136:137]
	ds_read_b128 v[186:189], v171 offset:32768
	ds_read_b128 v[190:193], v171 offset:33792
	ds_read_b128 v[194:197], v171 offset:34816
	ds_read_b128 v[198:201], v171 offset:35840
	ds_read_b128 v[202:205], v171 offset:36864
	ds_read_b128 v[206:209], v171 offset:37888
	ds_read_b128 v[210:213], v171 offset:38912
	ds_read_b128 v[214:217], v171 offset:39936
	global_load_lds_dwordx4 v[226:227], off
	v_lshl_add_u64 v[226:227], s[10:11], 0, v[140:141]
	s_mov_b32 m0, s48
	s_nop 0
	global_load_lds_dwordx4 v[226:227], off
	s_waitcnt vmcnt(8)
	s_waitcnt lgkmcnt(0)
	s_barrier
	s_setprio 1
	s_waitcnt lgkmcnt(0)
	v_mfma_f32_16x16x32_bf16 v[56:59], v[128:131], v[186:189], v[56:59]
	v_mfma_f32_16x16x32_bf16 v[64:67], v[152:155], v[186:189], v[64:67]
	v_mfma_f32_16x16x32_bf16 v[84:87], v[128:131], v[194:197], v[84:87]
	v_mfma_f32_16x16x32_bf16 v[92:95], v[152:155], v[194:197], v[92:95]
	v_mfma_f32_16x16x32_bf16 v[112:115], v[128:131], v[202:205], v[112:115]
	v_mfma_f32_16x16x32_bf16 v[116:119], v[152:155], v[202:205], v[116:119]
	v_mfma_f32_16x16x32_bf16 v[120:123], v[128:131], v[210:213], v[120:123]
	v_mfma_f32_16x16x32_bf16 v[124:127], v[152:155], v[210:213], v[124:127]
	v_mfma_f32_16x16x32_bf16 v[56:59], v[132:135], v[190:193], v[56:59]
	v_mfma_f32_16x16x32_bf16 v[64:67], v[156:159], v[190:193], v[64:67]
	v_mfma_f32_16x16x32_bf16 v[84:87], v[132:135], v[198:201], v[84:87]
	v_mfma_f32_16x16x32_bf16 v[92:95], v[156:159], v[198:201], v[92:95]
	v_mfma_f32_16x16x32_bf16 v[112:115], v[132:135], v[206:209], v[112:115]
	v_mfma_f32_16x16x32_bf16 v[116:119], v[156:159], v[206:209], v[116:119]
	v_mfma_f32_16x16x32_bf16 v[120:123], v[132:135], v[214:217], v[120:123]
	v_mfma_f32_16x16x32_bf16 v[124:127], v[156:159], v[214:217], v[124:127]
	v_mfma_f32_16x16x32_bf16 v[20:23], v[160:163], v[186:189], v[20:23]
	v_mfma_f32_16x16x32_bf16 v[28:31], v[178:181], v[186:189], v[28:31]
	v_mfma_f32_16x16x32_bf16 v[36:39], v[160:163], v[194:197], v[36:39]
	v_mfma_f32_16x16x32_bf16 v[48:51], v[178:181], v[194:197], v[48:51]
	v_mfma_f32_16x16x32_bf16 v[60:63], v[160:163], v[202:205], v[60:63]
	v_mfma_f32_16x16x32_bf16 v[80:83], v[178:181], v[202:205], v[80:83]
	v_mfma_f32_16x16x32_bf16 v[96:99], v[160:163], v[210:213], v[96:99]
	v_mfma_f32_16x16x32_bf16 v[104:107], v[178:181], v[210:213], v[104:107]
	v_mfma_f32_16x16x32_bf16 v[20:23], v[174:177], v[190:193], v[20:23]
	v_mfma_f32_16x16x32_bf16 v[28:31], v[182:185], v[190:193], v[28:31]
	v_mfma_f32_16x16x32_bf16 v[36:39], v[174:177], v[198:201], v[36:39]
	v_mfma_f32_16x16x32_bf16 v[48:51], v[182:185], v[198:201], v[48:51]
	v_mfma_f32_16x16x32_bf16 v[60:63], v[174:177], v[206:209], v[60:63]
	v_mfma_f32_16x16x32_bf16 v[80:83], v[182:185], v[206:209], v[80:83]
	v_mfma_f32_16x16x32_bf16 v[96:99], v[174:177], v[214:217], v[96:99]
	v_mfma_f32_16x16x32_bf16 v[104:107], v[182:185], v[214:217], v[104:107]
	s_setprio 0
	s_barrier
; #define PG8_STAGE(bufoff, gbase, voff) do { _Pragma("unroll") for (int _i = 0; _i < 2; ++_i) \
;         __builtin_amdgcn_global_load_lds((const unsigned*)((const char*)(gbase) + (voff)[_i]), (LAS unsigned*)(lds + (bufoff) + ldsw + _i * 8192), 16, 0, 0); } while (0)
; #define PG8_LDA(dst, b, h) do { _Pragma("unroll") for (int m = 0; m < 4; ++m) _Pragma("unroll") for (int k = 0; k < 2; ++k) dst[m][k] = *(const LAS bf16x8*)(lds + PG8_SA(b, h) + aoff + m * 2048 + k * 1024); } while (0)
; #define PG8_MMA(ai, bj, At, Bt) do { __builtin_amdgcn_s_setprio(1); _Pragma("unroll") for (int m = 0; m < 4; ++m) _Pragma("unroll") for (int n = 0; n < 2; ++n) _Pragma("unroll") for (int k = 0; k < 2; ++k) \
;         acc[ai][bj][m][n] = __builtin_amdgcn_mfma_f32_16x16x32_bf16(Bt[n][k], At[m][k], acc[ai][bj][m][n], 0, 0, 0); __builtin_amdgcn_s_setprio(0); } while (0)
; #define PG8_WAIT_V(n) asm volatile("s_waitcnt vmcnt(" #n ")" ::: "memory")
; #define PG8_WAIT_L(n) asm volatile("s_waitcnt lgkmcnt(" #n ")" ::: "memory")
; #define PG8_BAR __builtin_amdgcn_s_barrier()
; #define PG8_SCHED __builtin_amdgcn_sched_barrier(0)
; template <class Epi, class Sched>
; __device__ __forceinline__ void gemm_phase(LAS unsigned char* lds, const Gemm g, const Sched& S, const Epi& E, int wid) {
;     ...
;             PG8_LDA(At, 1, 1); PG8_STAGE(PG8_SB(1, 0), b3, voffB); PG8_STAGE(PG8_SB(1, 1), b3 + hstep, voffB); PG8_STAGE(PG8_SA(1, 0), a3, voffA);
;             PG8_WAIT_V(8); PG8_WAIT_L(0); PG8_BAR; PG8_MMA(1, 0, At, B0); PG8_MMA(1, 1, At, B1); PG8_BAR; PG8_SCHED;
	s_add_i32 s10, s45, s75
	v_lshl_add_u64 v[218:219], v[218:219], 0, s[24:25]
	s_mov_b32 m0, s10
	ds_read_b128 v[186:189], v171 offset:49152
	ds_read_b128 v[190:193], v171 offset:50176
	ds_read_b128 v[194:197], v171 offset:51200
	ds_read_b128 v[198:201], v171 offset:52224
	ds_read_b128 v[202:205], v171 offset:53248
	ds_read_b128 v[206:209], v171 offset:54272
	ds_read_b128 v[210:213], v171 offset:55296
	ds_read_b128 v[214:217], v171 offset:56320
	global_load_lds_dwordx4 v[218:219], off
	s_add_i32 m0, s10, 0x2000
	s_add_u32 s4, s4, 0x40080
	v_lshl_add_u64 v[218:219], v[220:221], 0, s[24:25]
	s_addc_u32 s5, s5, 0
	s_add_i32 s10, s68, s75
	global_load_lds_dwordx4 v[218:219], off
	v_lshl_add_u64 v[218:219], s[4:5], 0, v[138:139]
	s_mov_b32 m0, s10
	s_nop 0
	global_load_lds_dwordx4 v[218:219], off
	v_lshl_add_u64 v[218:219], s[4:5], 0, v[142:143]
	s_add_i32 m0, s10, 0x2000
	s_nop 0
	global_load_lds_dwordx4 v[218:219], off
	v_lshl_add_u64 v[218:219], v[222:223], 0, s[24:25]
	s_mov_b32 m0, s54
	s_nop 0
	global_load_lds_dwordx4 v[218:219], off
	v_lshl_add_u64 v[218:219], v[224:225], 0, s[24:25]
	s_mov_b32 m0, s55
	s_nop 0
	global_load_lds_dwordx4 v[218:219], off
	s_waitcnt vmcnt(8)
	s_waitcnt lgkmcnt(0)
	s_barrier
	s_setprio 1
	s_waitcnt lgkmcnt(0)
	v_mfma_f32_16x16x32_bf16 v[108:111], v[128:131], v[186:189], v[108:111]
	v_mfma_f32_16x16x32_bf16 v[100:103], v[152:155], v[186:189], v[100:103]
	v_mfma_f32_16x16x32_bf16 v[72:75], v[128:131], v[194:197], v[72:75]
	v_mfma_f32_16x16x32_bf16 v[68:71], v[152:155], v[194:197], v[68:71]
	v_mfma_f32_16x16x32_bf16 v[40:43], v[128:131], v[202:205], v[40:43]
	v_mfma_f32_16x16x32_bf16 v[32:35], v[152:155], v[202:205], v[32:35]
	v_mfma_f32_16x16x32_bf16 v[12:15], v[128:131], v[210:213], v[12:15]
	v_mfma_f32_16x16x32_bf16 v[8:11], v[152:155], v[210:213], v[8:11]
	v_mfma_f32_16x16x32_bf16 v[108:111], v[132:135], v[190:193], v[108:111]
	v_mfma_f32_16x16x32_bf16 v[100:103], v[156:159], v[190:193], v[100:103]
	v_mfma_f32_16x16x32_bf16 v[72:75], v[132:135], v[198:201], v[72:75]
	v_mfma_f32_16x16x32_bf16 v[68:71], v[156:159], v[198:201], v[68:71]
	v_mfma_f32_16x16x32_bf16 v[40:43], v[132:135], v[206:209], v[40:43]
	v_mfma_f32_16x16x32_bf16 v[32:35], v[156:159], v[206:209], v[32:35]
	v_mfma_f32_16x16x32_bf16 v[12:15], v[132:135], v[214:217], v[12:15]
	v_mfma_f32_16x16x32_bf16 v[8:11], v[156:159], v[214:217], v[8:11]
	v_mfma_f32_16x16x32_bf16 v[88:91], v[160:163], v[186:189], v[88:91]
	v_mfma_f32_16x16x32_bf16 v[76:79], v[178:181], v[186:189], v[76:79]
	v_mfma_f32_16x16x32_bf16 v[52:55], v[160:163], v[194:197], v[52:55]
	v_mfma_f32_16x16x32_bf16 v[44:47], v[178:181], v[194:197], v[44:47]
	v_mfma_f32_16x16x32_bf16 v[24:27], v[160:163], v[202:205], v[24:27]
	v_mfma_f32_16x16x32_bf16 v[16:19], v[178:181], v[202:205], v[16:19]
	v_mfma_f32_16x16x32_bf16 v[4:7], v[160:163], v[210:213], v[4:7]
	v_mfma_f32_16x16x32_bf16 v[0:3], v[178:181], v[210:213], v[0:3]
	v_mfma_f32_16x16x32_bf16 v[88:91], v[174:177], v[190:193], v[88:91]
	v_mfma_f32_16x16x32_bf16 v[76:79], v[182:185], v[190:193], v[76:79]
	v_mfma_f32_16x16x32_bf16 v[52:55], v[174:177], v[198:201], v[52:55]
	v_mfma_f32_16x16x32_bf16 v[44:47], v[182:185], v[198:201], v[44:47]
	v_mfma_f32_16x16x32_bf16 v[24:27], v[174:177], v[206:209], v[24:27]
	v_mfma_f32_16x16x32_bf16 v[16:19], v[182:185], v[206:209], v[16:19]
	v_mfma_f32_16x16x32_bf16 v[4:7], v[174:177], v[214:217], v[4:7]
	v_mfma_f32_16x16x32_bf16 v[0:3], v[182:185], v[214:217], v[0:3]
	s_setprio 0
	s_barrier
	s_add_i32 s44, s44, 2
	s_add_u32 s6, s6, 0x100
	s_addc_u32 s7, s7, 0
	s_add_u32 s42, s42, 0x100
	s_addc_u32 s43, s43, 0
	s_cmp_gt_u32 s44, 13
	s_cbranch_scc0 .LBB0_2014
	s_and_b64 vcc, exec, s[26:27]
	s_cbranch_vccz .LBB0_2017
	s_barrier

; #define PG8_STAGE(bufoff, gbase, voff) do { _Pragma("unroll") for (int _i = 0; _i < 2; ++_i) \
;         __builtin_amdgcn_global_load_lds((const unsigned*)((const char*)(gbase) + (voff)[_i]), (LAS unsigned*)(lds + (bufoff) + ldsw + _i * 8192), 16, 0, 0); } while (0)
; #define PG8_LDA(dst, b, h) do { _Pragma("unroll") for (int m = 0; m < 4; ++m) _Pragma("unroll") for (int k = 0; k < 2; ++k) dst[m][k] = *(const LAS bf16x8*)(lds + PG8_SA(b, h) + aoff + m * 2048 + k * 1024); } while (0)
; #define PG8_LDB(dst, b, h) do { _Pragma("unroll") for (int n = 0; n < 2; ++n) _Pragma("unroll") for (int k = 0; k < 2; ++k) dst[n][k] = *(const LAS bf16x8*)(lds + PG8_SB(b, h) + boff + n * 2048 + k * 1024); } while (0)
; #define PG8_MMA(ai, bj, At, Bt) do { __builtin_amdgcn_s_setprio(1); _Pragma("unroll") for (int m = 0; m < 4; ++m) _Pragma("unroll") for (int n = 0; n < 2; ++n) _Pragma("unroll") for (int k = 0; k < 2; ++k) \
;         acc[ai][bj][m][n] = __builtin_amdgcn_mfma_f32_16x16x32_bf16(Bt[n][k], At[m][k], acc[ai][bj][m][n], 0, 0, 0); __builtin_amdgcn_s_setprio(0); } while (0)
; #define PG8_WAIT_V(n) asm volatile("s_waitcnt vmcnt(" #n ")" ::: "memory")
; #define PG8_WAIT_L(n) asm volatile("s_waitcnt lgkmcnt(" #n ")" ::: "memory")
; #define PG8_BAR __builtin_amdgcn_s_barrier()
; #define PG8_SCHED __builtin_amdgcn_sched_barrier(0)
; template <class Epi, class Sched>
; __device__ __forceinline__ void gemm_phase(LAS unsigned char* lds, const Gemm g, const Sched& S, const Epi& E, int wid) {
;     ...
;             PG8_LDB(B0, 0, 0); PG8_LDB(B1, 0, 1); PG8_SCHED; PG8_LDA(At, 0, 0); PG8_STAGE(PG8_SA(1, 1), a1 + hstep, voffA);
;             PG8_WAIT_V(8); PG8_WAIT_L(0); PG8_BAR; PG8_MMA(0, 0, At, B0); PG8_MMA(0, 1, At, B1); PG8_BAR; PG8_SCHED;
;             PG8_LDA(At, 0, 1); PG8_STAGE(PG8_SB(0, 0), b2, voffB); PG8_STAGE(PG8_SB(0, 1), b2 + hstep, voffB); PG8_STAGE(PG8_SA(0, 0), a2, voffA);
.LBB0_2203:
	ds_read_b128 v[152:155], v148
	ds_read_b128 v[156:159], v148 offset:1024
	ds_read_b128 v[160:163], v148 offset:2048
	ds_read_b128 v[168:171], v148 offset:3072
	ds_read_b128 v[172:175], v149
	ds_read_b128 v[176:179], v149 offset:1024
	ds_read_b128 v[180:183], v149 offset:2048
	ds_read_b128 v[184:187], v149 offset:3072
	s_add_u32 s4, s28, 0xfffc0080
	s_addc_u32 s5, s29, -1
	s_cmp_eq_u32 s52, 12
	s_cselect_b32 s31, s21, s5
	s_cselect_b32 s30, s27, s4
	s_cselect_b32 s5, s19, s51
	s_cselect_b32 s4, s49, s50
	v_lshl_add_u64 v[164:165], s[28:29], 0, v[138:139]
	s_add_i32 m0, s35, 0xc000
	ds_read_b128 v[188:191], v150
	ds_read_b128 v[192:195], v150 offset:1024
	ds_read_b128 v[196:199], v150 offset:2048
	ds_read_b128 v[200:203], v150 offset:3072
	ds_read_b128 v[204:207], v150 offset:4096
	ds_read_b128 v[208:211], v150 offset:5120
	ds_read_b128 v[212:215], v150 offset:6144
	ds_read_b128 v[216:219], v150 offset:7168
	global_load_lds_dwordx4 v[164:165], off
	v_lshl_add_u64 v[164:165], s[28:29], 0, v[140:141]
	s_add_i32 m0, s35, 0xe000
	s_nop 0
	global_load_lds_dwordx4 v[164:165], off
	s_waitcnt vmcnt(8)
	s_waitcnt lgkmcnt(0)
	s_barrier
	s_setprio 1
	s_waitcnt lgkmcnt(0)
	v_mfma_f32_16x16x32_bf16 v[124:127], v[152:155], v[188:191], v[124:127]
	v_mfma_f32_16x16x32_bf16 v[116:119], v[160:163], v[188:191], v[116:119]
	v_mfma_f32_16x16x32_bf16 v[108:111], v[152:155], v[196:199], v[108:111]
	v_mfma_f32_16x16x32_bf16 v[100:103], v[160:163], v[196:199], v[100:103]
	v_mfma_f32_16x16x32_bf16 v[92:95], v[152:155], v[204:207], v[92:95]
	v_mfma_f32_16x16x32_bf16 v[84:87], v[160:163], v[204:207], v[84:87]
	v_mfma_f32_16x16x32_bf16 v[76:79], v[152:155], v[212:215], v[76:79]
	v_mfma_f32_16x16x32_bf16 v[68:71], v[160:163], v[212:215], v[68:71]
	v_mfma_f32_16x16x32_bf16 v[124:127], v[156:159], v[192:195], v[124:127]
	v_mfma_f32_16x16x32_bf16 v[116:119], v[168:171], v[192:195], v[116:119]
	v_mfma_f32_16x16x32_bf16 v[108:111], v[156:159], v[200:203], v[108:111]
	v_mfma_f32_16x16x32_bf16 v[100:103], v[168:171], v[200:203], v[100:103]
	v_mfma_f32_16x16x32_bf16 v[92:95], v[156:159], v[208:211], v[92:95]
	v_mfma_f32_16x16x32_bf16 v[84:87], v[168:171], v[208:211], v[84:87]
	v_mfma_f32_16x16x32_bf16 v[76:79], v[156:159], v[216:219], v[76:79]
	v_mfma_f32_16x16x32_bf16 v[68:71], v[168:171], v[216:219], v[68:71]
	v_mfma_f32_16x16x32_bf16 v[120:123], v[172:175], v[188:191], v[120:123]
	v_mfma_f32_16x16x32_bf16 v[112:115], v[180:183], v[188:191], v[112:115]
	v_mfma_f32_16x16x32_bf16 v[104:107], v[172:175], v[196:199], v[104:107]
	v_mfma_f32_16x16x32_bf16 v[96:99], v[180:183], v[196:199], v[96:99]
	v_mfma_f32_16x16x32_bf16 v[88:91], v[172:175], v[204:207], v[88:91]
	v_mfma_f32_16x16x32_bf16 v[80:83], v[180:183], v[204:207], v[80:83]
	v_mfma_f32_16x16x32_bf16 v[72:75], v[172:175], v[212:215], v[72:75]
	v_mfma_f32_16x16x32_bf16 v[64:67], v[180:183], v[212:215], v[64:67]
	v_mfma_f32_16x16x32_bf16 v[120:123], v[176:179], v[192:195], v[120:123]
	v_mfma_f32_16x16x32_bf16 v[112:115], v[184:187], v[192:195], v[112:115]
	v_mfma_f32_16x16x32_bf16 v[104:107], v[176:179], v[200:203], v[104:107]
	v_mfma_f32_16x16x32_bf16 v[96:99], v[184:187], v[200:203], v[96:99]
	v_mfma_f32_16x16x32_bf16 v[88:91], v[176:179], v[208:211], v[88:91]
	v_mfma_f32_16x16x32_bf16 v[80:83], v[184:187], v[208:211], v[80:83]
	v_mfma_f32_16x16x32_bf16 v[72:75], v[176:179], v[216:219], v[72:75]
	v_mfma_f32_16x16x32_bf16 v[64:67], v[184:187], v[216:219], v[64:67]
	s_setprio 0
	s_barrier
	s_add_i32 s53, s44, s75
	v_lshl_add_u64 v[164:165], s[4:5], 0, v[130:131]
	s_mov_b32 m0, s53
	ds_read_b128 v[188:191], v150 offset:16384
	ds_read_b128 v[192:195], v150 offset:17408
	ds_read_b128 v[196:199], v150 offset:18432
	ds_read_b128 v[200:203], v150 offset:19456
	ds_read_b128 v[204:207], v150 offset:20480
	ds_read_b128 v[208:211], v150 offset:21504
	ds_read_b128 v[212:215], v150 offset:22528
	ds_read_b128 v[216:219], v150 offset:23552
	global_load_lds_dwordx4 v[164:165], off
	s_add_i32 m0, s53, 0x2000
	s_add_u32 s54, s4, 0x40000
	v_lshl_add_u64 v[220:221], s[4:5], 0, v[134:135]
	s_addc_u32 s55, s5, 0
	s_add_i32 s53, s45, s75
	global_load_lds_dwordx4 v[220:221], off
	v_lshl_add_u64 v[222:223], s[54:55], 0, v[130:131]
	s_mov_b32 m0, s53
	v_lshl_add_u64 v[224:225], s[30:31], 0, v[132:133]
	global_load_lds_dwordx4 v[222:223], off
	v_lshl_add_u64 v[222:223], s[54:55], 0, v[134:135]
	s_add_i32 m0, s53, 0x2000
	s_nop 0
	global_load_lds_dwordx4 v[222:223], off
	v_lshl_add_u64 v[222:223], s[30:31], 0, v[128:129]
	s_mov_b32 m0, s35
	s_nop 0
	global_load_lds_dwordx4 v[222:223], off
	s_mov_b32 m0, s36
	s_nop 0
	global_load_lds_dwordx4 v[224:225], off
	s_waitcnt vmcnt(8)
	s_waitcnt lgkmcnt(0)
	s_barrier
; #define PG8_STAGE(bufoff, gbase, voff) do { _Pragma("unroll") for (int _i = 0; _i < 2; ++_i) \
;         __builtin_amdgcn_global_load_lds((const unsigned*)((const char*)(gbase) + (voff)[_i]), (LAS unsigned*)(lds + (bufoff) + ldsw + _i * 8192), 16, 0, 0); } while (0)
; #define PG8_LDA(dst, b, h) do { _Pragma("unroll") for (int m = 0; m < 4; ++m) _Pragma("unroll") for (int k = 0; k < 2; ++k) dst[m][k] = *(const LAS bf16x8*)(lds + PG8_SA(b, h) + aoff + m * 2048 + k * 1024); } while (0)
; #define PG8_LDB(dst, b, h) do { _Pragma("unroll") for (int n = 0; n < 2; ++n) _Pragma("unroll") for (int k = 0; k < 2; ++k) dst[n][k] = *(const LAS bf16x8*)(lds + PG8_SB(b, h) + boff + n * 2048 + k * 1024); } while (0)
; #define PG8_MMA(ai, bj, At, Bt) do { __builtin_amdgcn_s_setprio(1); _Pragma("unroll") for (int m = 0; m < 4; ++m) _Pragma("unroll") for (int n = 0; n < 2; ++n) _Pragma("unroll") for (int k = 0; k < 2; ++k) \
;         acc[ai][bj][m][n] = __builtin_amdgcn_mfma_f32_16x16x32_bf16(Bt[n][k], At[m][k], acc[ai][bj][m][n], 0, 0, 0); __builtin_amdgcn_s_setprio(0); } while (0)
; #define PG8_WAIT_V(n) asm volatile("s_waitcnt vmcnt(" #n ")" ::: "memory")
; #define PG8_WAIT_L(n) asm volatile("s_waitcnt lgkmcnt(" #n ")" ::: "memory")
; #define PG8_BAR __builtin_amdgcn_s_barrier()
; #define PG8_SCHED __builtin_amdgcn_sched_barrier(0)
; template <class Epi, class Sched>
; __device__ __forceinline__ void gemm_phase(LAS unsigned char* lds, const Gemm g, const Sched& S, const Epi& E, int wid) {
;     ...
;             PG8_WAIT_V(8); PG8_WAIT_L(0); PG8_BAR; PG8_MMA(1, 0, At, B0); PG8_MMA(1, 1, At, B1); PG8_BAR; PG8_SCHED;
;             PG8_LDB(B0, 1, 0); PG8_LDB(B1, 1, 1); PG8_SCHED; PG8_LDA(At, 1, 0); PG8_STAGE(PG8_SA(0, 1), a2 + hstep, voffA);
;             PG8_WAIT_V(8); PG8_WAIT_L(0); PG8_BAR; PG8_MMA(0, 0, At, B0); PG8_MMA(0, 1, At, B1); PG8_BAR; PG8_SCHED;
	s_setprio 1
	s_waitcnt lgkmcnt(0)
	v_mfma_f32_16x16x32_bf16 v[60:63], v[152:155], v[188:191], v[60:63]
	v_mfma_f32_16x16x32_bf16 v[52:55], v[160:163], v[188:191], v[52:55]
	v_mfma_f32_16x16x32_bf16 v[44:47], v[152:155], v[196:199], v[44:47]
	v_mfma_f32_16x16x32_bf16 v[36:39], v[160:163], v[196:199], v[36:39]
	v_mfma_f32_16x16x32_bf16 v[28:31], v[152:155], v[204:207], v[28:31]
	v_mfma_f32_16x16x32_bf16 v[20:23], v[160:163], v[204:207], v[20:23]
	v_mfma_f32_16x16x32_bf16 v[12:15], v[152:155], v[212:215], v[12:15]
	v_mfma_f32_16x16x32_bf16 v[4:7], v[160:163], v[212:215], v[4:7]
	v_mfma_f32_16x16x32_bf16 v[60:63], v[156:159], v[192:195], v[60:63]
	v_mfma_f32_16x16x32_bf16 v[52:55], v[168:171], v[192:195], v[52:55]
	v_mfma_f32_16x16x32_bf16 v[44:47], v[156:159], v[200:203], v[44:47]
	v_mfma_f32_16x16x32_bf16 v[36:39], v[168:171], v[200:203], v[36:39]
	v_mfma_f32_16x16x32_bf16 v[28:31], v[156:159], v[208:211], v[28:31]
	v_mfma_f32_16x16x32_bf16 v[20:23], v[168:171], v[208:211], v[20:23]
	v_mfma_f32_16x16x32_bf16 v[12:15], v[156:159], v[216:219], v[12:15]
	v_mfma_f32_16x16x32_bf16 v[4:7], v[168:171], v[216:219], v[4:7]
	v_mfma_f32_16x16x32_bf16 v[56:59], v[172:175], v[188:191], v[56:59]
	v_mfma_f32_16x16x32_bf16 v[48:51], v[180:183], v[188:191], v[48:51]
	v_mfma_f32_16x16x32_bf16 v[40:43], v[172:175], v[196:199], v[40:43]
	v_mfma_f32_16x16x32_bf16 v[32:35], v[180:183], v[196:199], v[32:35]
	v_mfma_f32_16x16x32_bf16 v[24:27], v[172:175], v[204:207], v[24:27]
	v_mfma_f32_16x16x32_bf16 v[16:19], v[180:183], v[204:207], v[16:19]
	v_mfma_f32_16x16x32_bf16 v[8:11], v[172:175], v[212:215], v[8:11]
	v_mfma_f32_16x16x32_bf16 v[0:3], v[180:183], v[212:215], v[0:3]
	v_mfma_f32_16x16x32_bf16 v[56:59], v[176:179], v[192:195], v[56:59]
	v_mfma_f32_16x16x32_bf16 v[48:51], v[184:187], v[192:195], v[48:51]
	v_mfma_f32_16x16x32_bf16 v[40:43], v[176:179], v[200:203], v[40:43]
	v_mfma_f32_16x16x32_bf16 v[32:35], v[184:187], v[200:203], v[32:35]
	v_mfma_f32_16x16x32_bf16 v[24:27], v[176:179], v[208:211], v[24:27]
	v_mfma_f32_16x16x32_bf16 v[16:19], v[184:187], v[208:211], v[16:19]
	v_mfma_f32_16x16x32_bf16 v[8:11], v[176:179], v[216:219], v[8:11]
	v_mfma_f32_16x16x32_bf16 v[0:3], v[184:187], v[216:219], v[0:3]
	s_setprio 0
	s_barrier
	s_add_i32 s53, 0, 0x18000
	v_add_u32_e32 v151, s53, v147
	s_add_i32 s54, 0, 0x1c000
	ds_read_b128 v[152:155], v151
	ds_read_b128 v[156:159], v151 offset:1024
	ds_read_b128 v[160:163], v151 offset:2048
	ds_read_b128 v[168:171], v151 offset:3072
	v_add_u32_e32 v151, s54, v147
	ds_read_b128 v[172:175], v151
	ds_read_b128 v[176:179], v151 offset:1024
	ds_read_b128 v[180:183], v151 offset:2048
	ds_read_b128 v[184:187], v151 offset:3072
	s_add_u32 s30, s30, 0x40000
	s_addc_u32 s31, s31, 0
	s_mov_b32 m0, s37
	v_lshl_add_u64 v[226:227], s[30:31], 0, v[128:129]
	ds_read_b128 v[188:191], v150 offset:32768
	ds_read_b128 v[192:195], v150 offset:33792
	ds_read_b128 v[196:199], v150 offset:34816
	ds_read_b128 v[200:203], v150 offset:35840
	ds_read_b128 v[204:207], v150 offset:36864
	ds_read_b128 v[208:211], v150 offset:37888
	ds_read_b128 v[212:215], v150 offset:38912
	ds_read_b128 v[216:219], v150 offset:39936
	global_load_lds_dwordx4 v[226:227], off
	v_lshl_add_u64 v[226:227], s[30:31], 0, v[132:133]
	s_mov_b32 m0, s38
	s_nop 0
	global_load_lds_dwordx4 v[226:227], off
	s_waitcnt vmcnt(8)
	s_waitcnt lgkmcnt(0)
	s_barrier
	s_setprio 1
	s_waitcnt lgkmcnt(0)
	v_mfma_f32_16x16x32_bf16 v[124:127], v[152:155], v[188:191], v[124:127]
	v_mfma_f32_16x16x32_bf16 v[116:119], v[160:163], v[188:191], v[116:119]
	v_mfma_f32_16x16x32_bf16 v[108:111], v[152:155], v[196:199], v[108:111]
	v_mfma_f32_16x16x32_bf16 v[100:103], v[160:163], v[196:199], v[100:103]
	v_mfma_f32_16x16x32_bf16 v[92:95], v[152:155], v[204:207], v[92:95]
	v_mfma_f32_16x16x32_bf16 v[84:87], v[160:163], v[204:207], v[84:87]
	v_mfma_f32_16x16x32_bf16 v[76:79], v[152:155], v[212:215], v[76:79]
	v_mfma_f32_16x16x32_bf16 v[68:71], v[160:163], v[212:215], v[68:71]
	v_mfma_f32_16x16x32_bf16 v[124:127], v[156:159], v[192:195], v[124:127]
	v_mfma_f32_16x16x32_bf16 v[116:119], v[168:171], v[192:195], v[116:119]
	v_mfma_f32_16x16x32_bf16 v[108:111], v[156:159], v[200:203], v[108:111]
	v_mfma_f32_16x16x32_bf16 v[100:103], v[168:171], v[200:203], v[100:103]
	v_mfma_f32_16x16x32_bf16 v[92:95], v[156:159], v[208:211], v[92:95]
	v_mfma_f32_16x16x32_bf16 v[84:87], v[168:171], v[208:211], v[84:87]
	v_mfma_f32_16x16x32_bf16 v[76:79], v[156:159], v[216:219], v[76:79]
	v_mfma_f32_16x16x32_bf16 v[68:71], v[168:171], v[216:219], v[68:71]
	v_mfma_f32_16x16x32_bf16 v[120:123], v[172:175], v[188:191], v[120:123]
	v_mfma_f32_16x16x32_bf16 v[112:115], v[180:183], v[188:191], v[112:115]
	v_mfma_f32_16x16x32_bf16 v[104:107], v[172:175], v[196:199], v[104:107]
	v_mfma_f32_16x16x32_bf16 v[96:99], v[180:183], v[196:199], v[96:99]
	v_mfma_f32_16x16x32_bf16 v[88:91], v[172:175], v[204:207], v[88:91]
	v_mfma_f32_16x16x32_bf16 v[80:83], v[180:183], v[204:207], v[80:83]
	v_mfma_f32_16x16x32_bf16 v[72:75], v[172:175], v[212:215], v[72:75]
	v_mfma_f32_16x16x32_bf16 v[64:67], v[180:183], v[212:215], v[64:67]
	v_mfma_f32_16x16x32_bf16 v[120:123], v[176:179], v[192:195], v[120:123]
	v_mfma_f32_16x16x32_bf16 v[112:115], v[184:187], v[192:195], v[112:115]
	v_mfma_f32_16x16x32_bf16 v[104:107], v[176:179], v[200:203], v[104:107]
	v_mfma_f32_16x16x32_bf16 v[96:99], v[184:187], v[200:203], v[96:99]
	v_mfma_f32_16x16x32_bf16 v[88:91], v[176:179], v[208:211], v[88:91]
	v_mfma_f32_16x16x32_bf16 v[80:83], v[184:187], v[208:211], v[80:83]
	v_mfma_f32_16x16x32_bf16 v[72:75], v[176:179], v[216:219], v[72:75]
	v_mfma_f32_16x16x32_bf16 v[64:67], v[184:187], v[216:219], v[64:67]
	s_setprio 0
	s_barrier
; #define PG8_STAGE(bufoff, gbase, voff) do { _Pragma("unroll") for (int _i = 0; _i < 2; ++_i) \
;         __builtin_amdgcn_global_load_lds((const unsigned*)((const char*)(gbase) + (voff)[_i]), (LAS unsigned*)(lds + (bufoff) + ldsw + _i * 8192), 16, 0, 0); } while (0)
; #define PG8_LDA(dst, b, h) do { _Pragma("unroll") for (int m = 0; m < 4; ++m) _Pragma("unroll") for (int k = 0; k < 2; ++k) dst[m][k] = *(const LAS bf16x8*)(lds + PG8_SA(b, h) + aoff + m * 2048 + k * 1024); } while (0)
; #define PG8_MMA(ai, bj, At, Bt) do { __builtin_amdgcn_s_setprio(1); _Pragma("unroll") for (int m = 0; m < 4; ++m) _Pragma("unroll") for (int n = 0; n < 2; ++n) _Pragma("unroll") for (int k = 0; k < 2; ++k) \
;         acc[ai][bj][m][n] = __builtin_amdgcn_mfma_f32_16x16x32_bf16(Bt[n][k], At[m][k], acc[ai][bj][m][n], 0, 0, 0); __builtin_amdgcn_s_setprio(0); } while (0)
; #define PG8_WAIT_V(n) asm volatile("s_waitcnt vmcnt(" #n ")" ::: "memory")
; #define PG8_WAIT_L(n) asm volatile("s_waitcnt lgkmcnt(" #n ")" ::: "memory")
; #define PG8_BAR __builtin_amdgcn_s_barrier()
; #define PG8_SCHED __builtin_amdgcn_sched_barrier(0)
; template <class Epi, class Sched>
; __device__ __forceinline__ void gemm_phase(LAS unsigned char* lds, const Gemm g, const Sched& S, const Epi& E, int wid) {
;     ...
;             PG8_LDA(At, 1, 1); PG8_STAGE(PG8_SB(1, 0), b3, voffB); PG8_STAGE(PG8_SB(1, 1), b3 + hstep, voffB); PG8_STAGE(PG8_SA(1, 0), a3, voffA);
;             PG8_WAIT_V(8); PG8_WAIT_L(0); PG8_BAR; PG8_MMA(1, 0, At, B0); PG8_MMA(1, 1, At, B1); PG8_BAR; PG8_SCHED;
	s_add_i32 s30, s53, s75
	v_lshl_add_u64 v[164:165], v[164:165], 0, s[14:15]
	s_mov_b32 m0, s30
	ds_read_b128 v[188:191], v150 offset:49152
	ds_read_b128 v[192:195], v150 offset:50176
	ds_read_b128 v[196:199], v150 offset:51200
	ds_read_b128 v[200:203], v150 offset:52224
	ds_read_b128 v[204:207], v150 offset:53248
	ds_read_b128 v[208:211], v150 offset:54272
	ds_read_b128 v[212:215], v150 offset:55296
	ds_read_b128 v[216:219], v150 offset:56320
	global_load_lds_dwordx4 v[164:165], off
	s_add_i32 m0, s30, 0x2000
	s_add_u32 s4, s4, 0x40080
	v_lshl_add_u64 v[164:165], v[220:221], 0, s[14:15]
	s_addc_u32 s5, s5, 0
	s_add_i32 s30, s54, s75
	global_load_lds_dwordx4 v[164:165], off
	v_lshl_add_u64 v[164:165], s[4:5], 0, v[130:131]
	s_mov_b32 m0, s30
	s_nop 0
	global_load_lds_dwordx4 v[164:165], off
	v_lshl_add_u64 v[164:165], s[4:5], 0, v[134:135]
	s_add_i32 m0, s30, 0x2000
	s_nop 0
	global_load_lds_dwordx4 v[164:165], off
	v_lshl_add_u64 v[164:165], v[222:223], 0, s[14:15]
	s_mov_b32 m0, s39
	s_nop 0
	global_load_lds_dwordx4 v[164:165], off
	v_lshl_add_u64 v[164:165], v[224:225], 0, s[14:15]
	s_mov_b32 m0, s40
	s_nop 0
	global_load_lds_dwordx4 v[164:165], off
	s_waitcnt vmcnt(8)
	s_waitcnt lgkmcnt(0)
	s_barrier
	s_setprio 1
	s_waitcnt lgkmcnt(0)
	v_mfma_f32_16x16x32_bf16 v[60:63], v[152:155], v[188:191], v[60:63]
	v_mfma_f32_16x16x32_bf16 v[52:55], v[160:163], v[188:191], v[52:55]
	v_mfma_f32_16x16x32_bf16 v[44:47], v[152:155], v[196:199], v[44:47]
	v_mfma_f32_16x16x32_bf16 v[36:39], v[160:163], v[196:199], v[36:39]
	v_mfma_f32_16x16x32_bf16 v[28:31], v[152:155], v[204:207], v[28:31]
	v_mfma_f32_16x16x32_bf16 v[20:23], v[160:163], v[204:207], v[20:23]
	v_mfma_f32_16x16x32_bf16 v[12:15], v[152:155], v[212:215], v[12:15]
	v_mfma_f32_16x16x32_bf16 v[4:7], v[160:163], v[212:215], v[4:7]
	v_mfma_f32_16x16x32_bf16 v[60:63], v[156:159], v[192:195], v[60:63]
	v_mfma_f32_16x16x32_bf16 v[52:55], v[168:171], v[192:195], v[52:55]
	v_mfma_f32_16x16x32_bf16 v[44:47], v[156:159], v[200:203], v[44:47]
	v_mfma_f32_16x16x32_bf16 v[36:39], v[168:171], v[200:203], v[36:39]
	v_mfma_f32_16x16x32_bf16 v[28:31], v[156:159], v[208:211], v[28:31]
	v_mfma_f32_16x16x32_bf16 v[20:23], v[168:171], v[208:211], v[20:23]
	v_mfma_f32_16x16x32_bf16 v[12:15], v[156:159], v[216:219], v[12:15]
	v_mfma_f32_16x16x32_bf16 v[4:7], v[168:171], v[216:219], v[4:7]
	v_mfma_f32_16x16x32_bf16 v[56:59], v[172:175], v[188:191], v[56:59]
	v_mfma_f32_16x16x32_bf16 v[48:51], v[180:183], v[188:191], v[48:51]
	v_mfma_f32_16x16x32_bf16 v[40:43], v[172:175], v[196:199], v[40:43]
	v_mfma_f32_16x16x32_bf16 v[32:35], v[180:183], v[196:199], v[32:35]
	v_mfma_f32_16x16x32_bf16 v[24:27], v[172:175], v[204:207], v[24:27]
	v_mfma_f32_16x16x32_bf16 v[16:19], v[180:183], v[204:207], v[16:19]
	v_mfma_f32_16x16x32_bf16 v[8:11], v[172:175], v[212:215], v[8:11]
	v_mfma_f32_16x16x32_bf16 v[0:3], v[180:183], v[212:215], v[0:3]
	v_mfma_f32_16x16x32_bf16 v[56:59], v[176:179], v[192:195], v[56:59]
	v_mfma_f32_16x16x32_bf16 v[48:51], v[184:187], v[192:195], v[48:51]
	v_mfma_f32_16x16x32_bf16 v[40:43], v[176:179], v[200:203], v[40:43]
	v_mfma_f32_16x16x32_bf16 v[32:35], v[184:187], v[200:203], v[32:35]
	v_mfma_f32_16x16x32_bf16 v[24:27], v[176:179], v[208:211], v[24:27]
	v_mfma_f32_16x16x32_bf16 v[16:19], v[184:187], v[208:211], v[16:19]
	v_mfma_f32_16x16x32_bf16 v[8:11], v[176:179], v[216:219], v[8:11]
	v_mfma_f32_16x16x32_bf16 v[0:3], v[184:187], v[216:219], v[0:3]
	s_setprio 0
	s_barrier
	s_add_i32 s52, s52, 2
	s_add_u32 s28, s28, 0x100
	s_addc_u32 s29, s29, 0
	s_add_u32 s50, s50, 0x100
	s_addc_u32 s51, s51, 0
	s_cmp_gt_u32 s52, 13
	s_cbranch_scc0 .LBB0_2203
	s_and_b64 vcc, exec, s[16:17]
	s_cbranch_vccz .LBB0_2206
	s_barrier

; #define PG8_STAGE(bufoff, gbase, voff) do { _Pragma("unroll") for (int _i = 0; _i < 2; ++_i) \
;         __builtin_amdgcn_global_load_lds((const unsigned*)((const char*)(gbase) + (voff)[_i]), (LAS unsigned*)(lds + (bufoff) + ldsw + _i * 8192), 16, 0, 0); } while (0)
; #define PG8_LDA(dst, b, h) do { _Pragma("unroll") for (int m = 0; m < 4; ++m) _Pragma("unroll") for (int k = 0; k < 2; ++k) dst[m][k] = *(const LAS bf16x8*)(lds + PG8_SA(b, h) + aoff + m * 2048 + k * 1024); } while (0)
; #define PG8_LDB(dst, b, h) do { _Pragma("unroll") for (int n = 0; n < 2; ++n) _Pragma("unroll") for (int k = 0; k < 2; ++k) dst[n][k] = *(const LAS bf16x8*)(lds + PG8_SB(b, h) + boff + n * 2048 + k * 1024); } while (0)
; #define PG8_MMA(ai, bj, At, Bt) do { __builtin_amdgcn_s_setprio(1); _Pragma("unroll") for (int m = 0; m < 4; ++m) _Pragma("unroll") for (int n = 0; n < 2; ++n) _Pragma("unroll") for (int k = 0; k < 2; ++k) \
;         acc[ai][bj][m][n] = __builtin_amdgcn_mfma_f32_16x16x32_bf16(Bt[n][k], At[m][k], acc[ai][bj][m][n], 0, 0, 0); __builtin_amdgcn_s_setprio(0); } while (0)
; #define PG8_WAIT_V(n) asm volatile("s_waitcnt vmcnt(" #n ")" ::: "memory")
; #define PG8_WAIT_L(n) asm volatile("s_waitcnt lgkmcnt(" #n ")" ::: "memory")
; #define PG8_BAR __builtin_amdgcn_s_barrier()
; #define PG8_SCHED __builtin_amdgcn_sched_barrier(0)
; template <class Epi, class Sched>
; __device__ __forceinline__ void gemm_phase(LAS unsigned char* lds, const Gemm g, const Sched& S, const Epi& E, int wid) {
;     ...
;             PG8_LDB(B0, 0, 0); PG8_LDB(B1, 0, 1); PG8_SCHED; PG8_LDA(At, 0, 0); PG8_STAGE(PG8_SA(1, 1), a1 + hstep, voffA);
;             PG8_WAIT_V(8); PG8_WAIT_L(0); PG8_BAR; PG8_MMA(0, 0, At, B0); PG8_MMA(0, 1, At, B1); PG8_BAR; PG8_SCHED;
;             PG8_LDA(At, 0, 1); PG8_STAGE(PG8_SB(0, 0), b2, voffB); PG8_STAGE(PG8_SB(0, 1), b2 + hstep, voffB); PG8_STAGE(PG8_SA(0, 0), a2, voffA);
.LBB0_2323:
	ds_read_b128 v[144:147], v163
	ds_read_b128 v[148:151], v163 offset:1024
	ds_read_b128 v[152:155], v163 offset:2048
	ds_read_b128 v[156:159], v163 offset:3072
	ds_read_b128 v[170:173], v164
	ds_read_b128 v[174:177], v164 offset:1024
	ds_read_b128 v[178:181], v164 offset:2048
	ds_read_b128 v[182:185], v164 offset:3072
	s_add_u32 s4, s36, 0x100
	s_addc_u32 s5, s37, 0
	s_cmp_eq_u32 s64, 40
	s_cselect_b32 s39, s27, s5
	s_cselect_b32 s38, s26, s4
	s_cselect_b32 s11, s29, s35
	s_cselect_b32 s10, s28, s31
	v_lshl_add_u64 v[218:219], s[36:37], 0, v[136:137]
	s_add_i32 m0, s41, 0xc000
	ds_read_b128 v[186:189], v165
	ds_read_b128 v[190:193], v165 offset:1024
	ds_read_b128 v[194:197], v165 offset:2048
	ds_read_b128 v[198:201], v165 offset:3072
	ds_read_b128 v[202:205], v165 offset:4096
	ds_read_b128 v[206:209], v165 offset:5120
	ds_read_b128 v[210:213], v165 offset:6144
	ds_read_b128 v[214:217], v165 offset:7168
	global_load_lds_dwordx4 v[218:219], off
	v_lshl_add_u64 v[218:219], s[36:37], 0, v[138:139]
	s_add_i32 m0, s41, 0xe000
	s_nop 0
	global_load_lds_dwordx4 v[218:219], off
	s_waitcnt vmcnt(8)
	s_waitcnt lgkmcnt(0)
	s_barrier
	s_setprio 1
	s_waitcnt lgkmcnt(0)
	v_mfma_f32_16x16x32_bf16 v[124:127], v[144:147], v[186:189], v[124:127]
	v_mfma_f32_16x16x32_bf16 v[120:123], v[152:155], v[186:189], v[120:123]
	v_mfma_f32_16x16x32_bf16 v[108:111], v[144:147], v[194:197], v[108:111]
	v_mfma_f32_16x16x32_bf16 v[104:107], v[152:155], v[194:197], v[104:107]
	v_mfma_f32_16x16x32_bf16 v[92:95], v[144:147], v[202:205], v[92:95]
	v_mfma_f32_16x16x32_bf16 v[88:91], v[152:155], v[202:205], v[88:91]
	v_mfma_f32_16x16x32_bf16 v[76:79], v[144:147], v[210:213], v[76:79]
	v_mfma_f32_16x16x32_bf16 v[72:75], v[152:155], v[210:213], v[72:75]
	v_mfma_f32_16x16x32_bf16 v[124:127], v[148:151], v[190:193], v[124:127]
	v_mfma_f32_16x16x32_bf16 v[120:123], v[156:159], v[190:193], v[120:123]
	v_mfma_f32_16x16x32_bf16 v[108:111], v[148:151], v[198:201], v[108:111]
	v_mfma_f32_16x16x32_bf16 v[104:107], v[156:159], v[198:201], v[104:107]
	v_mfma_f32_16x16x32_bf16 v[92:95], v[148:151], v[206:209], v[92:95]
	v_mfma_f32_16x16x32_bf16 v[88:91], v[156:159], v[206:209], v[88:91]
	v_mfma_f32_16x16x32_bf16 v[76:79], v[148:151], v[214:217], v[76:79]
	v_mfma_f32_16x16x32_bf16 v[72:75], v[156:159], v[214:217], v[72:75]
	v_mfma_f32_16x16x32_bf16 v[116:119], v[170:173], v[186:189], v[116:119]
	v_mfma_f32_16x16x32_bf16 v[112:115], v[178:181], v[186:189], v[112:115]
	v_mfma_f32_16x16x32_bf16 v[100:103], v[170:173], v[194:197], v[100:103]
	v_mfma_f32_16x16x32_bf16 v[96:99], v[178:181], v[194:197], v[96:99]
	v_mfma_f32_16x16x32_bf16 v[84:87], v[170:173], v[202:205], v[84:87]
	v_mfma_f32_16x16x32_bf16 v[80:83], v[178:181], v[202:205], v[80:83]
	v_mfma_f32_16x16x32_bf16 v[68:71], v[170:173], v[210:213], v[68:71]
	v_mfma_f32_16x16x32_bf16 v[64:67], v[178:181], v[210:213], v[64:67]
	v_mfma_f32_16x16x32_bf16 v[116:119], v[174:177], v[190:193], v[116:119]
	v_mfma_f32_16x16x32_bf16 v[112:115], v[182:185], v[190:193], v[112:115]
	v_mfma_f32_16x16x32_bf16 v[100:103], v[174:177], v[198:201], v[100:103]
	v_mfma_f32_16x16x32_bf16 v[96:99], v[182:185], v[198:201], v[96:99]
	v_mfma_f32_16x16x32_bf16 v[84:87], v[174:177], v[206:209], v[84:87]
	v_mfma_f32_16x16x32_bf16 v[80:83], v[182:185], v[206:209], v[80:83]
	v_mfma_f32_16x16x32_bf16 v[68:71], v[174:177], v[214:217], v[68:71]
	v_mfma_f32_16x16x32_bf16 v[64:67], v[182:185], v[214:217], v[64:67]
	s_setprio 0
	s_barrier
	s_add_i32 s36, s56, s75
	v_lshl_add_u64 v[218:219], s[10:11], 0, v[130:131]
	s_mov_b32 m0, s36
	ds_read_b128 v[186:189], v165 offset:16384
	ds_read_b128 v[190:193], v165 offset:17408
	ds_read_b128 v[194:197], v165 offset:18432
	ds_read_b128 v[198:201], v165 offset:19456
	ds_read_b128 v[202:205], v165 offset:20480
	ds_read_b128 v[206:209], v165 offset:21504
	ds_read_b128 v[210:213], v165 offset:22528
	ds_read_b128 v[214:217], v165 offset:23552
	global_load_lds_dwordx4 v[218:219], off
	s_add_i32 m0, s36, 0x2000
	s_add_u32 s36, s10, 0xb0000
	v_lshl_add_u64 v[220:221], s[10:11], 0, v[134:135]
	s_addc_u32 s37, s11, 0
	s_add_i32 s65, s57, s75
	global_load_lds_dwordx4 v[220:221], off
	v_lshl_add_u64 v[222:223], s[36:37], 0, v[130:131]
	s_mov_b32 m0, s65
	v_lshl_add_u64 v[224:225], s[38:39], 0, v[132:133]
	global_load_lds_dwordx4 v[222:223], off
	v_lshl_add_u64 v[222:223], s[36:37], 0, v[134:135]
	s_add_i32 m0, s65, 0x2000
	s_nop 0
	global_load_lds_dwordx4 v[222:223], off
	v_lshl_add_u64 v[222:223], s[38:39], 0, v[128:129]
	s_mov_b32 m0, s41
	s_nop 0
	global_load_lds_dwordx4 v[222:223], off
	s_mov_b32 m0, s42
	s_nop 0
	global_load_lds_dwordx4 v[224:225], off
	s_waitcnt vmcnt(8)
	s_waitcnt lgkmcnt(0)
	s_barrier
; #define PG8_STAGE(bufoff, gbase, voff) do { _Pragma("unroll") for (int _i = 0; _i < 2; ++_i) \
;         __builtin_amdgcn_global_load_lds((const unsigned*)((const char*)(gbase) + (voff)[_i]), (LAS unsigned*)(lds + (bufoff) + ldsw + _i * 8192), 16, 0, 0); } while (0)
; #define PG8_LDA(dst, b, h) do { _Pragma("unroll") for (int m = 0; m < 4; ++m) _Pragma("unroll") for (int k = 0; k < 2; ++k) dst[m][k] = *(const LAS bf16x8*)(lds + PG8_SA(b, h) + aoff + m * 2048 + k * 1024); } while (0)
; #define PG8_LDB(dst, b, h) do { _Pragma("unroll") for (int n = 0; n < 2; ++n) _Pragma("unroll") for (int k = 0; k < 2; ++k) dst[n][k] = *(const LAS bf16x8*)(lds + PG8_SB(b, h) + boff + n * 2048 + k * 1024); } while (0)
; #define PG8_MMA(ai, bj, At, Bt) do { __builtin_amdgcn_s_setprio(1); _Pragma("unroll") for (int m = 0; m < 4; ++m) _Pragma("unroll") for (int n = 0; n < 2; ++n) _Pragma("unroll") for (int k = 0; k < 2; ++k) \
;         acc[ai][bj][m][n] = __builtin_amdgcn_mfma_f32_16x16x32_bf16(Bt[n][k], At[m][k], acc[ai][bj][m][n], 0, 0, 0); __builtin_amdgcn_s_setprio(0); } while (0)
; #define PG8_WAIT_V(n) asm volatile("s_waitcnt vmcnt(" #n ")" ::: "memory")
; #define PG8_WAIT_L(n) asm volatile("s_waitcnt lgkmcnt(" #n ")" ::: "memory")
; #define PG8_BAR __builtin_amdgcn_s_barrier()
; #define PG8_SCHED __builtin_amdgcn_sched_barrier(0)
; template <class Epi, class Sched>
; __device__ __forceinline__ void gemm_phase(LAS unsigned char* lds, const Gemm g, const Sched& S, const Epi& E, int wid) {
;     ...
;             PG8_WAIT_V(8); PG8_WAIT_L(0); PG8_BAR; PG8_MMA(1, 0, At, B0); PG8_MMA(1, 1, At, B1); PG8_BAR; PG8_SCHED;
;             PG8_LDB(B0, 1, 0); PG8_LDB(B1, 1, 1); PG8_SCHED; PG8_LDA(At, 1, 0); PG8_STAGE(PG8_SA(0, 1), a2 + hstep, voffA);
;             PG8_WAIT_V(8); PG8_WAIT_L(0); PG8_BAR; PG8_MMA(0, 0, At, B0); PG8_MMA(0, 1, At, B1); PG8_BAR; PG8_SCHED;
	s_setprio 1
	s_waitcnt lgkmcnt(0)
	v_mfma_f32_16x16x32_bf16 v[60:63], v[144:147], v[186:189], v[60:63]
	v_mfma_f32_16x16x32_bf16 v[56:59], v[152:155], v[186:189], v[56:59]
	v_mfma_f32_16x16x32_bf16 v[44:47], v[144:147], v[194:197], v[44:47]
	v_mfma_f32_16x16x32_bf16 v[40:43], v[152:155], v[194:197], v[40:43]
	v_mfma_f32_16x16x32_bf16 v[28:31], v[144:147], v[202:205], v[28:31]
	v_mfma_f32_16x16x32_bf16 v[24:27], v[152:155], v[202:205], v[24:27]
	v_mfma_f32_16x16x32_bf16 v[12:15], v[144:147], v[210:213], v[12:15]
	v_mfma_f32_16x16x32_bf16 v[8:11], v[152:155], v[210:213], v[8:11]
	v_mfma_f32_16x16x32_bf16 v[60:63], v[148:151], v[190:193], v[60:63]
	v_mfma_f32_16x16x32_bf16 v[56:59], v[156:159], v[190:193], v[56:59]
	v_mfma_f32_16x16x32_bf16 v[44:47], v[148:151], v[198:201], v[44:47]
	v_mfma_f32_16x16x32_bf16 v[40:43], v[156:159], v[198:201], v[40:43]
	v_mfma_f32_16x16x32_bf16 v[28:31], v[148:151], v[206:209], v[28:31]
	v_mfma_f32_16x16x32_bf16 v[24:27], v[156:159], v[206:209], v[24:27]
	v_mfma_f32_16x16x32_bf16 v[12:15], v[148:151], v[214:217], v[12:15]
	v_mfma_f32_16x16x32_bf16 v[8:11], v[156:159], v[214:217], v[8:11]
	v_mfma_f32_16x16x32_bf16 v[52:55], v[170:173], v[186:189], v[52:55]
	v_mfma_f32_16x16x32_bf16 v[48:51], v[178:181], v[186:189], v[48:51]
	v_mfma_f32_16x16x32_bf16 v[36:39], v[170:173], v[194:197], v[36:39]
	v_mfma_f32_16x16x32_bf16 v[32:35], v[178:181], v[194:197], v[32:35]
	v_mfma_f32_16x16x32_bf16 v[20:23], v[170:173], v[202:205], v[20:23]
	v_mfma_f32_16x16x32_bf16 v[16:19], v[178:181], v[202:205], v[16:19]
	v_mfma_f32_16x16x32_bf16 v[4:7], v[170:173], v[210:213], v[4:7]
	v_mfma_f32_16x16x32_bf16 v[0:3], v[178:181], v[210:213], v[0:3]
	v_mfma_f32_16x16x32_bf16 v[52:55], v[174:177], v[190:193], v[52:55]
	v_mfma_f32_16x16x32_bf16 v[48:51], v[182:185], v[190:193], v[48:51]
	v_mfma_f32_16x16x32_bf16 v[36:39], v[174:177], v[198:201], v[36:39]
	v_mfma_f32_16x16x32_bf16 v[32:35], v[182:185], v[198:201], v[32:35]
	v_mfma_f32_16x16x32_bf16 v[20:23], v[174:177], v[206:209], v[20:23]
	v_mfma_f32_16x16x32_bf16 v[16:19], v[182:185], v[206:209], v[16:19]
	v_mfma_f32_16x16x32_bf16 v[4:7], v[174:177], v[214:217], v[4:7]
	v_mfma_f32_16x16x32_bf16 v[0:3], v[182:185], v[214:217], v[0:3]
	s_setprio 0
	s_barrier
	s_add_i32 s65, 0, 0x18000
	s_add_i32 s66, 0, 0x1c000
	v_add_u32_e32 v156, s65, v162
	v_add_u32_e32 v169, s66, v162
	ds_read_b128 v[144:147], v156
	ds_read_b128 v[148:151], v156 offset:1024
	ds_read_b128 v[152:155], v156 offset:2048
	ds_read_b128 v[156:159], v156 offset:3072
	ds_read_b128 v[170:173], v169
	ds_read_b128 v[174:177], v169 offset:1024
	ds_read_b128 v[178:181], v169 offset:2048
	ds_read_b128 v[182:185], v169 offset:3072
	s_add_u32 s36, s38, 0xb0000
	s_addc_u32 s37, s39, 0
	s_mov_b32 m0, s43
	v_lshl_add_u64 v[226:227], s[36:37], 0, v[128:129]
	ds_read_b128 v[186:189], v165 offset:32768
	ds_read_b128 v[190:193], v165 offset:33792
	ds_read_b128 v[194:197], v165 offset:34816
	ds_read_b128 v[198:201], v165 offset:35840
	ds_read_b128 v[202:205], v165 offset:36864
	ds_read_b128 v[206:209], v165 offset:37888
	ds_read_b128 v[210:213], v165 offset:38912
	ds_read_b128 v[214:217], v165 offset:39936
	global_load_lds_dwordx4 v[226:227], off
	v_lshl_add_u64 v[226:227], s[36:37], 0, v[132:133]
	s_mov_b32 m0, s44
	s_nop 0
	global_load_lds_dwordx4 v[226:227], off
	s_waitcnt vmcnt(8)
	s_waitcnt lgkmcnt(0)
	s_barrier
	s_setprio 1
	s_waitcnt lgkmcnt(0)
	v_mfma_f32_16x16x32_bf16 v[124:127], v[144:147], v[186:189], v[124:127]
	v_mfma_f32_16x16x32_bf16 v[120:123], v[152:155], v[186:189], v[120:123]
	v_mfma_f32_16x16x32_bf16 v[108:111], v[144:147], v[194:197], v[108:111]
	v_mfma_f32_16x16x32_bf16 v[104:107], v[152:155], v[194:197], v[104:107]
	v_mfma_f32_16x16x32_bf16 v[92:95], v[144:147], v[202:205], v[92:95]
	v_mfma_f32_16x16x32_bf16 v[88:91], v[152:155], v[202:205], v[88:91]
	v_mfma_f32_16x16x32_bf16 v[76:79], v[144:147], v[210:213], v[76:79]
	v_mfma_f32_16x16x32_bf16 v[72:75], v[152:155], v[210:213], v[72:75]
	v_mfma_f32_16x16x32_bf16 v[124:127], v[148:151], v[190:193], v[124:127]
	v_mfma_f32_16x16x32_bf16 v[120:123], v[156:159], v[190:193], v[120:123]
	v_mfma_f32_16x16x32_bf16 v[108:111], v[148:151], v[198:201], v[108:111]
	v_mfma_f32_16x16x32_bf16 v[104:107], v[156:159], v[198:201], v[104:107]
	v_mfma_f32_16x16x32_bf16 v[92:95], v[148:151], v[206:209], v[92:95]
	v_mfma_f32_16x16x32_bf16 v[88:91], v[156:159], v[206:209], v[88:91]
	v_mfma_f32_16x16x32_bf16 v[76:79], v[148:151], v[214:217], v[76:79]
	v_mfma_f32_16x16x32_bf16 v[72:75], v[156:159], v[214:217], v[72:75]
	v_mfma_f32_16x16x32_bf16 v[116:119], v[170:173], v[186:189], v[116:119]
	v_mfma_f32_16x16x32_bf16 v[112:115], v[178:181], v[186:189], v[112:115]
	v_mfma_f32_16x16x32_bf16 v[100:103], v[170:173], v[194:197], v[100:103]
	v_mfma_f32_16x16x32_bf16 v[96:99], v[178:181], v[194:197], v[96:99]
	v_mfma_f32_16x16x32_bf16 v[84:87], v[170:173], v[202:205], v[84:87]
	v_mfma_f32_16x16x32_bf16 v[80:83], v[178:181], v[202:205], v[80:83]
	v_mfma_f32_16x16x32_bf16 v[68:71], v[170:173], v[210:213], v[68:71]
	v_mfma_f32_16x16x32_bf16 v[64:67], v[178:181], v[210:213], v[64:67]
	v_mfma_f32_16x16x32_bf16 v[116:119], v[174:177], v[190:193], v[116:119]
	v_mfma_f32_16x16x32_bf16 v[112:115], v[182:185], v[190:193], v[112:115]
	v_mfma_f32_16x16x32_bf16 v[100:103], v[174:177], v[198:201], v[100:103]
	v_mfma_f32_16x16x32_bf16 v[96:99], v[182:185], v[198:201], v[96:99]
	v_mfma_f32_16x16x32_bf16 v[84:87], v[174:177], v[206:209], v[84:87]
	v_mfma_f32_16x16x32_bf16 v[80:83], v[182:185], v[206:209], v[80:83]
	v_mfma_f32_16x16x32_bf16 v[68:71], v[174:177], v[214:217], v[68:71]
	v_mfma_f32_16x16x32_bf16 v[64:67], v[182:185], v[214:217], v[64:67]
	s_setprio 0
	s_barrier
; #define PG8_STAGE(bufoff, gbase, voff) do { _Pragma("unroll") for (int _i = 0; _i < 2; ++_i) \
;         __builtin_amdgcn_global_load_lds((const unsigned*)((const char*)(gbase) + (voff)[_i]), (LAS unsigned*)(lds + (bufoff) + ldsw + _i * 8192), 16, 0, 0); } while (0)
; #define PG8_LDA(dst, b, h) do { _Pragma("unroll") for (int m = 0; m < 4; ++m) _Pragma("unroll") for (int k = 0; k < 2; ++k) dst[m][k] = *(const LAS bf16x8*)(lds + PG8_SA(b, h) + aoff + m * 2048 + k * 1024); } while (0)
; #define PG8_MMA(ai, bj, At, Bt) do { __builtin_amdgcn_s_setprio(1); _Pragma("unroll") for (int m = 0; m < 4; ++m) _Pragma("unroll") for (int n = 0; n < 2; ++n) _Pragma("unroll") for (int k = 0; k < 2; ++k) \
;         acc[ai][bj][m][n] = __builtin_amdgcn_mfma_f32_16x16x32_bf16(Bt[n][k], At[m][k], acc[ai][bj][m][n], 0, 0, 0); __builtin_amdgcn_s_setprio(0); } while (0)
; #define PG8_WAIT_V(n) asm volatile("s_waitcnt vmcnt(" #n ")" ::: "memory")
; #define PG8_WAIT_L(n) asm volatile("s_waitcnt lgkmcnt(" #n ")" ::: "memory")
; #define PG8_BAR __builtin_amdgcn_s_barrier()
; #define PG8_SCHED __builtin_amdgcn_sched_barrier(0)
; template <class Epi, class Sched>
; __device__ __forceinline__ void gemm_phase(LAS unsigned char* lds, const Gemm g, const Sched& S, const Epi& E, int wid) {
;     ...
;             PG8_LDA(At, 1, 1); PG8_STAGE(PG8_SB(1, 0), b3, voffB); PG8_STAGE(PG8_SB(1, 1), b3 + hstep, voffB); PG8_STAGE(PG8_SA(1, 0), a3, voffA);
;             PG8_WAIT_V(8); PG8_WAIT_L(0); PG8_BAR; PG8_MMA(1, 0, At, B0); PG8_MMA(1, 1, At, B1); PG8_BAR; PG8_SCHED;
	s_add_i32 s36, s65, s75
	v_lshl_add_u64 v[218:219], v[218:219], 0, s[22:23]
	s_mov_b32 m0, s36
	ds_read_b128 v[186:189], v165 offset:49152
	ds_read_b128 v[190:193], v165 offset:50176
	ds_read_b128 v[194:197], v165 offset:51200
	ds_read_b128 v[198:201], v165 offset:52224
	ds_read_b128 v[202:205], v165 offset:53248
	ds_read_b128 v[206:209], v165 offset:54272
	ds_read_b128 v[210:213], v165 offset:55296
	ds_read_b128 v[214:217], v165 offset:56320
	global_load_lds_dwordx4 v[218:219], off
	s_add_i32 m0, s36, 0x2000
	s_add_u32 s10, s10, 0xb0080
	v_lshl_add_u64 v[218:219], v[220:221], 0, s[22:23]
	s_addc_u32 s11, s11, 0
	s_add_i32 s36, s66, s75
	global_load_lds_dwordx4 v[218:219], off
	v_lshl_add_u64 v[218:219], s[10:11], 0, v[130:131]
	s_mov_b32 m0, s36
	s_nop 0
	global_load_lds_dwordx4 v[218:219], off
	v_lshl_add_u64 v[218:219], s[10:11], 0, v[134:135]
	s_add_i32 m0, s36, 0x2000
	s_nop 0
	global_load_lds_dwordx4 v[218:219], off
	v_lshl_add_u64 v[218:219], v[222:223], 0, s[22:23]
	s_mov_b32 m0, s48
	s_nop 0
	global_load_lds_dwordx4 v[218:219], off
	v_lshl_add_u64 v[218:219], v[224:225], 0, s[22:23]
	s_mov_b32 m0, s49
	s_nop 0
	global_load_lds_dwordx4 v[218:219], off
	s_waitcnt vmcnt(8)
	s_waitcnt lgkmcnt(0)
	s_barrier
	s_setprio 1
	s_waitcnt lgkmcnt(0)
	v_mfma_f32_16x16x32_bf16 v[60:63], v[144:147], v[186:189], v[60:63]
	v_mfma_f32_16x16x32_bf16 v[56:59], v[152:155], v[186:189], v[56:59]
	v_mfma_f32_16x16x32_bf16 v[44:47], v[144:147], v[194:197], v[44:47]
	v_mfma_f32_16x16x32_bf16 v[40:43], v[152:155], v[194:197], v[40:43]
	v_mfma_f32_16x16x32_bf16 v[28:31], v[144:147], v[202:205], v[28:31]
	v_mfma_f32_16x16x32_bf16 v[24:27], v[152:155], v[202:205], v[24:27]
	v_mfma_f32_16x16x32_bf16 v[12:15], v[144:147], v[210:213], v[12:15]
	v_mfma_f32_16x16x32_bf16 v[8:11], v[152:155], v[210:213], v[8:11]
	v_mfma_f32_16x16x32_bf16 v[60:63], v[148:151], v[190:193], v[60:63]
	v_mfma_f32_16x16x32_bf16 v[56:59], v[156:159], v[190:193], v[56:59]
	v_mfma_f32_16x16x32_bf16 v[44:47], v[148:151], v[198:201], v[44:47]
	v_mfma_f32_16x16x32_bf16 v[40:43], v[156:159], v[198:201], v[40:43]
	v_mfma_f32_16x16x32_bf16 v[28:31], v[148:151], v[206:209], v[28:31]
	v_mfma_f32_16x16x32_bf16 v[24:27], v[156:159], v[206:209], v[24:27]
	v_mfma_f32_16x16x32_bf16 v[12:15], v[148:151], v[214:217], v[12:15]
	v_mfma_f32_16x16x32_bf16 v[8:11], v[156:159], v[214:217], v[8:11]
	v_mfma_f32_16x16x32_bf16 v[52:55], v[170:173], v[186:189], v[52:55]
	v_mfma_f32_16x16x32_bf16 v[48:51], v[178:181], v[186:189], v[48:51]
	v_mfma_f32_16x16x32_bf16 v[36:39], v[170:173], v[194:197], v[36:39]
	v_mfma_f32_16x16x32_bf16 v[32:35], v[178:181], v[194:197], v[32:35]
	v_mfma_f32_16x16x32_bf16 v[20:23], v[170:173], v[202:205], v[20:23]
	v_mfma_f32_16x16x32_bf16 v[16:19], v[178:181], v[202:205], v[16:19]
	v_mfma_f32_16x16x32_bf16 v[4:7], v[170:173], v[210:213], v[4:7]
	v_mfma_f32_16x16x32_bf16 v[0:3], v[178:181], v[210:213], v[0:3]
	v_mfma_f32_16x16x32_bf16 v[52:55], v[174:177], v[190:193], v[52:55]
	v_mfma_f32_16x16x32_bf16 v[48:51], v[182:185], v[190:193], v[48:51]
	v_mfma_f32_16x16x32_bf16 v[36:39], v[174:177], v[198:201], v[36:39]
	v_mfma_f32_16x16x32_bf16 v[32:35], v[182:185], v[198:201], v[32:35]
	v_mfma_f32_16x16x32_bf16 v[20:23], v[174:177], v[206:209], v[20:23]
	v_mfma_f32_16x16x32_bf16 v[16:19], v[182:185], v[206:209], v[16:19]
	v_mfma_f32_16x16x32_bf16 v[4:7], v[174:177], v[214:217], v[4:7]
	v_mfma_f32_16x16x32_bf16 v[0:3], v[182:185], v[214:217], v[0:3]
	s_setprio 0
	s_barrier
	s_add_i32 s64, s64, 2
	s_add_u32 s31, s31, 0x100
	s_addc_u32 s35, s35, 0
	s_cmp_gt_u32 s64, 41
	s_mov_b64 s[36:37], s[4:5]
	s_cbranch_scc0 .LBB0_2323
	s_and_b64 vcc, exec, s[24:25]
	s_cbranch_vccz .LBB0_2326
	s_barrier
